# k21: k20 + FFN-out back-edge block hoisted; I1 phase issues all 12 ds_reads first with the B address precomputed before the loop-back barrier
# baseline (speedup 1.0000x reference)
; #define PG8_STAGE(bufoff, gbase, voff) do { _Pragma("unroll") for (int _i = 0; _i < 2; ++_i) \
;         __builtin_amdgcn_global_load_lds((const unsigned*)((const char*)(gbase) + (voff)[_i]), (LAS unsigned*)(lds + (bufoff) + ldsw + _i * 8192), 16, 0, 0); } while (0)
; #define PG8_LDA(dst, b, h) do { _Pragma("unroll") for (int m = 0; m < 4; ++m) _Pragma("unroll") for (int k = 0; k < 2; ++k) dst[m][k] = *(const LAS bf16x8*)(lds + PG8_SA(b, h) + aoff + m * 2048 + k * 1024); } while (0)
; #define PG8_LDB(dst, b, h) do { _Pragma("unroll") for (int n = 0; n < 2; ++n) _Pragma("unroll") for (int k = 0; k < 2; ++k) dst[n][k] = *(const LAS bf16x8*)(lds + PG8_SB(b, h) + boff + n * 2048 + k * 1024); } while (0)
; #define PG8_MMA(ai, bj, At, Bt) do { __builtin_amdgcn_s_setprio(1); _Pragma("unroll") for (int m = 0; m < 4; ++m) _Pragma("unroll") for (int n = 0; n < 2; ++n) _Pragma("unroll") for (int k = 0; k < 2; ++k) \
;         acc[ai][bj][m][n] = __builtin_amdgcn_mfma_f32_16x16x32_bf16(Bt[n][k], At[m][k], acc[ai][bj][m][n], 0, 0, 0); __builtin_amdgcn_s_setprio(0); } while (0)
; template <class Epi>
; __device__ __forceinline__ void gemm_phase(LAS unsigned char* lds, const Gemm g, const Epi& E) {
;     ...
;         const bool has_next = S.next(ui + 1, nxt);
;         const char* nA = has_next ? (const char*)g.A + (size_t)g.mapA.src(nxt.pm) * tstepA + (size_t)nxt.pn * g.a_pn_step : cA;
;         const char* nB = has_next ? (const char*)g.Bt + (size_t)g.mapB.src(nxt.pn) * tstepB : cB;
;         for (int t = 0; t < nt; t += 2) {
;             const bool last = (t == nt - 2);
;             const char* a1 = cA + (size_t)(t + 1) * kstep;
;             const char* a2 = last ? nA : cA + (size_t)(t + 2) * kstep; const char* b2 = last ? nB : cB + (size_t)(t + 2) * kstep;
;             const char* a3 = a2 + kstep; const char* b3 = b2 + kstep;
;             PG8_LDB(B0, 0, 0); PG8_SCHED; PG8_LDA(At, 0, 0); PG8_STAGE(PG8_SA(1, 1), a1 + hstepA, voffA);
;             PG8_WAIT_L(8); PG8_BAR; PG8_WAIT_L(0); PG8_MMA(0, 0, At, B0); PG8_BAR; PG8_SCHED;
;     ...
; #pragma unroll
;         for (int a = 0; a < 2; ++a)
; #pragma unroll
;             for (int b = 0; b < 2; ++b)
; #pragma unroll
;                 for (int m = 0; m < 4; ++m)
; #pragma unroll
;                     for (int n = 0; n < 2; ++n) acc[a][b][m][n] = (f32x4){0.f, 0.f, 0.f, 0.f};
;         cur = nxt; cA = nA; cB = nB; ++ui;
.LBB0_330:
	s_ashr_i32 s15, s14, 31
	s_lshl_b64 s[52:53], s[14:15], 19
	s_add_u32 s15, s92, s52
	s_addc_u32 s52, s93, s53
	s_and_b64 s[4:5], s[4:5], exec
	s_cselect_b32 s59, s52, s65
	s_cselect_b32 s58, s15, s64
	s_add_u32 s4, s60, 0x40080
	s_addc_u32 s5, s61, 0
	s_add_u32 s15, s64, 0x100
	v_mov_b32_e32 v2, 0
	s_addc_u32 s52, s65, 0
	s_mov_b32 s53, -2
	v_mov_b32_e32 v3, v2
	v_mov_b64_e32 v[4:5], v[2:3]
	v_mov_b64_e32 v[6:7], v[2:3]
	v_mov_b64_e32 v[8:9], v[2:3]
	v_mov_b64_e32 v[10:11], v[2:3]
	v_mov_b64_e32 v[12:13], v[2:3]
	v_mov_b64_e32 v[14:15], v[2:3]
	v_mov_b64_e32 v[16:17], v[2:3]
	v_mov_b64_e32 v[18:19], v[2:3]
	v_mov_b64_e32 v[20:21], v[2:3]
	v_mov_b64_e32 v[22:23], v[2:3]
	v_mov_b64_e32 v[24:25], v[2:3]
	v_mov_b64_e32 v[26:27], v[2:3]
	v_mov_b64_e32 v[28:29], v[2:3]
	v_mov_b64_e32 v[30:31], v[2:3]
	v_mov_b64_e32 v[32:33], v[2:3]
	v_mov_b64_e32 v[34:35], v[2:3]
	v_mov_b64_e32 v[36:37], v[2:3]
	v_mov_b64_e32 v[38:39], v[2:3]
	v_mov_b64_e32 v[40:41], v[2:3]
	v_mov_b64_e32 v[42:43], v[2:3]
	v_mov_b64_e32 v[44:45], v[2:3]
	v_mov_b64_e32 v[46:47], v[2:3]
	v_mov_b64_e32 v[48:49], v[2:3]
	v_mov_b64_e32 v[50:51], v[2:3]
	v_mov_b64_e32 v[52:53], v[2:3]
	v_mov_b64_e32 v[54:55], v[2:3]
	v_mov_b64_e32 v[56:57], v[2:3]
	v_mov_b64_e32 v[58:59], v[2:3]
	v_mov_b64_e32 v[60:61], v[2:3]
	v_mov_b64_e32 v[62:63], v[2:3]
	v_mov_b64_e32 v[64:65], v[2:3]
	v_mov_b64_e32 v[66:67], v[2:3]
	v_mov_b64_e32 v[68:69], v[2:3]
	v_mov_b64_e32 v[70:71], v[2:3]
	v_mov_b64_e32 v[72:73], v[2:3]
	v_mov_b64_e32 v[78:79], v[2:3]
	v_mov_b64_e32 v[80:81], v[2:3]
	v_mov_b64_e32 v[90:91], v[2:3]
	v_mov_b64_e32 v[92:93], v[2:3]
	v_mov_b64_e32 v[98:99], v[2:3]
	v_mov_b64_e32 v[100:101], v[2:3]
	v_mov_b64_e32 v[102:103], v[2:3]
	v_mov_b64_e32 v[104:105], v[2:3]
	v_mov_b64_e32 v[114:115], v[2:3]
	v_mov_b64_e32 v[116:117], v[2:3]
	v_mov_b64_e32 v[118:119], v[2:3]
	v_mov_b64_e32 v[120:121], v[2:3]
	v_mov_b64_e32 v[122:123], v[2:3]
	v_mov_b64_e32 v[124:125], v[2:3]
	v_mov_b64_e32 v[126:127], v[2:3]
	v_mov_b64_e32 v[128:129], v[2:3]
	v_mov_b64_e32 v[138:139], v[2:3]
	v_mov_b64_e32 v[140:141], v[2:3]
	v_mov_b64_e32 v[142:143], v[2:3]
	v_mov_b64_e32 v[144:145], v[2:3]
	v_mov_b64_e32 v[146:147], v[2:3]
	v_mov_b64_e32 v[148:149], v[2:3]
	v_mov_b64_e32 v[150:151], v[2:3]
	v_mov_b64_e32 v[152:153], v[2:3]
	v_mov_b64_e32 v[162:163], v[2:3]
	v_mov_b64_e32 v[164:165], v[2:3]
	v_mov_b64_e32 v[166:167], v[2:3]
	v_mov_b64_e32 v[168:169], v[2:3]
	s_add_i32 s72, 0, 0x10000
	v_add_u32_e32 v94, s72, v201
.LBB0_331:
	ds_read_b128 v[74:77], v94
	ds_read_b128 v[82:85], v94 offset:1024
	ds_read_b128 v[86:89], v94 offset:2048
	ds_read_b128 v[94:97], v94 offset:3072
	ds_read_b128 v[106:109], v202
	ds_read_b128 v[110:113], v202 offset:1024
	ds_read_b128 v[130:133], v202 offset:2048
	ds_read_b128 v[134:137], v202 offset:3072
	ds_read_b128 v[154:157], v202 offset:4096
	ds_read_b128 v[158:161], v202 offset:5120
	ds_read_b128 v[170:173], v202 offset:6144
	ds_read_b128 v[174:177], v202 offset:7168
	s_add_u32 s60, s4, 0xfffc0080
	s_addc_u32 s61, s5, -1
	s_cmp_eq_u32 s53, 12
	s_cselect_b32 s65, s29, s61
	s_cselect_b32 s64, s28, s60
	s_cselect_b32 s61, s59, s52
	s_cselect_b32 s60, s58, s15
	v_lshl_add_u64 v[192:193], s[4:5], 0, v[188:189]
	s_add_i32 m0, s24, 0xc000
	s_nop 0
	global_load_lds_dwordx4 v[192:193], off
	v_lshl_add_u64 v[192:193], s[4:5], 0, v[190:191]
	s_add_i32 m0, s24, 0xe000
	s_nop 0
	global_load_lds_dwordx4 v[192:193], off
	s_waitcnt lgkmcnt(8)
	s_barrier
	s_waitcnt lgkmcnt(0)
	v_mfma_f32_16x16x32_bf16 v[166:169], v[74:77], v[106:109], v[166:169]
	v_mfma_f32_16x16x32_bf16 v[162:165], v[86:89], v[106:109], v[162:165]
	v_mfma_f32_16x16x32_bf16 v[142:145], v[74:77], v[130:133], v[142:145]
	v_mfma_f32_16x16x32_bf16 v[138:141], v[86:89], v[130:133], v[138:141]
	v_mfma_f32_16x16x32_bf16 v[118:121], v[74:77], v[154:157], v[118:121]
	v_mfma_f32_16x16x32_bf16 v[114:117], v[86:89], v[154:157], v[114:117]
	v_mfma_f32_16x16x32_bf16 v[90:93], v[74:77], v[170:173], v[90:93]
	v_mfma_f32_16x16x32_bf16 v[78:81], v[86:89], v[170:173], v[78:81]
	v_mfma_f32_16x16x32_bf16 v[166:169], v[82:85], v[110:113], v[166:169]
	v_mfma_f32_16x16x32_bf16 v[162:165], v[94:97], v[110:113], v[162:165]
	v_mfma_f32_16x16x32_bf16 v[142:145], v[82:85], v[134:137], v[142:145]
	v_mfma_f32_16x16x32_bf16 v[138:141], v[94:97], v[134:137], v[138:141]
	v_mfma_f32_16x16x32_bf16 v[118:121], v[82:85], v[158:161], v[118:121]
	v_mfma_f32_16x16x32_bf16 v[114:117], v[94:97], v[158:161], v[114:117]
	v_mfma_f32_16x16x32_bf16 v[90:93], v[82:85], v[174:177], v[90:93]
	v_mfma_f32_16x16x32_bf16 v[78:81], v[94:97], v[174:177], v[78:81]
	s_barrier
	s_add_i32 s74, 0, 0x14000
	s_add_i32 s72, s72, s1
	v_add_u32_e32 v203, s74, v201
	v_lshl_add_u64 v[208:209], s[60:61], 0, v[184:185]
	s_mov_b32 m0, s72
	ds_read_b128 v[192:195], v203
	ds_read_b128 v[196:199], v203 offset:1024
	ds_read_b128 v[204:207], v203 offset:2048
	ds_read_b128 v[226:229], v203 offset:3072
	global_load_lds_dwordx4 v[208:209], off
	v_lshl_add_u64 v[234:235], s[60:61], 0, v[180:181]
	s_add_i32 m0, s72, 0x2000
	s_nop 0
	global_load_lds_dwordx4 v[234:235], off
	s_nop 1
	s_mov_b32 m0, s24
	v_lshl_add_u64 v[236:237], s[64:65], 0, v[186:187]
	s_barrier
; #define PG8_STAGE(bufoff, gbase, voff) do { _Pragma("unroll") for (int _i = 0; _i < 2; ++_i) \
;         __builtin_amdgcn_global_load_lds((const unsigned*)((const char*)(gbase) + (voff)[_i]), (LAS unsigned*)(lds + (bufoff) + ldsw + _i * 8192), 16, 0, 0); } while (0)
; #define PG8_LDA(dst, b, h) do { _Pragma("unroll") for (int m = 0; m < 4; ++m) _Pragma("unroll") for (int k = 0; k < 2; ++k) dst[m][k] = *(const LAS bf16x8*)(lds + PG8_SA(b, h) + aoff + m * 2048 + k * 1024); } while (0)
; #define PG8_LDB(dst, b, h) do { _Pragma("unroll") for (int n = 0; n < 2; ++n) _Pragma("unroll") for (int k = 0; k < 2; ++k) dst[n][k] = *(const LAS bf16x8*)(lds + PG8_SB(b, h) + boff + n * 2048 + k * 1024); } while (0)
; #define PG8_MMA(ai, bj, At, Bt) do { __builtin_amdgcn_s_setprio(1); _Pragma("unroll") for (int m = 0; m < 4; ++m) _Pragma("unroll") for (int n = 0; n < 2; ++n) _Pragma("unroll") for (int k = 0; k < 2; ++k) \
;         acc[ai][bj][m][n] = __builtin_amdgcn_mfma_f32_16x16x32_bf16(Bt[n][k], At[m][k], acc[ai][bj][m][n], 0, 0, 0); __builtin_amdgcn_s_setprio(0); } while (0)
; #define PG8_WAIT_V(n) asm volatile("s_waitcnt vmcnt(" #n ")" ::: "memory")
; #define PG8_WAIT_L(n) asm volatile("s_waitcnt lgkmcnt(" #n ")" ::: "memory")
; #define PG8_BAR __builtin_amdgcn_s_barrier()
; #define PG8_SCHED __builtin_amdgcn_sched_barrier(0)
; template <class Epi>
; __device__ __forceinline__ void gemm_phase(LAS unsigned char* lds, const Gemm g, const Epi& E) {
;     ...
;             PG8_BAR; PG8_WAIT_L(0); PG8_MMA(0, 1, At, B1); PG8_BAR;
;             PG8_LDA(At, 0, 1); PG8_STAGE(PG8_SA(0, 0), a2, voffA);
;             PG8_BAR; PG8_WAIT_L(0); PG8_MMA(1, 0, At, B0); PG8_BAR; PG8_SCHED;
;             PG8_STAGE(PG8_SB(0, 1), b2 + hstepB, voffB);
;             PG8_WAIT_V(6); PG8_BAR; PG8_MMA(1, 1, At, B1); PG8_BAR;
;             PG8_LDB(B0, 1, 0); PG8_SCHED; PG8_LDA(At, 1, 0); PG8_STAGE(PG8_SA(0, 1), a2 + hstepA, voffA);
;             PG8_WAIT_L(8); PG8_BAR; PG8_WAIT_L(0); PG8_MMA(0, 0, At, B0); PG8_BAR; PG8_SCHED;
	s_waitcnt lgkmcnt(0)
	v_mfma_f32_16x16x32_bf16 v[150:153], v[192:195], v[106:109], v[150:153]
	v_mfma_f32_16x16x32_bf16 v[106:109], v[204:207], v[106:109], v[146:149]
	v_mfma_f32_16x16x32_bf16 v[122:125], v[204:207], v[130:133], v[122:125]
	v_mfma_f32_16x16x32_bf16 v[102:105], v[192:195], v[154:157], v[102:105]
	v_mfma_f32_16x16x32_bf16 v[98:101], v[204:207], v[154:157], v[98:101]
	v_mfma_f32_16x16x32_bf16 v[70:73], v[192:195], v[170:173], v[70:73]
	v_mfma_f32_16x16x32_bf16 v[66:69], v[204:207], v[170:173], v[66:69]
	v_mfma_f32_16x16x32_bf16 v[150:153], v[196:199], v[110:113], v[150:153]
	v_mfma_f32_16x16x32_bf16 v[106:109], v[226:229], v[110:113], v[106:109]
	v_mfma_f32_16x16x32_bf16 v[110:113], v[192:195], v[130:133], v[126:129]
	v_mfma_f32_16x16x32_bf16 v[122:125], v[226:229], v[134:137], v[122:125]
	v_mfma_f32_16x16x32_bf16 v[102:105], v[196:199], v[158:161], v[102:105]
	v_mfma_f32_16x16x32_bf16 v[98:101], v[226:229], v[158:161], v[98:101]
	v_mfma_f32_16x16x32_bf16 v[70:73], v[196:199], v[174:177], v[70:73]
	v_mfma_f32_16x16x32_bf16 v[66:69], v[226:229], v[174:177], v[66:69]
	v_mfma_f32_16x16x32_bf16 v[110:113], v[196:199], v[134:137], v[110:113]
	s_barrier
	ds_read_b128 v[126:129], v202 offset:16384
	ds_read_b128 v[130:133], v202 offset:17408
	ds_read_b128 v[134:137], v202 offset:18432
	ds_read_b128 v[146:149], v202 offset:19456
	ds_read_b128 v[154:157], v202 offset:20480
	ds_read_b128 v[158:161], v202 offset:21504
	ds_read_b128 v[170:173], v202 offset:22528
	ds_read_b128 v[174:177], v202 offset:23552
	global_load_lds_dwordx4 v[236:237], off
	v_lshl_add_u64 v[238:239], s[64:65], 0, v[182:183]
	s_mov_b32 m0, s25
	s_nop 0
	global_load_lds_dwordx4 v[238:239], off
	s_barrier
	s_waitcnt lgkmcnt(0)
	v_mfma_f32_16x16x32_bf16 v[62:65], v[74:77], v[126:129], v[62:65]
	v_mfma_f32_16x16x32_bf16 v[58:61], v[86:89], v[126:129], v[58:61]
	v_mfma_f32_16x16x32_bf16 v[46:49], v[74:77], v[134:137], v[46:49]
	v_mfma_f32_16x16x32_bf16 v[42:45], v[86:89], v[134:137], v[42:45]
	v_mfma_f32_16x16x32_bf16 v[30:33], v[74:77], v[154:157], v[30:33]
	v_mfma_f32_16x16x32_bf16 v[26:29], v[86:89], v[154:157], v[26:29]
	v_mfma_f32_16x16x32_bf16 v[14:17], v[74:77], v[170:173], v[14:17]
	v_mfma_f32_16x16x32_bf16 v[10:13], v[86:89], v[170:173], v[10:13]
	v_mfma_f32_16x16x32_bf16 v[62:65], v[82:85], v[130:133], v[62:65]
	v_mfma_f32_16x16x32_bf16 v[58:61], v[94:97], v[130:133], v[58:61]
	v_mfma_f32_16x16x32_bf16 v[46:49], v[82:85], v[146:149], v[46:49]
	v_mfma_f32_16x16x32_bf16 v[42:45], v[94:97], v[146:149], v[42:45]
	v_mfma_f32_16x16x32_bf16 v[30:33], v[82:85], v[158:161], v[30:33]
	v_mfma_f32_16x16x32_bf16 v[26:29], v[94:97], v[158:161], v[26:29]
	v_mfma_f32_16x16x32_bf16 v[14:17], v[82:85], v[174:177], v[14:17]
	v_mfma_f32_16x16x32_bf16 v[10:13], v[94:97], v[174:177], v[10:13]
	s_barrier
	s_add_u32 s72, s60, 0x40000
	s_addc_u32 s73, s61, 0
	s_add_i32 s74, s74, s1
	v_lshl_add_u64 v[74:75], s[72:73], 0, v[184:185]
	s_mov_b32 m0, s74
	s_nop 0
	global_load_lds_dwordx4 v[74:75], off
	v_lshl_add_u64 v[74:75], s[72:73], 0, v[180:181]
	s_add_i32 m0, s74, 0x2000
	s_nop 0
	global_load_lds_dwordx4 v[74:75], off
	s_add_i32 s72, 0, 0x18000
	v_add_u32_e32 v94, s72, v201
	s_waitcnt vmcnt(6)
	s_barrier
	v_mfma_f32_16x16x32_bf16 v[54:57], v[192:195], v[126:129], v[54:57]
	v_mfma_f32_16x16x32_bf16 v[50:53], v[204:207], v[126:129], v[50:53]
	v_mfma_f32_16x16x32_bf16 v[38:41], v[192:195], v[134:137], v[38:41]
	v_mfma_f32_16x16x32_bf16 v[34:37], v[204:207], v[134:137], v[34:37]
	v_mfma_f32_16x16x32_bf16 v[22:25], v[192:195], v[154:157], v[22:25]
	v_mfma_f32_16x16x32_bf16 v[18:21], v[204:207], v[154:157], v[18:21]
	v_mfma_f32_16x16x32_bf16 v[6:9], v[192:195], v[170:173], v[6:9]
	v_mfma_f32_16x16x32_bf16 v[2:5], v[204:207], v[170:173], v[2:5]
	v_mfma_f32_16x16x32_bf16 v[54:57], v[196:199], v[130:133], v[54:57]
	v_mfma_f32_16x16x32_bf16 v[50:53], v[226:229], v[130:133], v[50:53]
	v_mfma_f32_16x16x32_bf16 v[38:41], v[196:199], v[146:149], v[38:41]
	v_mfma_f32_16x16x32_bf16 v[34:37], v[226:229], v[146:149], v[34:37]
	v_mfma_f32_16x16x32_bf16 v[22:25], v[196:199], v[158:161], v[22:25]
	v_mfma_f32_16x16x32_bf16 v[18:21], v[226:229], v[158:161], v[18:21]
	v_mfma_f32_16x16x32_bf16 v[6:9], v[196:199], v[174:177], v[6:9]
	v_mfma_f32_16x16x32_bf16 v[2:5], v[226:229], v[174:177], v[2:5]
	s_barrier
	ds_read_b128 v[74:77], v94
	ds_read_b128 v[82:85], v94 offset:1024
	ds_read_b128 v[86:89], v94 offset:2048
	ds_read_b128 v[94:97], v94 offset:3072
	s_add_u32 s64, s64, 0x40000
	s_addc_u32 s65, s65, 0
	s_mov_b32 m0, s31
	v_lshl_add_u64 v[146:147], s[64:65], 0, v[186:187]
	ds_read_b128 v[126:129], v202 offset:32768
	ds_read_b128 v[130:133], v202 offset:33792
	ds_read_b128 v[134:137], v202 offset:34816
	ds_read_b128 v[154:157], v202 offset:35840
	ds_read_b128 v[158:161], v202 offset:36864
	ds_read_b128 v[170:173], v202 offset:37888
	ds_read_b128 v[174:177], v202 offset:38912
	ds_read_b128 v[192:195], v202 offset:39936
	global_load_lds_dwordx4 v[146:147], off
	v_lshl_add_u64 v[146:147], s[64:65], 0, v[182:183]
	s_mov_b32 m0, s36
	s_nop 0
	global_load_lds_dwordx4 v[146:147], off
	s_waitcnt lgkmcnt(8)
	s_barrier
; #define PG8_STAGE(bufoff, gbase, voff) do { _Pragma("unroll") for (int _i = 0; _i < 2; ++_i) \
;         __builtin_amdgcn_global_load_lds((const unsigned*)((const char*)(gbase) + (voff)[_i]), (LAS unsigned*)(lds + (bufoff) + ldsw + _i * 8192), 16, 0, 0); } while (0)
; #define PG8_LDA(dst, b, h) do { _Pragma("unroll") for (int m = 0; m < 4; ++m) _Pragma("unroll") for (int k = 0; k < 2; ++k) dst[m][k] = *(const LAS bf16x8*)(lds + PG8_SA(b, h) + aoff + m * 2048 + k * 1024); } while (0)
; #define PG8_LDB(dst, b, h) do { _Pragma("unroll") for (int n = 0; n < 2; ++n) _Pragma("unroll") for (int k = 0; k < 2; ++k) dst[n][k] = *(const LAS bf16x8*)(lds + PG8_SB(b, h) + boff + n * 2048 + k * 1024); } while (0)
; #define PG8_MMA(ai, bj, At, Bt) do { __builtin_amdgcn_s_setprio(1); _Pragma("unroll") for (int m = 0; m < 4; ++m) _Pragma("unroll") for (int n = 0; n < 2; ++n) _Pragma("unroll") for (int k = 0; k < 2; ++k) \
;         acc[ai][bj][m][n] = __builtin_amdgcn_mfma_f32_16x16x32_bf16(Bt[n][k], At[m][k], acc[ai][bj][m][n], 0, 0, 0); __builtin_amdgcn_s_setprio(0); } while (0)
; #define PG8_WAIT_L(n) asm volatile("s_waitcnt lgkmcnt(" #n ")" ::: "memory")
; #define PG8_BAR __builtin_amdgcn_s_barrier()
; #define PG8_SCHED __builtin_amdgcn_sched_barrier(0)
; template <class Epi>
; __device__ __forceinline__ void gemm_phase(LAS unsigned char* lds, const Gemm g, const Epi& E) {
;     ...
;             PG8_WAIT_L(8); PG8_BAR; PG8_WAIT_L(0); PG8_MMA(0, 0, At, B0); PG8_BAR; PG8_SCHED;
;             PG8_LDB(B1, 1, 1); PG8_STAGE(PG8_SB(1, 0), b3, voffB);
;             PG8_BAR; PG8_WAIT_L(0); PG8_MMA(0, 1, At, B1); PG8_BAR;
;             PG8_LDA(At, 1, 1); PG8_STAGE(PG8_SA(1, 0), a3, voffA);
;             PG8_BAR; PG8_WAIT_L(0); PG8_MMA(1, 0, At, B0); PG8_BAR; PG8_SCHED;
	s_waitcnt lgkmcnt(0)
	v_mfma_f32_16x16x32_bf16 v[146:149], v[74:77], v[126:129], v[166:169]
	v_mfma_f32_16x16x32_bf16 v[166:169], v[82:85], v[130:133], v[146:149]
	v_mfma_f32_16x16x32_bf16 v[146:149], v[86:89], v[126:129], v[162:165]
	v_mfma_f32_16x16x32_bf16 v[142:145], v[74:77], v[134:137], v[142:145]
	v_mfma_f32_16x16x32_bf16 v[138:141], v[86:89], v[134:137], v[138:141]
	v_mfma_f32_16x16x32_bf16 v[118:121], v[74:77], v[158:161], v[118:121]
	v_mfma_f32_16x16x32_bf16 v[114:117], v[86:89], v[158:161], v[114:117]
	v_mfma_f32_16x16x32_bf16 v[90:93], v[74:77], v[174:177], v[90:93]
	v_mfma_f32_16x16x32_bf16 v[78:81], v[86:89], v[174:177], v[78:81]
	v_mfma_f32_16x16x32_bf16 v[162:165], v[94:97], v[130:133], v[146:149]
	v_mfma_f32_16x16x32_bf16 v[142:145], v[82:85], v[154:157], v[142:145]
	v_mfma_f32_16x16x32_bf16 v[138:141], v[94:97], v[154:157], v[138:141]
	v_mfma_f32_16x16x32_bf16 v[118:121], v[82:85], v[170:173], v[118:121]
	v_mfma_f32_16x16x32_bf16 v[114:117], v[94:97], v[170:173], v[114:117]
	v_mfma_f32_16x16x32_bf16 v[90:93], v[82:85], v[192:195], v[90:93]
	v_mfma_f32_16x16x32_bf16 v[78:81], v[94:97], v[192:195], v[78:81]
	s_barrier
	s_add_i32 s64, 0, 0x1c000
	v_add_u32_e32 v146, s64, v201
	s_add_i32 s65, s72, s1
	ds_read_b128 v[196:199], v146
	ds_read_b128 v[204:207], v146 offset:1024
	ds_read_b128 v[226:229], v146 offset:2048
	ds_read_b128 v[230:233], v146 offset:3072
	v_lshl_add_u64 v[146:147], v[208:209], 0, s[86:87]
	s_mov_b32 m0, s65
	s_nop 0
	global_load_lds_dwordx4 v[146:147], off
	v_lshl_add_u64 v[146:147], v[234:235], 0, s[86:87]
	s_add_i32 m0, s65, 0x2000
	s_nop 0
	global_load_lds_dwordx4 v[146:147], off
	s_barrier
	s_waitcnt lgkmcnt(0)
	v_mfma_f32_16x16x32_bf16 v[146:149], v[196:199], v[126:129], v[150:153]
	v_mfma_f32_16x16x32_bf16 v[106:109], v[226:229], v[126:129], v[106:109]
	v_mfma_f32_16x16x32_bf16 v[150:153], v[204:207], v[130:133], v[146:149]
	v_mfma_f32_16x16x32_bf16 v[146:149], v[230:233], v[130:133], v[106:109]
	v_mfma_f32_16x16x32_bf16 v[106:109], v[196:199], v[134:137], v[110:113]
	v_mfma_f32_16x16x32_bf16 v[126:129], v[204:207], v[154:157], v[106:109]
	v_mfma_f32_16x16x32_bf16 v[106:109], v[226:229], v[134:137], v[122:125]
	v_mfma_f32_16x16x32_bf16 v[102:105], v[196:199], v[158:161], v[102:105]
	v_mfma_f32_16x16x32_bf16 v[98:101], v[226:229], v[158:161], v[98:101]
	v_mfma_f32_16x16x32_bf16 v[70:73], v[196:199], v[174:177], v[70:73]
	v_mfma_f32_16x16x32_bf16 v[66:69], v[226:229], v[174:177], v[66:69]
	v_mfma_f32_16x16x32_bf16 v[122:125], v[230:233], v[154:157], v[106:109]
	v_mfma_f32_16x16x32_bf16 v[102:105], v[204:207], v[170:173], v[102:105]
	v_mfma_f32_16x16x32_bf16 v[98:101], v[230:233], v[170:173], v[98:101]
	v_mfma_f32_16x16x32_bf16 v[70:73], v[204:207], v[192:195], v[70:73]
	v_mfma_f32_16x16x32_bf16 v[66:69], v[230:233], v[192:195], v[66:69]
	s_mov_b32 m0, s50
	v_lshl_add_u64 v[192:193], v[236:237], 0, s[86:87]
	s_barrier
	ds_read_b128 v[106:109], v202 offset:49152
	ds_read_b128 v[110:113], v202 offset:50176
	ds_read_b128 v[130:133], v202 offset:51200
	ds_read_b128 v[134:137], v202 offset:52224
	ds_read_b128 v[154:157], v202 offset:53248
	ds_read_b128 v[158:161], v202 offset:54272
	ds_read_b128 v[170:173], v202 offset:55296
	ds_read_b128 v[174:177], v202 offset:56320
	global_load_lds_dwordx4 v[192:193], off
	v_lshl_add_u64 v[192:193], v[238:239], 0, s[86:87]
	s_mov_b32 m0, s66
	s_nop 0
	global_load_lds_dwordx4 v[192:193], off
	s_barrier
	s_waitcnt lgkmcnt(0)
	v_mfma_f32_16x16x32_bf16 v[62:65], v[74:77], v[106:109], v[62:65]
	v_mfma_f32_16x16x32_bf16 v[58:61], v[86:89], v[106:109], v[58:61]
	v_mfma_f32_16x16x32_bf16 v[46:49], v[74:77], v[130:133], v[46:49]
	v_mfma_f32_16x16x32_bf16 v[42:45], v[86:89], v[130:133], v[42:45]
	v_mfma_f32_16x16x32_bf16 v[30:33], v[74:77], v[154:157], v[30:33]
	v_mfma_f32_16x16x32_bf16 v[26:29], v[86:89], v[154:157], v[26:29]
	v_mfma_f32_16x16x32_bf16 v[14:17], v[74:77], v[170:173], v[14:17]
	v_mfma_f32_16x16x32_bf16 v[10:13], v[86:89], v[170:173], v[10:13]
	v_mfma_f32_16x16x32_bf16 v[62:65], v[82:85], v[110:113], v[62:65]
	v_mfma_f32_16x16x32_bf16 v[58:61], v[94:97], v[110:113], v[58:61]
	v_mfma_f32_16x16x32_bf16 v[46:49], v[82:85], v[134:137], v[46:49]
	v_mfma_f32_16x16x32_bf16 v[42:45], v[94:97], v[134:137], v[42:45]
	v_mfma_f32_16x16x32_bf16 v[30:33], v[82:85], v[158:161], v[30:33]
	v_mfma_f32_16x16x32_bf16 v[26:29], v[94:97], v[158:161], v[26:29]
	v_mfma_f32_16x16x32_bf16 v[14:17], v[82:85], v[174:177], v[14:17]
	v_mfma_f32_16x16x32_bf16 v[10:13], v[94:97], v[174:177], v[10:13]
	s_barrier
; #define PG8_STAGE(bufoff, gbase, voff) do { _Pragma("unroll") for (int _i = 0; _i < 2; ++_i) \
;         __builtin_amdgcn_global_load_lds((const unsigned*)((const char*)(gbase) + (voff)[_i]), (LAS unsigned*)(lds + (bufoff) + ldsw + _i * 8192), 16, 0, 0); } while (0)
; #define PG8_MMA(ai, bj, At, Bt) do { __builtin_amdgcn_s_setprio(1); _Pragma("unroll") for (int m = 0; m < 4; ++m) _Pragma("unroll") for (int n = 0; n < 2; ++n) _Pragma("unroll") for (int k = 0; k < 2; ++k) \
;         acc[ai][bj][m][n] = __builtin_amdgcn_mfma_f32_16x16x32_bf16(Bt[n][k], At[m][k], acc[ai][bj][m][n], 0, 0, 0); __builtin_amdgcn_s_setprio(0); } while (0)
; #define PG8_WAIT_V(n) asm volatile("s_waitcnt vmcnt(" #n ")" ::: "memory")
; #define PG8_BAR __builtin_amdgcn_s_barrier()
; template <class Epi>
; __device__ __forceinline__ void gemm_phase(LAS unsigned char* lds, const Gemm g, const Epi& E) {
;     ...
;             PG8_STAGE(PG8_SB(1, 1), b3 + hstepB, voffB);
;             PG8_WAIT_V(6); PG8_BAR; PG8_MMA(1, 1, At, B1); PG8_BAR;
;     __device__ __forceinline__ void operator()(const AccT& acc, const Unit& u, int wr, int wc, int fr, int fq) const {
;     ...
;         const int gpm = mapA.src(u.pm);
;         const bool isq = u.pn < 4, isv = u.pn >= 8;
;         const bool lat = gpm >= 32 && !isv;
;         bf16_t* base = isq ? Q : (isv ? Vv + (size_t)(u.pn - 8) * 256 : Kk);
;         const int hh = isv ? 0 : (u.pn & 3);
;         const int ldo = isv ? 2048 : 1024;
;         const float osc = isq ? 0.0625f : 1.0f;
;         const int p0 = 16 * wc + 4 * fq;
;         f32x4 ctR[2][2], ctC[4][2];
;         if (lat) {
; #pragma unroll
;             for (int ai = 0; ai < 2; ++ai) { const int pr = ((gpm - 32) * 4 + 2 * ai + wr) & 31;
;                 ctR[ai][0] = *(const f32x4*)(cs + pr * 64 + p0); ctR[ai][1] = *(const f32x4*)(cs + pr * 64 + p0 + 2); }
; #pragma unroll
;             for (int m = 0; m < 4; ++m) { const int pc = m * 16 + fr;
;                 ctC[m][0] = *(const f32x4*)(cs + pc * 64 + p0); ctC[m][1] = *(const f32x4*)(cs + pc * 64 + p0 + 2); }
;         }
	s_add_u32 s60, s60, 0x40080
	s_addc_u32 s61, s61, 0
	s_add_i32 s64, s64, s1
	v_lshl_add_u64 v[74:75], s[60:61], 0, v[184:185]
	s_mov_b32 m0, s64
	s_nop 0
	global_load_lds_dwordx4 v[74:75], off
	v_lshl_add_u64 v[74:75], s[60:61], 0, v[180:181]
	s_add_i32 m0, s64, 0x2000
	s_nop 0
	global_load_lds_dwordx4 v[74:75], off
	s_add_i32 s53, s53, 2
	s_add_u32 s4, s4, 0x100
	s_addc_u32 s5, s5, 0
	s_add_u32 s15, s15, 0x100
	s_addc_u32 s52, s52, 0
	s_add_i32 s72, 0, 0x10000
	v_add_u32_e32 v94, s72, v201
	s_cmp_gt_u32 s53, 13
	s_waitcnt vmcnt(6)
	s_barrier
	v_mfma_f32_16x16x32_bf16 v[54:57], v[196:199], v[106:109], v[54:57]
	v_mfma_f32_16x16x32_bf16 v[50:53], v[226:229], v[106:109], v[50:53]
	v_mfma_f32_16x16x32_bf16 v[38:41], v[196:199], v[130:133], v[38:41]
	v_mfma_f32_16x16x32_bf16 v[34:37], v[226:229], v[130:133], v[34:37]
	v_mfma_f32_16x16x32_bf16 v[22:25], v[196:199], v[154:157], v[22:25]
	v_mfma_f32_16x16x32_bf16 v[18:21], v[226:229], v[154:157], v[18:21]
	v_mfma_f32_16x16x32_bf16 v[6:9], v[196:199], v[170:173], v[6:9]
	v_mfma_f32_16x16x32_bf16 v[2:5], v[226:229], v[170:173], v[2:5]
	v_mfma_f32_16x16x32_bf16 v[54:57], v[204:207], v[110:113], v[54:57]
	v_mfma_f32_16x16x32_bf16 v[50:53], v[230:233], v[110:113], v[50:53]
	v_mfma_f32_16x16x32_bf16 v[38:41], v[204:207], v[134:137], v[38:41]
	v_mfma_f32_16x16x32_bf16 v[34:37], v[230:233], v[134:137], v[34:37]
	v_mfma_f32_16x16x32_bf16 v[22:25], v[204:207], v[158:161], v[22:25]
	v_mfma_f32_16x16x32_bf16 v[18:21], v[230:233], v[158:161], v[18:21]
	v_mfma_f32_16x16x32_bf16 v[6:9], v[204:207], v[174:177], v[6:9]
	v_mfma_f32_16x16x32_bf16 v[2:5], v[230:233], v[174:177], v[2:5]
	s_barrier
	s_cbranch_scc0 .LBB0_331
	s_cmp_lt_i32 s10, 16
	s_cselect_b32 s4, s68, s18
	s_add_i32 s15, s10, s4
	s_cmp_lt_i32 s11, 8
	s_cselect_b64 s[60:61], -1, 0
	s_cmp_gt_i32 s15, 31
	s_cselect_b64 s[4:5], -1, 0
	s_and_b64 s[52:53], s[60:61], s[4:5]
	v_cndmask_b32_e64 v74, 0, 1, s[52:53]
	v_mov_b32_e32 v194, v200
	v_mov_b32_e32 v193, v1
	v_cmp_ne_u32_e64 s[4:5], 1, v74
	s_andn2_b64 vcc, exec, s[52:53]
	s_cbranch_vccnz .LBB0_334
	v_lshl_add_u32 v74, v193, 2, s67
	v_readlane_b32 s52, v254, 2
	s_lshl_b32 s15, s15, 8
	v_ashrrev_i32_e32 v75, 31, v74
	v_readlane_b32 s53, v254, 3
	s_add_i32 s15, s15, s44
	s_nop 0
	v_lshl_add_u64 v[74:75], v[74:75], 3, s[52:53]
	s_and_b32 s52, s15, 0x7c0
	s_addk_i32 s15, 0x80
	s_lshl_b32 s76, s52, 3
	s_and_b32 s15, s15, 0x7c0
	v_lshl_add_u64 v[76:77], v[74:75], 0, s[76:77]
	s_lshl_b32 s76, s15, 3
	global_load_dwordx4 v[170:173], v[76:77], off offset:16
	global_load_dwordx4 v[174:177], v[76:77], off
	v_lshl_add_u64 v[76:77], v[74:75], 0, s[76:77]
	global_load_dwordx4 v[86:89], v[76:77], off offset:16
	global_load_dwordx4 v[94:97], v[76:77], off
	v_lshlrev_b32_e32 v76, 6, v194
	v_ashrrev_i32_e32 v77, 31, v76
	v_lshl_add_u64 v[82:83], v[76:77], 3, v[74:75]
	global_load_dwordx4 v[154:157], v[82:83], off offset:16
	global_load_dwordx4 v[158:161], v[82:83], off
	v_add_u32_e32 v82, 0x400, v76
	v_ashrrev_i32_e32 v83, 31, v82
	v_lshl_add_u64 v[82:83], v[82:83], 3, v[74:75]
	global_load_dwordx4 v[130:133], v[82:83], off offset:16
	global_load_dwordx4 v[134:137], v[82:83], off
	v_add_u32_e32 v82, 0x800, v76
	v_ashrrev_i32_e32 v83, 31, v82
	v_add_u32_e32 v76, 0xc00, v76
	v_lshl_add_u64 v[82:83], v[82:83], 3, v[74:75]
	v_ashrrev_i32_e32 v77, 31, v76
	global_load_dwordx4 v[106:109], v[82:83], off offset:16
	global_load_dwordx4 v[110:113], v[82:83], off
	v_lshl_add_u64 v[82:83], v[76:77], 3, v[74:75]
	global_load_dwordx4 v[74:77], v[82:83], off offset:16
	s_nop 0
	global_load_dwordx4 v[82:85], v[82:83], off

; #define PG8_STAGE(bufoff, gbase, voff) do { _Pragma("unroll") for (int _i = 0; _i < 2; ++_i) \
;         __builtin_amdgcn_global_load_lds((const unsigned*)((const char*)(gbase) + (voff)[_i]), (LAS unsigned*)(lds + (bufoff) + ldsw + _i * 8192), 16, 0, 0); } while (0)
; #define PG8_LDA(dst, b, h) do { _Pragma("unroll") for (int m = 0; m < 4; ++m) _Pragma("unroll") for (int k = 0; k < 2; ++k) dst[m][k] = *(const LAS bf16x8*)(lds + PG8_SA(b, h) + aoff + m * 2048 + k * 1024); } while (0)
; #define PG8_LDB(dst, b, h) do { _Pragma("unroll") for (int n = 0; n < 2; ++n) _Pragma("unroll") for (int k = 0; k < 2; ++k) dst[n][k] = *(const LAS bf16x8*)(lds + PG8_SB(b, h) + boff + n * 2048 + k * 1024); } while (0)
; #define PG8_MMA(ai, bj, At, Bt) do { __builtin_amdgcn_s_setprio(1); _Pragma("unroll") for (int m = 0; m < 4; ++m) _Pragma("unroll") for (int n = 0; n < 2; ++n) _Pragma("unroll") for (int k = 0; k < 2; ++k) \
;         acc[ai][bj][m][n] = __builtin_amdgcn_mfma_f32_16x16x32_bf16(Bt[n][k], At[m][k], acc[ai][bj][m][n], 0, 0, 0); __builtin_amdgcn_s_setprio(0); } while (0)
; template <class Epi>
; __device__ __forceinline__ void gemm_phase(LAS unsigned char* lds, const Gemm g, const Epi& E) {
;     ...
;         const bool has_next = S.next(ui + 1, nxt);
;         const char* nA = has_next ? (const char*)g.A + (size_t)g.mapA.src(nxt.pm) * tstepA + (size_t)nxt.pn * g.a_pn_step : cA;
;         const char* nB = has_next ? (const char*)g.Bt + (size_t)g.mapB.src(nxt.pn) * tstepB : cB;
;         for (int t = 0; t < nt; t += 2) {
;             const bool last = (t == nt - 2);
;             const char* a1 = cA + (size_t)(t + 1) * kstep;
;             const char* a2 = last ? nA : cA + (size_t)(t + 2) * kstep; const char* b2 = last ? nB : cB + (size_t)(t + 2) * kstep;
;             const char* a3 = a2 + kstep; const char* b3 = b2 + kstep;
;             PG8_LDB(B0, 0, 0); PG8_SCHED; PG8_LDA(At, 0, 0); PG8_STAGE(PG8_SA(1, 1), a1 + hstepA, voffA);
;             PG8_WAIT_L(8); PG8_BAR; PG8_WAIT_L(0); PG8_MMA(0, 0, At, B0); PG8_BAR; PG8_SCHED;
;     ...
; #pragma unroll
;         for (int a = 0; a < 2; ++a)
; #pragma unroll
;             for (int b = 0; b < 2; ++b)
; #pragma unroll
;                 for (int m = 0; m < 4; ++m)
; #pragma unroll
;                     for (int n = 0; n < 2; ++n) acc[a][b][m][n] = (f32x4){0.f, 0.f, 0.f, 0.f};
;         cur = nxt; cA = nA; cB = nB; ++ui;
.LBB0_474:
	s_ashr_i32 s9, s8, 31
	s_lshl_b64 s[28:29], s[8:9], 19
	v_readlane_b32 s9, v255, 28
	s_add_u32 s9, s9, s28
	v_readlane_b32 s28, v255, 29
	s_addc_u32 s28, s28, s29
	s_and_b64 s[4:5], s[4:5], exec
	s_cselect_b32 s5, s28, s17
	s_cselect_b32 s4, s9, s16
	s_add_u32 s14, s14, 0x40080
	s_addc_u32 s15, s15, 0
	s_add_u32 s9, s16, 0x100
	v_mov_b32_e32 v2, 0
	s_addc_u32 s53, s17, 0
	s_mov_b32 s65, -2
	v_mov_b32_e32 v3, v2
	v_mov_b32_e32 v4, v2
	v_mov_b32_e32 v5, v2
	v_mov_b32_e32 v6, v2
	v_mov_b32_e32 v7, v2
	v_mov_b32_e32 v8, v2
	v_mov_b32_e32 v9, v2
	v_mov_b32_e32 v18, v2
	v_mov_b32_e32 v19, v2
	v_mov_b32_e32 v20, v2
	v_mov_b32_e32 v21, v2
	v_mov_b32_e32 v22, v2
	v_mov_b32_e32 v23, v2
	s_waitcnt vmcnt(0)
	v_mov_b32_e32 v24, v2
	v_mov_b32_e32 v25, v2
	v_mov_b32_e32 v34, v2
	v_mov_b32_e32 v35, v2
	v_mov_b32_e32 v36, v2
	v_mov_b32_e32 v37, v2
	v_mov_b32_e32 v38, v2
	v_mov_b32_e32 v39, v2
	v_mov_b32_e32 v40, v2
	v_mov_b32_e32 v41, v2
	v_mov_b32_e32 v50, v2
	v_mov_b32_e32 v51, v2
	v_mov_b32_e32 v52, v2
	v_mov_b32_e32 v53, v2
	v_mov_b32_e32 v54, v2
	v_mov_b32_e32 v55, v2
	v_mov_b32_e32 v56, v2
	v_mov_b32_e32 v57, v2
	v_mov_b32_e32 v10, v2
	v_mov_b32_e32 v11, v2
	v_mov_b32_e32 v12, v2
	v_mov_b32_e32 v13, v2
	v_mov_b32_e32 v14, v2
	v_mov_b32_e32 v15, v2
	v_mov_b32_e32 v16, v2
	v_mov_b32_e32 v17, v2
	v_mov_b32_e32 v26, v2
	v_mov_b32_e32 v27, v2
	v_mov_b32_e32 v28, v2
	v_mov_b32_e32 v29, v2
	v_mov_b32_e32 v30, v2
	v_mov_b32_e32 v31, v2
	v_mov_b32_e32 v32, v2
	v_mov_b32_e32 v33, v2
	v_mov_b32_e32 v42, v2
	v_mov_b32_e32 v43, v2
	v_mov_b32_e32 v44, v2
	v_mov_b32_e32 v45, v2
	v_mov_b32_e32 v46, v2
	v_mov_b32_e32 v47, v2
	v_mov_b32_e32 v48, v2
	v_mov_b32_e32 v49, v2
	v_mov_b32_e32 v58, v2
	v_mov_b32_e32 v59, v2
	v_mov_b32_e32 v60, v2
	v_mov_b32_e32 v61, v2
	v_mov_b32_e32 v62, v2
	v_mov_b32_e32 v63, v2
	v_mov_b32_e32 v64, v2
	v_mov_b32_e32 v65, v2
	v_mov_b32_e32 v74, v2
	v_mov_b32_e32 v75, v2
	v_mov_b32_e32 v76, v2
	v_mov_b32_e32 v77, v2
	v_mov_b32_e32 v78, v2
	v_mov_b32_e32 v79, v2
	v_mov_b32_e32 v80, v2
	v_mov_b32_e32 v81, v2
	v_mov_b32_e32 v98, v2
	v_mov_b32_e32 v99, v2
	v_mov_b32_e32 v100, v2
	v_mov_b32_e32 v101, v2
	v_mov_b32_e32 v102, v2
	v_mov_b32_e32 v103, v2
	v_mov_b32_e32 v104, v2
	v_mov_b32_e32 v105, v2
	v_mov_b32_e32 v114, v2
	v_mov_b32_e32 v115, v2
	v_mov_b32_e32 v116, v2
	v_mov_b32_e32 v117, v2
	v_mov_b32_e32 v118, v2
	v_mov_b32_e32 v119, v2
	v_mov_b32_e32 v120, v2
	v_mov_b32_e32 v121, v2
	v_mov_b32_e32 v130, v2
	v_mov_b32_e32 v131, v2
	v_mov_b32_e32 v132, v2
	v_mov_b32_e32 v133, v2
	v_mov_b32_e32 v134, v2
	v_mov_b32_e32 v135, v2
	v_mov_b32_e32 v136, v2
	v_mov_b32_e32 v137, v2
	v_mov_b32_e32 v90, v2
	v_mov_b32_e32 v91, v2
	v_mov_b32_e32 v92, v2
	v_mov_b32_e32 v93, v2
	v_mov_b32_e32 v94, v2
	v_mov_b32_e32 v95, v2
	v_mov_b32_e32 v96, v2
	v_mov_b32_e32 v97, v2
	v_mov_b32_e32 v106, v2
	v_mov_b32_e32 v107, v2
	v_mov_b32_e32 v108, v2
	v_mov_b32_e32 v109, v2
	v_mov_b32_e32 v110, v2
	v_mov_b32_e32 v111, v2
	v_mov_b32_e32 v112, v2
	v_mov_b32_e32 v113, v2
	v_mov_b32_e32 v122, v2
	v_mov_b32_e32 v123, v2
	v_mov_b32_e32 v124, v2
	v_mov_b32_e32 v125, v2
	v_mov_b32_e32 v126, v2
	v_mov_b32_e32 v127, v2
	v_mov_b32_e32 v128, v2
	v_mov_b32_e32 v129, v2
	v_mov_b32_e32 v138, v2
	v_mov_b32_e32 v139, v2
	v_mov_b32_e32 v140, v2
	v_mov_b32_e32 v141, v2
	v_mov_b32_e32 v142, v2
	v_mov_b32_e32 v143, v2
	v_mov_b32_e32 v144, v2
	v_mov_b32_e32 v145, v2
	s_add_i32 s66, 0, 0x10000
	v_add_u32_e32 v86, s66, v226
.LBB0_475:
	ds_read_b128 v[66:69], v86
	ds_read_b128 v[70:73], v86 offset:1024
	ds_read_b128 v[82:85], v86 offset:2048
	ds_read_b128 v[86:89], v86 offset:3072
	ds_read_b128 v[146:149], v227
	ds_read_b128 v[150:153], v227 offset:1024
	ds_read_b128 v[154:157], v227 offset:2048
	ds_read_b128 v[158:161], v227 offset:3072
	ds_read_b128 v[162:165], v227 offset:4096
	ds_read_b128 v[180:183], v227 offset:5120
	ds_read_b128 v[184:187], v227 offset:6144
	ds_read_b128 v[188:191], v227 offset:7168
	s_add_u32 s16, s14, 0xfffc0080
	s_addc_u32 s17, s15, -1
	s_cmp_eq_u32 s65, 12
	s_cselect_b32 s29, s11, s17
	s_cselect_b32 s28, s10, s16
	s_cselect_b32 s17, s5, s53
	s_cselect_b32 s16, s4, s9
	v_lshl_add_u64 v[192:193], s[14:15], 0, v[174:175]
	s_add_i32 m0, s13, 0xc000
	s_nop 0
	global_load_lds_dwordx4 v[192:193], off
	v_lshl_add_u64 v[192:193], s[14:15], 0, v[176:177]
	s_add_i32 m0, s13, 0xe000
	s_nop 0
	global_load_lds_dwordx4 v[192:193], off
	s_waitcnt lgkmcnt(8)
	s_barrier
	s_waitcnt lgkmcnt(0)
	v_mfma_f32_16x16x32_bf16 v[142:145], v[66:69], v[146:149], v[142:145]
	v_mfma_f32_16x16x32_bf16 v[138:141], v[82:85], v[146:149], v[138:141]
	v_mfma_f32_16x16x32_bf16 v[126:129], v[66:69], v[154:157], v[126:129]
	v_mfma_f32_16x16x32_bf16 v[122:125], v[82:85], v[154:157], v[122:125]
	v_mfma_f32_16x16x32_bf16 v[110:113], v[66:69], v[162:165], v[110:113]
	v_mfma_f32_16x16x32_bf16 v[106:109], v[82:85], v[162:165], v[106:109]
	v_mfma_f32_16x16x32_bf16 v[94:97], v[66:69], v[184:187], v[94:97]
	v_mfma_f32_16x16x32_bf16 v[90:93], v[82:85], v[184:187], v[90:93]
	v_mfma_f32_16x16x32_bf16 v[142:145], v[70:73], v[150:153], v[142:145]
	v_mfma_f32_16x16x32_bf16 v[138:141], v[86:89], v[150:153], v[138:141]
	v_mfma_f32_16x16x32_bf16 v[126:129], v[70:73], v[158:161], v[126:129]
	v_mfma_f32_16x16x32_bf16 v[122:125], v[86:89], v[158:161], v[122:125]
	v_mfma_f32_16x16x32_bf16 v[110:113], v[70:73], v[180:183], v[110:113]
	v_mfma_f32_16x16x32_bf16 v[106:109], v[86:89], v[180:183], v[106:109]
	v_mfma_f32_16x16x32_bf16 v[94:97], v[70:73], v[188:191], v[94:97]
	v_mfma_f32_16x16x32_bf16 v[90:93], v[86:89], v[188:191], v[90:93]
	s_barrier
; #define PG8_STAGE(bufoff, gbase, voff) do { _Pragma("unroll") for (int _i = 0; _i < 2; ++_i) \
;         __builtin_amdgcn_global_load_lds((const unsigned*)((const char*)(gbase) + (voff)[_i]), (LAS unsigned*)(lds + (bufoff) + ldsw + _i * 8192), 16, 0, 0); } while (0)
; #define PG8_LDA(dst, b, h) do { _Pragma("unroll") for (int m = 0; m < 4; ++m) _Pragma("unroll") for (int k = 0; k < 2; ++k) dst[m][k] = *(const LAS bf16x8*)(lds + PG8_SA(b, h) + aoff + m * 2048 + k * 1024); } while (0)
; #define PG8_LDB(dst, b, h) do { _Pragma("unroll") for (int n = 0; n < 2; ++n) _Pragma("unroll") for (int k = 0; k < 2; ++k) dst[n][k] = *(const LAS bf16x8*)(lds + PG8_SB(b, h) + boff + n * 2048 + k * 1024); } while (0)
; #define PG8_MMA(ai, bj, At, Bt) do { __builtin_amdgcn_s_setprio(1); _Pragma("unroll") for (int m = 0; m < 4; ++m) _Pragma("unroll") for (int n = 0; n < 2; ++n) _Pragma("unroll") for (int k = 0; k < 2; ++k) \
;         acc[ai][bj][m][n] = __builtin_amdgcn_mfma_f32_16x16x32_bf16(Bt[n][k], At[m][k], acc[ai][bj][m][n], 0, 0, 0); __builtin_amdgcn_s_setprio(0); } while (0)
; #define PG8_WAIT_V(n) asm volatile("s_waitcnt vmcnt(" #n ")" ::: "memory")
; #define PG8_WAIT_L(n) asm volatile("s_waitcnt lgkmcnt(" #n ")" ::: "memory")
; #define PG8_BAR __builtin_amdgcn_s_barrier()
; #define PG8_SCHED __builtin_amdgcn_sched_barrier(0)
; template <class Epi>
; __device__ __forceinline__ void gemm_phase(LAS unsigned char* lds, const Gemm g, const Epi& E) {
;     ...
;             PG8_LDB(B1, 0, 1); PG8_STAGE(PG8_SB(0, 0), b2, voffB);
;             PG8_BAR; PG8_WAIT_L(0); PG8_MMA(0, 1, At, B1); PG8_BAR;
;             PG8_LDA(At, 0, 1); PG8_STAGE(PG8_SA(0, 0), a2, voffA);
;             PG8_BAR; PG8_WAIT_L(0); PG8_MMA(1, 0, At, B0); PG8_BAR; PG8_SCHED;
;             PG8_STAGE(PG8_SB(0, 1), b2 + hstepB, voffB);
;             PG8_WAIT_V(6); PG8_BAR; PG8_MMA(1, 1, At, B1); PG8_BAR;
;             PG8_LDB(B0, 1, 0); PG8_SCHED; PG8_LDA(At, 1, 0); PG8_STAGE(PG8_SA(0, 1), a2 + hstepA, voffA);
	s_add_i32 s68, 0, 0x14000
	s_add_i32 s66, s66, s18
	v_add_u32_e32 v204, s68, v226
	v_lshl_add_u64 v[208:209], s[16:17], 0, v[170:171]
	s_mov_b32 m0, s66
	ds_read_b128 v[192:195], v204
	ds_read_b128 v[196:199], v204 offset:1024
	ds_read_b128 v[200:203], v204 offset:2048
	ds_read_b128 v[204:207], v204 offset:3072
	global_load_lds_dwordx4 v[208:209], off
	v_lshl_add_u64 v[228:229], s[16:17], 0, v[166:167]
	s_add_i32 m0, s66, 0x2000
	s_nop 0
	global_load_lds_dwordx4 v[228:229], off
	s_nop 1
	s_mov_b32 m0, s13
	v_lshl_add_u64 v[230:231], s[28:29], 0, v[172:173]
	s_barrier
	s_waitcnt lgkmcnt(0)
	v_mfma_f32_16x16x32_bf16 v[134:137], v[192:195], v[146:149], v[134:137]
	v_mfma_f32_16x16x32_bf16 v[130:133], v[200:203], v[146:149], v[130:133]
	v_mfma_f32_16x16x32_bf16 v[118:121], v[192:195], v[154:157], v[118:121]
	v_mfma_f32_16x16x32_bf16 v[114:117], v[200:203], v[154:157], v[114:117]
	v_mfma_f32_16x16x32_bf16 v[102:105], v[192:195], v[162:165], v[102:105]
	v_mfma_f32_16x16x32_bf16 v[98:101], v[200:203], v[162:165], v[98:101]
	v_mfma_f32_16x16x32_bf16 v[78:81], v[192:195], v[184:187], v[78:81]
	v_mfma_f32_16x16x32_bf16 v[74:77], v[200:203], v[184:187], v[74:77]
	v_mfma_f32_16x16x32_bf16 v[134:137], v[196:199], v[150:153], v[134:137]
	v_mfma_f32_16x16x32_bf16 v[130:133], v[204:207], v[150:153], v[130:133]
	v_mfma_f32_16x16x32_bf16 v[118:121], v[196:199], v[158:161], v[118:121]
	v_mfma_f32_16x16x32_bf16 v[114:117], v[204:207], v[158:161], v[114:117]
	v_mfma_f32_16x16x32_bf16 v[102:105], v[196:199], v[180:183], v[102:105]
	v_mfma_f32_16x16x32_bf16 v[98:101], v[204:207], v[180:183], v[98:101]
	v_mfma_f32_16x16x32_bf16 v[78:81], v[196:199], v[188:191], v[78:81]
	v_mfma_f32_16x16x32_bf16 v[74:77], v[204:207], v[188:191], v[74:77]
	s_barrier
	ds_read_b128 v[146:149], v227 offset:16384
	ds_read_b128 v[150:153], v227 offset:17408
	ds_read_b128 v[154:157], v227 offset:18432
	ds_read_b128 v[158:161], v227 offset:19456
	ds_read_b128 v[162:165], v227 offset:20480
	ds_read_b128 v[180:183], v227 offset:21504
	ds_read_b128 v[184:187], v227 offset:22528
	ds_read_b128 v[188:191], v227 offset:23552
	global_load_lds_dwordx4 v[230:231], off
	v_lshl_add_u64 v[232:233], s[28:29], 0, v[168:169]
	s_mov_b32 m0, s31
	s_nop 0
	global_load_lds_dwordx4 v[232:233], off
	s_barrier
	s_waitcnt lgkmcnt(0)
	v_mfma_f32_16x16x32_bf16 v[62:65], v[66:69], v[146:149], v[62:65]
	v_mfma_f32_16x16x32_bf16 v[58:61], v[82:85], v[146:149], v[58:61]
	v_mfma_f32_16x16x32_bf16 v[46:49], v[66:69], v[154:157], v[46:49]
	v_mfma_f32_16x16x32_bf16 v[42:45], v[82:85], v[154:157], v[42:45]
	v_mfma_f32_16x16x32_bf16 v[30:33], v[66:69], v[162:165], v[30:33]
	v_mfma_f32_16x16x32_bf16 v[26:29], v[82:85], v[162:165], v[26:29]
	v_mfma_f32_16x16x32_bf16 v[14:17], v[66:69], v[184:187], v[14:17]
	v_mfma_f32_16x16x32_bf16 v[10:13], v[82:85], v[184:187], v[10:13]
	v_mfma_f32_16x16x32_bf16 v[62:65], v[70:73], v[150:153], v[62:65]
	v_mfma_f32_16x16x32_bf16 v[58:61], v[86:89], v[150:153], v[58:61]
	v_mfma_f32_16x16x32_bf16 v[46:49], v[70:73], v[158:161], v[46:49]
	v_mfma_f32_16x16x32_bf16 v[42:45], v[86:89], v[158:161], v[42:45]
	v_mfma_f32_16x16x32_bf16 v[30:33], v[70:73], v[180:183], v[30:33]
	v_mfma_f32_16x16x32_bf16 v[26:29], v[86:89], v[180:183], v[26:29]
	v_mfma_f32_16x16x32_bf16 v[14:17], v[70:73], v[188:191], v[14:17]
	v_mfma_f32_16x16x32_bf16 v[10:13], v[86:89], v[188:191], v[10:13]
	s_barrier
	s_add_u32 s66, s16, 0x40000
	s_addc_u32 s67, s17, 0
	s_add_i32 s68, s68, s18
	v_lshl_add_u64 v[66:67], s[66:67], 0, v[170:171]
	s_mov_b32 m0, s68
	s_nop 0
	global_load_lds_dwordx4 v[66:67], off
	v_lshl_add_u64 v[66:67], s[66:67], 0, v[166:167]
	s_add_i32 m0, s68, 0x2000
	s_nop 0
	global_load_lds_dwordx4 v[66:67], off
	s_add_i32 s66, 0, 0x18000
	v_add_u32_e32 v86, s66, v226
	s_waitcnt vmcnt(6)
	s_barrier
	v_mfma_f32_16x16x32_bf16 v[54:57], v[192:195], v[146:149], v[54:57]
	v_mfma_f32_16x16x32_bf16 v[50:53], v[200:203], v[146:149], v[50:53]
	v_mfma_f32_16x16x32_bf16 v[38:41], v[192:195], v[154:157], v[38:41]
	v_mfma_f32_16x16x32_bf16 v[34:37], v[200:203], v[154:157], v[34:37]
	v_mfma_f32_16x16x32_bf16 v[22:25], v[192:195], v[162:165], v[22:25]
	v_mfma_f32_16x16x32_bf16 v[18:21], v[200:203], v[162:165], v[18:21]
	v_mfma_f32_16x16x32_bf16 v[6:9], v[192:195], v[184:187], v[6:9]
	v_mfma_f32_16x16x32_bf16 v[2:5], v[200:203], v[184:187], v[2:5]
	v_mfma_f32_16x16x32_bf16 v[54:57], v[196:199], v[150:153], v[54:57]
	v_mfma_f32_16x16x32_bf16 v[50:53], v[204:207], v[150:153], v[50:53]
	v_mfma_f32_16x16x32_bf16 v[38:41], v[196:199], v[158:161], v[38:41]
	v_mfma_f32_16x16x32_bf16 v[34:37], v[204:207], v[158:161], v[34:37]
	v_mfma_f32_16x16x32_bf16 v[22:25], v[196:199], v[180:183], v[22:25]
	v_mfma_f32_16x16x32_bf16 v[18:21], v[204:207], v[180:183], v[18:21]
	v_mfma_f32_16x16x32_bf16 v[6:9], v[196:199], v[188:191], v[6:9]
	v_mfma_f32_16x16x32_bf16 v[2:5], v[204:207], v[188:191], v[2:5]
	s_barrier
	ds_read_b128 v[66:69], v86
	ds_read_b128 v[70:73], v86 offset:1024
	ds_read_b128 v[82:85], v86 offset:2048
	ds_read_b128 v[86:89], v86 offset:3072
	s_add_u32 s28, s28, 0x40000
	s_addc_u32 s29, s29, 0
	s_mov_b32 m0, s36
	v_lshl_add_u64 v[192:193], s[28:29], 0, v[172:173]
	ds_read_b128 v[146:149], v227 offset:32768
	ds_read_b128 v[150:153], v227 offset:33792
	ds_read_b128 v[154:157], v227 offset:34816
	ds_read_b128 v[158:161], v227 offset:35840
	ds_read_b128 v[162:165], v227 offset:36864
	ds_read_b128 v[180:183], v227 offset:37888
	ds_read_b128 v[184:187], v227 offset:38912
	ds_read_b128 v[188:191], v227 offset:39936
	global_load_lds_dwordx4 v[192:193], off
	v_lshl_add_u64 v[192:193], s[28:29], 0, v[168:169]
	s_mov_b32 m0, s44
	s_nop 0
	global_load_lds_dwordx4 v[192:193], off
	s_waitcnt lgkmcnt(8)
	s_barrier
; #define PG8_STAGE(bufoff, gbase, voff) do { _Pragma("unroll") for (int _i = 0; _i < 2; ++_i) \
;         __builtin_amdgcn_global_load_lds((const unsigned*)((const char*)(gbase) + (voff)[_i]), (LAS unsigned*)(lds + (bufoff) + ldsw + _i * 8192), 16, 0, 0); } while (0)
; #define PG8_LDA(dst, b, h) do { _Pragma("unroll") for (int m = 0; m < 4; ++m) _Pragma("unroll") for (int k = 0; k < 2; ++k) dst[m][k] = *(const LAS bf16x8*)(lds + PG8_SA(b, h) + aoff + m * 2048 + k * 1024); } while (0)
; #define PG8_LDB(dst, b, h) do { _Pragma("unroll") for (int n = 0; n < 2; ++n) _Pragma("unroll") for (int k = 0; k < 2; ++k) dst[n][k] = *(const LAS bf16x8*)(lds + PG8_SB(b, h) + boff + n * 2048 + k * 1024); } while (0)
; #define PG8_MMA(ai, bj, At, Bt) do { __builtin_amdgcn_s_setprio(1); _Pragma("unroll") for (int m = 0; m < 4; ++m) _Pragma("unroll") for (int n = 0; n < 2; ++n) _Pragma("unroll") for (int k = 0; k < 2; ++k) \
;         acc[ai][bj][m][n] = __builtin_amdgcn_mfma_f32_16x16x32_bf16(Bt[n][k], At[m][k], acc[ai][bj][m][n], 0, 0, 0); __builtin_amdgcn_s_setprio(0); } while (0)
; #define PG8_WAIT_V(n) asm volatile("s_waitcnt vmcnt(" #n ")" ::: "memory")
; #define PG8_WAIT_L(n) asm volatile("s_waitcnt lgkmcnt(" #n ")" ::: "memory")
; #define PG8_BAR __builtin_amdgcn_s_barrier()
; #define PG8_SCHED __builtin_amdgcn_sched_barrier(0)
; template <class Epi>
; __device__ __forceinline__ void gemm_phase(LAS unsigned char* lds, const Gemm g, const Epi& E) {
;     ...
;             PG8_WAIT_L(8); PG8_BAR; PG8_WAIT_L(0); PG8_MMA(0, 0, At, B0); PG8_BAR; PG8_SCHED;
;             PG8_LDB(B1, 1, 1); PG8_STAGE(PG8_SB(1, 0), b3, voffB);
;             PG8_BAR; PG8_WAIT_L(0); PG8_MMA(0, 1, At, B1); PG8_BAR;
;             PG8_LDA(At, 1, 1); PG8_STAGE(PG8_SA(1, 0), a3, voffA);
;             PG8_BAR; PG8_WAIT_L(0); PG8_MMA(1, 0, At, B0); PG8_BAR; PG8_SCHED;
;             PG8_STAGE(PG8_SB(1, 1), b3 + hstepB, voffB);
;             PG8_WAIT_V(6); PG8_BAR; PG8_MMA(1, 1, At, B1); PG8_BAR;
	s_waitcnt lgkmcnt(0)
	v_mfma_f32_16x16x32_bf16 v[142:145], v[66:69], v[146:149], v[142:145]
	v_mfma_f32_16x16x32_bf16 v[138:141], v[82:85], v[146:149], v[138:141]
	v_mfma_f32_16x16x32_bf16 v[126:129], v[66:69], v[154:157], v[126:129]
	v_mfma_f32_16x16x32_bf16 v[122:125], v[82:85], v[154:157], v[122:125]
	v_mfma_f32_16x16x32_bf16 v[110:113], v[66:69], v[162:165], v[110:113]
	v_mfma_f32_16x16x32_bf16 v[106:109], v[82:85], v[162:165], v[106:109]
	v_mfma_f32_16x16x32_bf16 v[94:97], v[66:69], v[184:187], v[94:97]
	v_mfma_f32_16x16x32_bf16 v[90:93], v[82:85], v[184:187], v[90:93]
	v_mfma_f32_16x16x32_bf16 v[142:145], v[70:73], v[150:153], v[142:145]
	v_mfma_f32_16x16x32_bf16 v[138:141], v[86:89], v[150:153], v[138:141]
	v_mfma_f32_16x16x32_bf16 v[126:129], v[70:73], v[158:161], v[126:129]
	v_mfma_f32_16x16x32_bf16 v[122:125], v[86:89], v[158:161], v[122:125]
	v_mfma_f32_16x16x32_bf16 v[110:113], v[70:73], v[180:183], v[110:113]
	v_mfma_f32_16x16x32_bf16 v[106:109], v[86:89], v[180:183], v[106:109]
	v_mfma_f32_16x16x32_bf16 v[94:97], v[70:73], v[188:191], v[94:97]
	v_mfma_f32_16x16x32_bf16 v[90:93], v[86:89], v[188:191], v[90:93]
	s_barrier
	s_add_i32 s28, 0, 0x1c000
	s_add_i32 s29, s66, s18
	v_add_u32_e32 v204, s28, v226
	v_lshl_add_u64 v[208:209], v[208:209], 0, s[86:87]
	s_mov_b32 m0, s29
	ds_read_b128 v[192:195], v204
	ds_read_b128 v[196:199], v204 offset:1024
	ds_read_b128 v[200:203], v204 offset:2048
	ds_read_b128 v[204:207], v204 offset:3072
	global_load_lds_dwordx4 v[208:209], off
	v_lshl_add_u64 v[208:209], v[228:229], 0, s[86:87]
	s_add_i32 m0, s29, 0x2000
	s_nop 0
	global_load_lds_dwordx4 v[208:209], off
	s_nop 1
	s_mov_b32 m0, s59
	v_lshl_add_u64 v[208:209], v[230:231], 0, s[86:87]
	s_barrier
	s_waitcnt lgkmcnt(0)
	v_mfma_f32_16x16x32_bf16 v[134:137], v[192:195], v[146:149], v[134:137]
	v_mfma_f32_16x16x32_bf16 v[130:133], v[200:203], v[146:149], v[130:133]
	v_mfma_f32_16x16x32_bf16 v[118:121], v[192:195], v[154:157], v[118:121]
	v_mfma_f32_16x16x32_bf16 v[114:117], v[200:203], v[154:157], v[114:117]
	v_mfma_f32_16x16x32_bf16 v[102:105], v[192:195], v[162:165], v[102:105]
	v_mfma_f32_16x16x32_bf16 v[98:101], v[200:203], v[162:165], v[98:101]
	v_mfma_f32_16x16x32_bf16 v[78:81], v[192:195], v[184:187], v[78:81]
	v_mfma_f32_16x16x32_bf16 v[74:77], v[200:203], v[184:187], v[74:77]
	v_mfma_f32_16x16x32_bf16 v[134:137], v[196:199], v[150:153], v[134:137]
	v_mfma_f32_16x16x32_bf16 v[130:133], v[204:207], v[150:153], v[130:133]
	v_mfma_f32_16x16x32_bf16 v[118:121], v[196:199], v[158:161], v[118:121]
	v_mfma_f32_16x16x32_bf16 v[114:117], v[204:207], v[158:161], v[114:117]
	v_mfma_f32_16x16x32_bf16 v[102:105], v[196:199], v[180:183], v[102:105]
	v_mfma_f32_16x16x32_bf16 v[98:101], v[204:207], v[180:183], v[98:101]
	v_mfma_f32_16x16x32_bf16 v[78:81], v[196:199], v[188:191], v[78:81]
	v_mfma_f32_16x16x32_bf16 v[74:77], v[204:207], v[188:191], v[74:77]
	s_barrier
	ds_read_b128 v[146:149], v227 offset:49152
	ds_read_b128 v[150:153], v227 offset:50176
	ds_read_b128 v[154:157], v227 offset:51200
	ds_read_b128 v[158:161], v227 offset:52224
	ds_read_b128 v[162:165], v227 offset:53248
	ds_read_b128 v[180:183], v227 offset:54272
	ds_read_b128 v[184:187], v227 offset:55296
	ds_read_b128 v[188:191], v227 offset:56320
	global_load_lds_dwordx4 v[208:209], off
	v_lshl_add_u64 v[208:209], v[232:233], 0, s[86:87]
	s_mov_b32 m0, s60
	s_nop 0
	global_load_lds_dwordx4 v[208:209], off
	s_barrier
	s_waitcnt lgkmcnt(0)
	v_mfma_f32_16x16x32_bf16 v[62:65], v[66:69], v[146:149], v[62:65]
	v_mfma_f32_16x16x32_bf16 v[58:61], v[82:85], v[146:149], v[58:61]
	v_mfma_f32_16x16x32_bf16 v[46:49], v[66:69], v[154:157], v[46:49]
	v_mfma_f32_16x16x32_bf16 v[42:45], v[82:85], v[154:157], v[42:45]
	v_mfma_f32_16x16x32_bf16 v[30:33], v[66:69], v[162:165], v[30:33]
	v_mfma_f32_16x16x32_bf16 v[26:29], v[82:85], v[162:165], v[26:29]
	v_mfma_f32_16x16x32_bf16 v[14:17], v[66:69], v[184:187], v[14:17]
	v_mfma_f32_16x16x32_bf16 v[10:13], v[82:85], v[184:187], v[10:13]
	v_mfma_f32_16x16x32_bf16 v[62:65], v[70:73], v[150:153], v[62:65]
	v_mfma_f32_16x16x32_bf16 v[58:61], v[86:89], v[150:153], v[58:61]
	v_mfma_f32_16x16x32_bf16 v[46:49], v[70:73], v[158:161], v[46:49]
	v_mfma_f32_16x16x32_bf16 v[42:45], v[86:89], v[158:161], v[42:45]
	v_mfma_f32_16x16x32_bf16 v[30:33], v[70:73], v[180:183], v[30:33]
	v_mfma_f32_16x16x32_bf16 v[26:29], v[86:89], v[180:183], v[26:29]
	v_mfma_f32_16x16x32_bf16 v[14:17], v[70:73], v[188:191], v[14:17]
	v_mfma_f32_16x16x32_bf16 v[10:13], v[86:89], v[188:191], v[10:13]
	s_barrier
	s_add_u32 s16, s16, 0x40080
	s_addc_u32 s17, s17, 0
	s_add_i32 s28, s28, s18
	v_lshl_add_u64 v[66:67], s[16:17], 0, v[170:171]
	s_mov_b32 m0, s28
	s_nop 0
	global_load_lds_dwordx4 v[66:67], off
	v_lshl_add_u64 v[66:67], s[16:17], 0, v[166:167]
	s_add_i32 m0, s28, 0x2000
	s_nop 0
	global_load_lds_dwordx4 v[66:67], off
	s_add_i32 s65, s65, 2
	s_add_u32 s14, s14, 0x100
	s_addc_u32 s15, s15, 0
	s_add_u32 s9, s9, 0x100
	s_addc_u32 s53, s53, 0
	s_add_i32 s66, 0, 0x10000
	v_add_u32_e32 v86, s66, v226
	s_cmp_gt_u32 s65, 13
	s_waitcnt vmcnt(6)
	s_barrier
; #define PG8_MMA(ai, bj, At, Bt) do { __builtin_amdgcn_s_setprio(1); _Pragma("unroll") for (int m = 0; m < 4; ++m) _Pragma("unroll") for (int n = 0; n < 2; ++n) _Pragma("unroll") for (int k = 0; k < 2; ++k) \
;         acc[ai][bj][m][n] = __builtin_amdgcn_mfma_f32_16x16x32_bf16(Bt[n][k], At[m][k], acc[ai][bj][m][n], 0, 0, 0); __builtin_amdgcn_s_setprio(0); } while (0)
; #define PG8_WAIT_V(n) asm volatile("s_waitcnt vmcnt(" #n ")" ::: "memory")
; #define PG8_BAR __builtin_amdgcn_s_barrier()
; template <class Epi>
; __device__ __forceinline__ void gemm_phase(LAS unsigned char* lds, const Gemm g, const Epi& E) {
;     ...
;             PG8_WAIT_V(6); PG8_BAR; PG8_MMA(1, 1, At, B1); PG8_BAR;
;     __device__ __forceinline__ void operator()(const AccT& acc, const Unit& u, int wr, int wc, int fr, int fq) const {
;     ...
;         const int row0 = mapA.src(u.pm) * 256 + wr * 64 + fr, col0 = u.pn * 256 + wc * 32 + 8 * fq;
;         const int hd = u.pn >> 1;
;         f32x4 gw[2][2]; f32x2 st[2][4];
; #pragma unroll
;         for (int bj = 0; bj < 2; ++bj) { gw[bj][0] = *(const f32x4*)(gnw + col0 + bj * 128); gw[bj][1] = *(const f32x4*)(gnw + col0 + bj * 128 + 4); }
; #pragma unroll
;         for (int ai = 0; ai < 2; ++ai)
; #pragma unroll
;             for (int m = 0; m < 4; ++m) st[ai][m] = ST[(size_t)(row0 + ai * 128 + m * 16) * 4 + hd];
; #pragma unroll
;         for (int ai = 0; ai < 2; ++ai) {
;             u32x4 yv[4][2];
; #pragma unroll
;             for (int m = 0; m < 4; ++m)
; #pragma unroll
;                 for (int bj = 0; bj < 2; ++bj) yv[m][bj] = *(const u32x4*)(Y + (size_t)(row0 + ai * 128 + m * 16) * 2048 + col0 + bj * 128);
	v_mfma_f32_16x16x32_bf16 v[54:57], v[192:195], v[146:149], v[54:57]
	v_mfma_f32_16x16x32_bf16 v[50:53], v[200:203], v[146:149], v[50:53]
	v_mfma_f32_16x16x32_bf16 v[38:41], v[192:195], v[154:157], v[38:41]
	v_mfma_f32_16x16x32_bf16 v[34:37], v[200:203], v[154:157], v[34:37]
	v_mfma_f32_16x16x32_bf16 v[22:25], v[192:195], v[162:165], v[22:25]
	v_mfma_f32_16x16x32_bf16 v[18:21], v[200:203], v[162:165], v[18:21]
	v_mfma_f32_16x16x32_bf16 v[6:9], v[192:195], v[184:187], v[6:9]
	v_mfma_f32_16x16x32_bf16 v[2:5], v[200:203], v[184:187], v[2:5]
	v_mfma_f32_16x16x32_bf16 v[54:57], v[196:199], v[150:153], v[54:57]
	v_mfma_f32_16x16x32_bf16 v[50:53], v[204:207], v[150:153], v[50:53]
	v_mfma_f32_16x16x32_bf16 v[38:41], v[196:199], v[158:161], v[38:41]
	v_mfma_f32_16x16x32_bf16 v[34:37], v[204:207], v[158:161], v[34:37]
	v_mfma_f32_16x16x32_bf16 v[22:25], v[196:199], v[180:183], v[22:25]
	v_mfma_f32_16x16x32_bf16 v[18:21], v[204:207], v[180:183], v[18:21]
	v_mfma_f32_16x16x32_bf16 v[6:9], v[196:199], v[188:191], v[6:9]
	v_mfma_f32_16x16x32_bf16 v[2:5], v[204:207], v[188:191], v[2:5]
	s_barrier
	s_cbranch_scc0 .LBB0_475
	v_readlane_b32 s9, v255, 27
	s_cmp_ge_i32 s52, s9
	s_cselect_b32 s9, s25, 0
	s_lshl_b32 s14, s12, 8
	v_mov_b32_e32 v148, v225
	v_mov_b32_e32 v66, v1
	s_add_i32 s9, s52, s9
	s_or_b32 s14, s14, s58
	s_lshl_b32 s9, s9, 8
	v_lshl_add_u32 v146, v66, 3, s14
	s_ashr_i32 s14, s12, 1
	s_add_i32 s9, s9, s50
	s_ashr_i32 s15, s14, 31
	v_add_u32_e32 v148, s9, v148
	s_lshl_b64 s[14:15], s[14:15], 3
	s_add_u32 s14, s26, s14
	v_ashrrev_i32_e32 v149, 31, v148
	v_add_u32_e32 v152, 16, v148
	v_add_u32_e32 v156, 32, v148
	v_add_u32_e32 v202, 48, v148
	v_ashrrev_i32_e32 v147, 31, v146
	s_addc_u32 s15, s27, s15
	v_lshlrev_b64 v[150:151], 5, v[148:149]
	v_ashrrev_i32_e32 v153, 31, v152
	v_ashrrev_i32_e32 v157, 31, v156
	v_ashrrev_i32_e32 v203, 31, v202
	v_add_u32_e32 v190, 0x80, v148
	v_lshl_add_u64 v[70:71], v[146:147], 2, s[6:7]
	v_lshl_add_u64 v[150:151], s[14:15], 0, v[150:151]
	v_lshlrev_b64 v[154:155], 5, v[152:153]
	v_lshlrev_b64 v[158:159], 5, v[156:157]
	v_lshlrev_b64 v[160:161], 5, v[202:203]
	v_ashrrev_i32_e32 v191, 31, v190
	v_add_u32_e32 v192, 0x90, v148
	v_add_u32_e32 v194, 0xa0, v148
	v_add_u32_e32 v196, 0xb0, v148
	v_lshlrev_b64 v[182:183], 1, v[146:147]
	global_load_dwordx4 v[82:85], v[70:71], off offset:16
	global_load_dwordx4 v[86:89], v[70:71], off
	global_load_dwordx4 v[66:69], v[70:71], off offset:528
	s_nop 0
	global_load_dwordx4 v[70:73], v[70:71], off offset:512
	v_lshl_add_u64 v[154:155], s[14:15], 0, v[154:155]
	v_lshl_add_u64 v[158:159], s[14:15], 0, v[158:159]
	v_lshl_add_u64 v[160:161], s[14:15], 0, v[160:161]
	global_load_dwordx2 v[240:241], v[150:151], off
	global_load_dwordx2 v[208:209], v[154:155], off
	global_load_dwordx2 v[204:205], v[158:159], off
	global_load_dwordx2 v[200:201], v[160:161], off
	v_lshlrev_b64 v[150:151], 5, v[190:191]
	v_ashrrev_i32_e32 v193, 31, v192
	v_ashrrev_i32_e32 v195, 31, v194
	v_ashrrev_i32_e32 v197, 31, v196
	v_lshl_add_u64 v[198:199], s[38:39], 0, v[182:183]
	v_lshlrev_b64 v[242:243], 12, v[148:149]
	v_lshl_add_u64 v[150:151], s[14:15], 0, v[150:151]
	v_lshlrev_b64 v[154:155], 5, v[192:193]
	v_lshlrev_b64 v[158:159], 5, v[194:195]
	v_lshlrev_b64 v[160:161], 5, v[196:197]
	v_lshl_add_u64 v[146:147], v[198:199], 0, v[242:243]
	v_lshlrev_b64 v[244:245], 12, v[152:153]
	v_lshl_add_u64 v[154:155], s[14:15], 0, v[154:155]
	v_lshl_add_u64 v[158:159], s[14:15], 0, v[158:159]
	v_lshl_add_u64 v[160:161], s[14:15], 0, v[160:161]
	global_load_dwordx2 v[188:189], v[150:151], off
	global_load_dwordx2 v[186:187], v[154:155], off
	global_load_dwordx2 v[184:185], v[158:159], off
	global_load_dwordx2 v[180:181], v[160:161], off
	global_load_dwordx4 v[228:231], v[146:147], off
	global_load_dwordx4 v[232:235], v[146:147], off offset:256
	v_lshl_add_u64 v[146:147], v[198:199], 0, v[244:245]
	v_lshlrev_b64 v[206:207], 12, v[156:157]
	global_load_dwordx4 v[236:239], v[146:147], off
	global_load_dwordx4 v[162:165], v[146:147], off offset:256
	v_lshl_add_u64 v[146:147], v[198:199], 0, v[206:207]
	v_lshlrev_b64 v[202:203], 12, v[202:203]
	global_load_dwordx4 v[158:161], v[146:147], off
	global_load_dwordx4 v[154:157], v[146:147], off offset:256
	v_lshl_add_u64 v[146:147], v[198:199], 0, v[202:203]
	global_load_dwordx4 v[150:153], v[146:147], off
	s_nop 0
	global_load_dwordx4 v[146:149], v[146:147], off offset:256
	s_waitcnt vmcnt(0)
; __device__ __forceinline__ unsigned cvt_pk_bf16(float lo, float hi) { unsigned r; asm("v_cvt_pk_bf16_f32 %0, %1, %2" : "=v"(r) : "v"(lo), "v"(hi)); return r; }
; __device__ __forceinline__ float bf_lo(unsigned u) { return __uint_as_float(u << 16); }
; __device__ __forceinline__ float bf_hi(unsigned u) { return __uint_as_float(u & 0xffff0000u); }
;     __device__ __forceinline__ void operator()(const AccT& acc, const Unit& u, int wr, int wc, int fr, int fq) const {
;     ...
; #pragma unroll
;             for (int m = 0; m < 4; ++m) { bf16_t* rowp = A2 + (size_t)(row0 + ai * 128 + m * 16) * 2048 + col0;
;                 const float mu = st[ai][m][0], rs = st[ai][m][1];
; #pragma unroll
;                 for (int bj = 0; bj < 2; ++bj) { const f32x4 v0 = acc[ai][bj][m][0], v1 = acc[ai][bj][m][1]; const u32x4 yw = yv[m][bj];
;                     const f32x4 y0 = (f32x4){bf_lo(yw.x), bf_hi(yw.x), bf_lo(yw.y), bf_hi(yw.y)}, y1 = (f32x4){bf_lo(yw.z), bf_hi(yw.z), bf_lo(yw.w), bf_hi(yw.w)};
;                     const f32x4 n0 = (y0 - mu) * rs * gw[bj][0], n1 = (y1 - mu) * rs * gw[bj][1];
;                     const f32x4 s0 = silu4(v0) * n0, s1 = silu4(v1) * n1;
;                     u32x4 w; w.x = cvt_pk_bf16(s0[0], s0[1]); w.y = cvt_pk_bf16(s0[2], s0[3]); w.z = cvt_pk_bf16(s1[0], s1[1]); w.w = cvt_pk_bf16(s1[2], s1[3]);
;                     *(u32x4*)(rowp + bj * 128) = w; } }
	v_lshlrev_b32_e32 v246, 16, v228
	v_and_b32_e32 v228, 0xffff0000, v228
	v_lshlrev_b32_e32 v247, 16, v229
	v_and_b32_e32 v248, 0xffff0000, v229
	v_lshlrev_b32_e32 v249, 16, v230
	v_and_b32_e32 v250, 0xffff0000, v230
	v_lshlrev_b32_e32 v251, 16, v231
	v_and_b32_e32 v252, 0xffff0000, v231
	v_sub_f32_e32 v229, v228, v240
	v_sub_f32_e32 v228, v246, v240
	v_sub_f32_e32 v231, v248, v240
	v_sub_f32_e32 v230, v247, v240
	v_sub_f32_e32 v247, v250, v240
	v_sub_f32_e32 v246, v249, v240
	v_sub_f32_e32 v249, v252, v240
	v_sub_f32_e32 v248, v251, v240
	v_mul_f32_e32 v250, 0xbfb8aa3b, v142
	v_mul_f32_e32 v251, 0xbfb8aa3b, v143
	v_mul_f32_e32 v252, 0xbfb8aa3b, v144
	v_mul_f32_e32 v253, 0xbfb8aa3b, v145
	v_exp_f32_e32 v250, v250
	v_exp_f32_e32 v251, v251
	v_exp_f32_e32 v252, v252
	v_exp_f32_e32 v253, v253
	v_add_f32_e32 v250, 1.0, v250
	v_add_f32_e32 v251, 1.0, v251
	v_add_f32_e32 v252, 1.0, v252
	v_add_f32_e32 v253, 1.0, v253
	v_rcp_f32_e32 v250, v250
	v_rcp_f32_e32 v251, v251
	v_rcp_f32_e32 v252, v252
	v_rcp_f32_e32 v253, v253
	v_pk_mul_f32 v[228:229], v[240:241], v[228:229] op_sel:[1,0]
	v_pk_mul_f32 v[142:143], v[142:143], v[250:251]
	v_mul_f32_e32 v250, 0xbfb8aa3b, v138
	v_pk_mul_f32 v[144:145], v[144:145], v[252:253]
	v_mul_f32_e32 v251, 0xbfb8aa3b, v139
	v_mul_f32_e32 v252, 0xbfb8aa3b, v140
	v_mul_f32_e32 v253, 0xbfb8aa3b, v141
	v_exp_f32_e32 v250, v250
	v_exp_f32_e32 v251, v251
	v_exp_f32_e32 v252, v252
	v_exp_f32_e32 v253, v253
	v_add_f32_e32 v250, 1.0, v250
	v_add_f32_e32 v251, 1.0, v251
	v_add_f32_e32 v252, 1.0, v252
	v_add_f32_e32 v253, 1.0, v253
	v_rcp_f32_e32 v250, v250
	v_rcp_f32_e32 v251, v251
	v_rcp_f32_e32 v252, v252
	v_rcp_f32_e32 v253, v253
	v_pk_mul_f32 v[248:249], v[240:241], v[248:249] op_sel:[1,0]
	v_pk_mul_f32 v[246:247], v[240:241], v[246:247] op_sel:[1,0]
	v_pk_mul_f32 v[230:231], v[240:241], v[230:231] op_sel:[1,0]
	v_pk_mul_f32 v[228:229], v[86:87], v[228:229]
	v_pk_mul_f32 v[246:247], v[82:83], v[246:247]
	v_pk_mul_f32 v[248:249], v[84:85], v[248:249]
	v_pk_mul_f32 v[138:139], v[138:139], v[250:251]
	v_pk_mul_f32 v[140:141], v[140:141], v[252:253]
	v_pk_mul_f32 v[230:231], v[88:89], v[230:231]
	v_pk_mul_f32 v[142:143], v[142:143], v[228:229]
	v_pk_mul_f32 v[228:229], v[140:141], v[248:249]
	v_pk_mul_f32 v[140:141], v[138:139], v[246:247]
	v_pk_mul_f32 v[144:145], v[144:145], v[230:231]
	v_cvt_pk_bf16_f32 v140, v140, v141
	v_cvt_pk_bf16_f32 v141, v228, v229
	v_mul_f32_e32 v228, 0xbfb8aa3b, v134
	v_mul_f32_e32 v229, 0xbfb8aa3b, v135
	v_mul_f32_e32 v230, 0xbfb8aa3b, v136
	v_mul_f32_e32 v231, 0xbfb8aa3b, v137
	v_exp_f32_e32 v228, v228
	v_exp_f32_e32 v229, v229
	v_exp_f32_e32 v230, v230
	v_exp_f32_e32 v231, v231
	v_add_f32_e32 v228, 1.0, v228
	v_add_f32_e32 v229, 1.0, v229
	v_add_f32_e32 v230, 1.0, v230
	v_add_f32_e32 v231, 1.0, v231
	v_rcp_f32_e32 v228, v228
	v_rcp_f32_e32 v229, v229
	v_rcp_f32_e32 v230, v230
	v_rcp_f32_e32 v231, v231
	v_lshl_add_u64 v[242:243], s[34:35], 0, v[242:243]
	v_pk_mul_f32 v[134:135], v[134:135], v[228:229]
	v_mul_f32_e32 v228, 0xbfb8aa3b, v130
	v_pk_mul_f32 v[136:137], v[136:137], v[230:231]
	v_mul_f32_e32 v229, 0xbfb8aa3b, v131
	v_mul_f32_e32 v230, 0xbfb8aa3b, v132
	v_mul_f32_e32 v231, 0xbfb8aa3b, v133
	v_exp_f32_e32 v228, v228
	v_exp_f32_e32 v229, v229
	v_exp_f32_e32 v230, v230
	v_exp_f32_e32 v231, v231
	v_add_f32_e32 v228, 1.0, v228
	v_add_f32_e32 v229, 1.0, v229
	v_add_f32_e32 v230, 1.0, v230
	v_add_f32_e32 v231, 1.0, v231
	v_lshl_add_u64 v[242:243], v[242:243], 0, v[182:183]
	v_cvt_pk_bf16_f32 v138, v142, v143
	v_cvt_pk_bf16_f32 v139, v144, v145
	v_rcp_f32_e32 v228, v228
	v_rcp_f32_e32 v229, v229
	v_rcp_f32_e32 v230, v230
	v_rcp_f32_e32 v231, v231
	global_store_dwordx4 v[242:243], v[138:141], off
	v_lshlrev_b32_e32 v142, 16, v234
	v_and_b32_e32 v143, 0xffff0000, v234
	v_lshlrev_b32_e32 v138, 16, v232
	v_and_b32_e32 v139, 0xffff0000, v232
	v_lshlrev_b32_e32 v140, 16, v233
	v_and_b32_e32 v141, 0xffff0000, v233
	v_lshlrev_b32_e32 v144, 16, v235
	v_and_b32_e32 v145, 0xffff0000, v235
	v_sub_f32_e32 v139, v139, v240
	v_sub_f32_e32 v138, v138, v240
	v_sub_f32_e32 v141, v141, v240
	v_sub_f32_e32 v140, v140, v240
	v_sub_f32_e32 v143, v143, v240
	v_sub_f32_e32 v142, v142, v240
	v_sub_f32_e32 v145, v145, v240
	v_sub_f32_e32 v144, v144, v240
	v_pk_mul_f32 v[140:141], v[240:241], v[140:141] op_sel:[1,0]
	v_pk_mul_f32 v[138:139], v[240:241], v[138:139] op_sel:[1,0]
	v_pk_mul_f32 v[144:145], v[240:241], v[144:145] op_sel:[1,0]
	v_pk_mul_f32 v[142:143], v[240:241], v[142:143] op_sel:[1,0]
	v_pk_mul_f32 v[138:139], v[70:71], v[138:139]
	v_pk_mul_f32 v[140:141], v[72:73], v[140:141]
	v_pk_mul_f32 v[142:143], v[66:67], v[142:143]
	v_pk_mul_f32 v[144:145], v[68:69], v[144:145]
	v_pk_mul_f32 v[130:131], v[130:131], v[228:229]
	v_pk_mul_f32 v[132:133], v[132:133], v[230:231]
	v_pk_mul_f32 v[136:137], v[136:137], v[140:141]
	v_pk_mul_f32 v[134:135], v[134:135], v[138:139]
	v_pk_mul_f32 v[138:139], v[132:133], v[144:145]
	v_pk_mul_f32 v[132:133], v[130:131], v[142:143]
	v_mul_f32_e32 v140, 0xbfb8aa3b, v126
	v_mul_f32_e32 v141, 0xbfb8aa3b, v127
	v_mul_f32_e32 v142, 0xbfb8aa3b, v128
	v_mul_f32_e32 v143, 0xbfb8aa3b, v129
	v_exp_f32_e32 v140, v140
	v_exp_f32_e32 v141, v141
	v_exp_f32_e32 v142, v142
	v_exp_f32_e32 v143, v143
	v_add_f32_e32 v140, 1.0, v140
	v_add_f32_e32 v141, 1.0, v141
	v_add_f32_e32 v142, 1.0, v142
	v_add_f32_e32 v143, 1.0, v143
	v_rcp_f32_e32 v140, v140
	v_rcp_f32_e32 v141, v141
	v_rcp_f32_e32 v142, v142
	v_rcp_f32_e32 v143, v143
	v_cvt_pk_bf16_f32 v132, v132, v133
	v_pk_mul_f32 v[126:127], v[126:127], v[140:141]
	v_mul_f32_e32 v140, 0xbfb8aa3b, v122
	v_pk_mul_f32 v[128:129], v[128:129], v[142:143]
; __device__ __forceinline__ unsigned cvt_pk_bf16(float lo, float hi) { unsigned r; asm("v_cvt_pk_bf16_f32 %0, %1, %2" : "=v"(r) : "v"(lo), "v"(hi)); return r; }
; __device__ __forceinline__ float bf_lo(unsigned u) { return __uint_as_float(u << 16); }
; __device__ __forceinline__ float bf_hi(unsigned u) { return __uint_as_float(u & 0xffff0000u); }
;     __device__ __forceinline__ void operator()(const AccT& acc, const Unit& u, int wr, int wc, int fr, int fq) const {
;     ...
; #pragma unroll
;             for (int m = 0; m < 4; ++m) { bf16_t* rowp = A2 + (size_t)(row0 + ai * 128 + m * 16) * 2048 + col0;
;                 const float mu = st[ai][m][0], rs = st[ai][m][1];
; #pragma unroll
;                 for (int bj = 0; bj < 2; ++bj) { const f32x4 v0 = acc[ai][bj][m][0], v1 = acc[ai][bj][m][1]; const u32x4 yw = yv[m][bj];
;                     const f32x4 y0 = (f32x4){bf_lo(yw.x), bf_hi(yw.x), bf_lo(yw.y), bf_hi(yw.y)}, y1 = (f32x4){bf_lo(yw.z), bf_hi(yw.z), bf_lo(yw.w), bf_hi(yw.w)};
;                     const f32x4 n0 = (y0 - mu) * rs * gw[bj][0], n1 = (y1 - mu) * rs * gw[bj][1];
;                     const f32x4 s0 = silu4(v0) * n0, s1 = silu4(v1) * n1;
;                     u32x4 w; w.x = cvt_pk_bf16(s0[0], s0[1]); w.y = cvt_pk_bf16(s0[2], s0[3]); w.z = cvt_pk_bf16(s1[0], s1[1]); w.w = cvt_pk_bf16(s1[2], s1[3]);
;                     *(u32x4*)(rowp + bj * 128) = w; } }
	v_mul_f32_e32 v141, 0xbfb8aa3b, v123
	v_mul_f32_e32 v142, 0xbfb8aa3b, v124
	v_mul_f32_e32 v143, 0xbfb8aa3b, v125
	v_exp_f32_e32 v140, v140
	v_exp_f32_e32 v141, v141
	v_exp_f32_e32 v142, v142
	v_exp_f32_e32 v143, v143
	v_add_f32_e32 v140, 1.0, v140
	v_add_f32_e32 v141, 1.0, v141
	v_add_f32_e32 v142, 1.0, v142
	v_add_f32_e32 v143, 1.0, v143
	v_cvt_pk_bf16_f32 v133, v138, v139
	v_rcp_f32_e32 v140, v140
	v_rcp_f32_e32 v141, v141
	v_rcp_f32_e32 v142, v142
	v_rcp_f32_e32 v143, v143
	v_cvt_pk_bf16_f32 v130, v134, v135
	v_cvt_pk_bf16_f32 v131, v136, v137
	global_store_dwordx4 v[242:243], v[130:133], off offset:256
	v_lshlrev_b32_e32 v136, 16, v238
	v_and_b32_e32 v137, 0xffff0000, v238
	v_lshlrev_b32_e32 v132, 16, v236
	v_and_b32_e32 v133, 0xffff0000, v236
	v_lshlrev_b32_e32 v138, 16, v239
	v_and_b32_e32 v139, 0xffff0000, v239
	v_lshlrev_b32_e32 v134, 16, v237
	v_and_b32_e32 v135, 0xffff0000, v237
	v_sub_f32_e32 v133, v133, v208
	v_sub_f32_e32 v132, v132, v208
	v_sub_f32_e32 v137, v137, v208
	v_sub_f32_e32 v136, v136, v208
	v_sub_f32_e32 v139, v139, v208
	v_sub_f32_e32 v138, v138, v208
	v_sub_f32_e32 v135, v135, v208
	v_sub_f32_e32 v134, v134, v208
	v_pk_mul_f32 v[132:133], v[208:209], v[132:133] op_sel:[1,0]
	v_pk_mul_f32 v[138:139], v[208:209], v[138:139] op_sel:[1,0]
	v_pk_mul_f32 v[136:137], v[208:209], v[136:137] op_sel:[1,0]
	v_pk_mul_f32 v[134:135], v[208:209], v[134:135] op_sel:[1,0]
	v_pk_mul_f32 v[132:133], v[86:87], v[132:133]
	v_pk_mul_f32 v[136:137], v[82:83], v[136:137]
	v_pk_mul_f32 v[138:139], v[84:85], v[138:139]
	v_pk_mul_f32 v[122:123], v[122:123], v[140:141]
	v_pk_mul_f32 v[124:125], v[124:125], v[142:143]
	v_pk_mul_f32 v[134:135], v[88:89], v[134:135]
	v_pk_mul_f32 v[126:127], v[126:127], v[132:133]
	v_pk_mul_f32 v[132:133], v[124:125], v[138:139]
	v_pk_mul_f32 v[124:125], v[122:123], v[136:137]
	v_pk_mul_f32 v[128:129], v[128:129], v[134:135]
	v_cvt_pk_bf16_f32 v124, v124, v125
	v_cvt_pk_bf16_f32 v125, v132, v133
	v_mul_f32_e32 v132, 0xbfb8aa3b, v118
	v_mul_f32_e32 v133, 0xbfb8aa3b, v119
	v_mul_f32_e32 v134, 0xbfb8aa3b, v120
	v_mul_f32_e32 v135, 0xbfb8aa3b, v121
	v_exp_f32_e32 v132, v132
	v_exp_f32_e32 v133, v133
	v_exp_f32_e32 v134, v134
	v_exp_f32_e32 v135, v135
	v_add_f32_e32 v132, 1.0, v132
	v_add_f32_e32 v133, 1.0, v133
	v_add_f32_e32 v134, 1.0, v134
	v_add_f32_e32 v135, 1.0, v135
	v_rcp_f32_e32 v132, v132
	v_rcp_f32_e32 v133, v133
	v_rcp_f32_e32 v134, v134
	v_rcp_f32_e32 v135, v135
	v_lshl_add_u64 v[130:131], s[34:35], 0, v[244:245]
	v_pk_mul_f32 v[118:119], v[118:119], v[132:133]
	v_mul_f32_e32 v132, 0xbfb8aa3b, v114
	v_pk_mul_f32 v[120:121], v[120:121], v[134:135]
	v_mul_f32_e32 v133, 0xbfb8aa3b, v115
	v_mul_f32_e32 v134, 0xbfb8aa3b, v116
	v_mul_f32_e32 v135, 0xbfb8aa3b, v117
	v_exp_f32_e32 v132, v132
	v_exp_f32_e32 v133, v133
	v_exp_f32_e32 v134, v134
	v_exp_f32_e32 v135, v135
	v_add_f32_e32 v132, 1.0, v132
	v_add_f32_e32 v133, 1.0, v133
	v_add_f32_e32 v134, 1.0, v134
	v_add_f32_e32 v135, 1.0, v135
	v_lshl_add_u64 v[130:131], v[130:131], 0, v[182:183]
	v_cvt_pk_bf16_f32 v122, v126, v127
	v_cvt_pk_bf16_f32 v123, v128, v129
	v_rcp_f32_e32 v132, v132
	v_rcp_f32_e32 v133, v133
	v_rcp_f32_e32 v134, v134
	v_rcp_f32_e32 v135, v135
	global_store_dwordx4 v[130:131], v[122:125], off
	v_lshlrev_b32_e32 v126, 16, v164
	v_and_b32_e32 v127, 0xffff0000, v164
	v_lshlrev_b32_e32 v122, 16, v162
	v_and_b32_e32 v123, 0xffff0000, v162
	v_lshlrev_b32_e32 v124, 16, v163
	v_and_b32_e32 v125, 0xffff0000, v163
	v_lshlrev_b32_e32 v128, 16, v165
	v_and_b32_e32 v129, 0xffff0000, v165
	v_sub_f32_e32 v123, v123, v208
	v_sub_f32_e32 v122, v122, v208
	v_sub_f32_e32 v125, v125, v208
	v_sub_f32_e32 v124, v124, v208
	v_sub_f32_e32 v127, v127, v208
	v_sub_f32_e32 v126, v126, v208
	v_sub_f32_e32 v129, v129, v208
	v_sub_f32_e32 v128, v128, v208
	v_pk_mul_f32 v[124:125], v[208:209], v[124:125] op_sel:[1,0]
	v_pk_mul_f32 v[122:123], v[208:209], v[122:123] op_sel:[1,0]
	v_pk_mul_f32 v[128:129], v[208:209], v[128:129] op_sel:[1,0]
	v_pk_mul_f32 v[126:127], v[208:209], v[126:127] op_sel:[1,0]
	v_pk_mul_f32 v[122:123], v[70:71], v[122:123]
	v_pk_mul_f32 v[124:125], v[72:73], v[124:125]
	v_pk_mul_f32 v[126:127], v[66:67], v[126:127]
	v_pk_mul_f32 v[128:129], v[68:69], v[128:129]
	v_pk_mul_f32 v[114:115], v[114:115], v[132:133]
	v_pk_mul_f32 v[116:117], v[116:117], v[134:135]
	v_pk_mul_f32 v[120:121], v[120:121], v[124:125]
	v_pk_mul_f32 v[118:119], v[118:119], v[122:123]
	v_pk_mul_f32 v[122:123], v[116:117], v[128:129]
	v_pk_mul_f32 v[116:117], v[114:115], v[126:127]
	v_mul_f32_e32 v124, 0xbfb8aa3b, v110
	v_mul_f32_e32 v125, 0xbfb8aa3b, v111
	v_mul_f32_e32 v126, 0xbfb8aa3b, v112
	v_mul_f32_e32 v127, 0xbfb8aa3b, v113
	v_exp_f32_e32 v124, v124
	v_exp_f32_e32 v125, v125
	v_exp_f32_e32 v126, v126
	v_exp_f32_e32 v127, v127
	v_add_f32_e32 v124, 1.0, v124
	v_add_f32_e32 v125, 1.0, v125
	v_add_f32_e32 v126, 1.0, v126
	v_add_f32_e32 v127, 1.0, v127
	v_rcp_f32_e32 v124, v124
	v_rcp_f32_e32 v125, v125
	v_rcp_f32_e32 v126, v126
	v_rcp_f32_e32 v127, v127
	v_cvt_pk_bf16_f32 v116, v116, v117
	v_pk_mul_f32 v[110:111], v[110:111], v[124:125]
	v_mul_f32_e32 v124, 0xbfb8aa3b, v106
	v_pk_mul_f32 v[112:113], v[112:113], v[126:127]
	v_mul_f32_e32 v125, 0xbfb8aa3b, v107
	v_mul_f32_e32 v126, 0xbfb8aa3b, v108
	v_mul_f32_e32 v127, 0xbfb8aa3b, v109
	v_exp_f32_e32 v124, v124
	v_exp_f32_e32 v125, v125
	v_exp_f32_e32 v126, v126
	v_exp_f32_e32 v127, v127
	v_add_f32_e32 v124, 1.0, v124
	v_add_f32_e32 v125, 1.0, v125
	v_add_f32_e32 v126, 1.0, v126
	v_add_f32_e32 v127, 1.0, v127
	v_cvt_pk_bf16_f32 v117, v122, v123
	v_rcp_f32_e32 v124, v124
	v_rcp_f32_e32 v125, v125
	v_rcp_f32_e32 v126, v126
; __device__ __forceinline__ unsigned cvt_pk_bf16(float lo, float hi) { unsigned r; asm("v_cvt_pk_bf16_f32 %0, %1, %2" : "=v"(r) : "v"(lo), "v"(hi)); return r; }
; __device__ __forceinline__ float bf_lo(unsigned u) { return __uint_as_float(u << 16); }
; __device__ __forceinline__ float bf_hi(unsigned u) { return __uint_as_float(u & 0xffff0000u); }
;     __device__ __forceinline__ void operator()(const AccT& acc, const Unit& u, int wr, int wc, int fr, int fq) const {
;     ...
; #pragma unroll
;             for (int m = 0; m < 4; ++m) { bf16_t* rowp = A2 + (size_t)(row0 + ai * 128 + m * 16) * 2048 + col0;
;                 const float mu = st[ai][m][0], rs = st[ai][m][1];
; #pragma unroll
;                 for (int bj = 0; bj < 2; ++bj) { const f32x4 v0 = acc[ai][bj][m][0], v1 = acc[ai][bj][m][1]; const u32x4 yw = yv[m][bj];
;                     const f32x4 y0 = (f32x4){bf_lo(yw.x), bf_hi(yw.x), bf_lo(yw.y), bf_hi(yw.y)}, y1 = (f32x4){bf_lo(yw.z), bf_hi(yw.z), bf_lo(yw.w), bf_hi(yw.w)};
;                     const f32x4 n0 = (y0 - mu) * rs * gw[bj][0], n1 = (y1 - mu) * rs * gw[bj][1];
;                     const f32x4 s0 = silu4(v0) * n0, s1 = silu4(v1) * n1;
;                     u32x4 w; w.x = cvt_pk_bf16(s0[0], s0[1]); w.y = cvt_pk_bf16(s0[2], s0[3]); w.z = cvt_pk_bf16(s1[0], s1[1]); w.w = cvt_pk_bf16(s1[2], s1[3]);
;                     *(u32x4*)(rowp + bj * 128) = w; } }
	v_rcp_f32_e32 v127, v127
	v_cvt_pk_bf16_f32 v114, v118, v119
	v_cvt_pk_bf16_f32 v115, v120, v121
	global_store_dwordx4 v[130:131], v[114:117], off offset:256
	v_lshlrev_b32_e32 v120, 16, v160
	v_and_b32_e32 v121, 0xffff0000, v160
	v_lshlrev_b32_e32 v116, 16, v158
	v_and_b32_e32 v117, 0xffff0000, v158
	v_lshlrev_b32_e32 v122, 16, v161
	v_and_b32_e32 v123, 0xffff0000, v161
	v_lshlrev_b32_e32 v118, 16, v159
	v_and_b32_e32 v119, 0xffff0000, v159
	v_sub_f32_e32 v117, v117, v204
	v_sub_f32_e32 v116, v116, v204
	v_sub_f32_e32 v121, v121, v204
	v_sub_f32_e32 v120, v120, v204
	v_sub_f32_e32 v123, v123, v204
	v_sub_f32_e32 v122, v122, v204
	v_sub_f32_e32 v119, v119, v204
	v_sub_f32_e32 v118, v118, v204
	v_pk_mul_f32 v[116:117], v[204:205], v[116:117] op_sel:[1,0]
	v_pk_mul_f32 v[122:123], v[204:205], v[122:123] op_sel:[1,0]
	v_pk_mul_f32 v[120:121], v[204:205], v[120:121] op_sel:[1,0]
	v_pk_mul_f32 v[118:119], v[204:205], v[118:119] op_sel:[1,0]
	v_pk_mul_f32 v[116:117], v[86:87], v[116:117]
	v_pk_mul_f32 v[120:121], v[82:83], v[120:121]
	v_pk_mul_f32 v[122:123], v[84:85], v[122:123]
	v_pk_mul_f32 v[106:107], v[106:107], v[124:125]
	v_pk_mul_f32 v[108:109], v[108:109], v[126:127]
	v_pk_mul_f32 v[118:119], v[88:89], v[118:119]
	v_pk_mul_f32 v[110:111], v[110:111], v[116:117]
	v_pk_mul_f32 v[116:117], v[108:109], v[122:123]
	v_pk_mul_f32 v[108:109], v[106:107], v[120:121]
	v_pk_mul_f32 v[112:113], v[112:113], v[118:119]
	v_cvt_pk_bf16_f32 v108, v108, v109
	v_cvt_pk_bf16_f32 v109, v116, v117
	v_mul_f32_e32 v116, 0xbfb8aa3b, v102
	v_mul_f32_e32 v117, 0xbfb8aa3b, v103
	v_mul_f32_e32 v118, 0xbfb8aa3b, v104
	v_mul_f32_e32 v119, 0xbfb8aa3b, v105
	v_exp_f32_e32 v116, v116
	v_exp_f32_e32 v117, v117
	v_exp_f32_e32 v118, v118
	v_exp_f32_e32 v119, v119
	v_add_f32_e32 v116, 1.0, v116
	v_add_f32_e32 v117, 1.0, v117
	v_add_f32_e32 v118, 1.0, v118
	v_add_f32_e32 v119, 1.0, v119
	v_rcp_f32_e32 v116, v116
	v_rcp_f32_e32 v117, v117
	v_rcp_f32_e32 v118, v118
	v_rcp_f32_e32 v119, v119
	v_lshl_add_u64 v[114:115], s[34:35], 0, v[206:207]
	v_pk_mul_f32 v[102:103], v[102:103], v[116:117]
	v_mul_f32_e32 v116, 0xbfb8aa3b, v98
	v_pk_mul_f32 v[104:105], v[104:105], v[118:119]
	v_mul_f32_e32 v117, 0xbfb8aa3b, v99
	v_mul_f32_e32 v118, 0xbfb8aa3b, v100
	v_mul_f32_e32 v119, 0xbfb8aa3b, v101
	v_exp_f32_e32 v116, v116
	v_exp_f32_e32 v117, v117
	v_exp_f32_e32 v118, v118
	v_exp_f32_e32 v119, v119
	v_add_f32_e32 v116, 1.0, v116
	v_add_f32_e32 v117, 1.0, v117
	v_add_f32_e32 v118, 1.0, v118
	v_add_f32_e32 v119, 1.0, v119
	v_lshl_add_u64 v[114:115], v[114:115], 0, v[182:183]
	v_cvt_pk_bf16_f32 v106, v110, v111
	v_cvt_pk_bf16_f32 v107, v112, v113
	v_rcp_f32_e32 v116, v116
	v_rcp_f32_e32 v117, v117
	v_rcp_f32_e32 v118, v118
	v_rcp_f32_e32 v119, v119
	global_store_dwordx4 v[114:115], v[106:109], off
	v_lshlrev_b32_e32 v110, 16, v156
	v_and_b32_e32 v111, 0xffff0000, v156
	v_lshlrev_b32_e32 v106, 16, v154
	v_and_b32_e32 v107, 0xffff0000, v154
	v_lshlrev_b32_e32 v108, 16, v155
	v_and_b32_e32 v109, 0xffff0000, v155
	v_lshlrev_b32_e32 v112, 16, v157
	v_and_b32_e32 v113, 0xffff0000, v157
	v_sub_f32_e32 v107, v107, v204
	v_sub_f32_e32 v106, v106, v204
	v_sub_f32_e32 v109, v109, v204
	v_sub_f32_e32 v108, v108, v204
	v_sub_f32_e32 v111, v111, v204
	v_sub_f32_e32 v110, v110, v204
	v_sub_f32_e32 v113, v113, v204
	v_sub_f32_e32 v112, v112, v204
	v_pk_mul_f32 v[108:109], v[204:205], v[108:109] op_sel:[1,0]
	v_pk_mul_f32 v[106:107], v[204:205], v[106:107] op_sel:[1,0]
	v_pk_mul_f32 v[112:113], v[204:205], v[112:113] op_sel:[1,0]
	v_pk_mul_f32 v[110:111], v[204:205], v[110:111] op_sel:[1,0]
	v_pk_mul_f32 v[106:107], v[70:71], v[106:107]
	v_pk_mul_f32 v[108:109], v[72:73], v[108:109]
	v_pk_mul_f32 v[110:111], v[66:67], v[110:111]
	v_pk_mul_f32 v[112:113], v[68:69], v[112:113]
	v_pk_mul_f32 v[98:99], v[98:99], v[116:117]
	v_pk_mul_f32 v[100:101], v[100:101], v[118:119]
	v_pk_mul_f32 v[104:105], v[104:105], v[108:109]
	v_pk_mul_f32 v[102:103], v[102:103], v[106:107]
	v_pk_mul_f32 v[106:107], v[100:101], v[112:113]
	v_pk_mul_f32 v[100:101], v[98:99], v[110:111]
	v_mul_f32_e32 v108, 0xbfb8aa3b, v94
	v_mul_f32_e32 v109, 0xbfb8aa3b, v95
	v_mul_f32_e32 v110, 0xbfb8aa3b, v96
	v_mul_f32_e32 v111, 0xbfb8aa3b, v97
	v_exp_f32_e32 v108, v108
	v_exp_f32_e32 v109, v109
	v_exp_f32_e32 v110, v110
	v_exp_f32_e32 v111, v111
	v_add_f32_e32 v108, 1.0, v108
	v_add_f32_e32 v109, 1.0, v109
	v_add_f32_e32 v110, 1.0, v110
	v_add_f32_e32 v111, 1.0, v111
	v_rcp_f32_e32 v108, v108
	v_rcp_f32_e32 v109, v109
	v_rcp_f32_e32 v110, v110
	v_rcp_f32_e32 v111, v111
	v_cvt_pk_bf16_f32 v100, v100, v101
	v_pk_mul_f32 v[94:95], v[94:95], v[108:109]
	v_mul_f32_e32 v108, 0xbfb8aa3b, v90
	v_pk_mul_f32 v[96:97], v[96:97], v[110:111]
	v_mul_f32_e32 v109, 0xbfb8aa3b, v91
	v_mul_f32_e32 v110, 0xbfb8aa3b, v92
	v_mul_f32_e32 v111, 0xbfb8aa3b, v93
	v_exp_f32_e32 v108, v108
	v_exp_f32_e32 v109, v109
	v_exp_f32_e32 v110, v110
	v_exp_f32_e32 v111, v111
	v_add_f32_e32 v108, 1.0, v108
	v_add_f32_e32 v109, 1.0, v109
	v_add_f32_e32 v110, 1.0, v110
	v_add_f32_e32 v111, 1.0, v111
	v_cvt_pk_bf16_f32 v101, v106, v107
	v_rcp_f32_e32 v108, v108
	v_rcp_f32_e32 v109, v109
	v_rcp_f32_e32 v110, v110
	v_rcp_f32_e32 v111, v111
	v_cvt_pk_bf16_f32 v98, v102, v103
	v_cvt_pk_bf16_f32 v99, v104, v105
	global_store_dwordx4 v[114:115], v[98:101], off offset:256
	v_lshlrev_b32_e32 v104, 16, v152
	v_and_b32_e32 v105, 0xffff0000, v152
	v_lshlrev_b32_e32 v100, 16, v150
	v_and_b32_e32 v101, 0xffff0000, v150
	v_lshlrev_b32_e32 v106, 16, v153
	v_and_b32_e32 v107, 0xffff0000, v153
	v_lshlrev_b32_e32 v102, 16, v151
	v_and_b32_e32 v103, 0xffff0000, v151
	v_sub_f32_e32 v101, v101, v200
; __device__ __forceinline__ unsigned cvt_pk_bf16(float lo, float hi) { unsigned r; asm("v_cvt_pk_bf16_f32 %0, %1, %2" : "=v"(r) : "v"(lo), "v"(hi)); return r; }
; __device__ __forceinline__ float bf_lo(unsigned u) { return __uint_as_float(u << 16); }
; __device__ __forceinline__ float bf_hi(unsigned u) { return __uint_as_float(u & 0xffff0000u); }
;     __device__ __forceinline__ void operator()(const AccT& acc, const Unit& u, int wr, int wc, int fr, int fq) const {
;     ...
;         for (int ai = 0; ai < 2; ++ai) {
;             u32x4 yv[4][2];
; #pragma unroll
;             for (int m = 0; m < 4; ++m)
; #pragma unroll
;                 for (int bj = 0; bj < 2; ++bj) yv[m][bj] = *(const u32x4*)(Y + (size_t)(row0 + ai * 128 + m * 16) * 2048 + col0 + bj * 128);
;             __builtin_amdgcn_sched_barrier(0);
; #pragma unroll
;             for (int m = 0; m < 4; ++m) { bf16_t* rowp = A2 + (size_t)(row0 + ai * 128 + m * 16) * 2048 + col0;
;                 const float mu = st[ai][m][0], rs = st[ai][m][1];
; #pragma unroll
;                 for (int bj = 0; bj < 2; ++bj) { const f32x4 v0 = acc[ai][bj][m][0], v1 = acc[ai][bj][m][1]; const u32x4 yw = yv[m][bj];
;                     const f32x4 y0 = (f32x4){bf_lo(yw.x), bf_hi(yw.x), bf_lo(yw.y), bf_hi(yw.y)}, y1 = (f32x4){bf_lo(yw.z), bf_hi(yw.z), bf_lo(yw.w), bf_hi(yw.w)};
;                     const f32x4 n0 = (y0 - mu) * rs * gw[bj][0], n1 = (y1 - mu) * rs * gw[bj][1];
;                     const f32x4 s0 = silu4(v0) * n0, s1 = silu4(v1) * n1;
;                     u32x4 w; w.x = cvt_pk_bf16(s0[0], s0[1]); w.y = cvt_pk_bf16(s0[2], s0[3]); w.z = cvt_pk_bf16(s1[0], s1[1]); w.w = cvt_pk_bf16(s1[2], s1[3]);
;                     *(u32x4*)(rowp + bj * 128) = w; } }
	v_sub_f32_e32 v100, v100, v200
	v_sub_f32_e32 v105, v105, v200
	v_sub_f32_e32 v104, v104, v200
	v_sub_f32_e32 v107, v107, v200
	v_sub_f32_e32 v106, v106, v200
	v_sub_f32_e32 v103, v103, v200
	v_sub_f32_e32 v102, v102, v200
	v_pk_mul_f32 v[100:101], v[200:201], v[100:101] op_sel:[1,0]
	v_pk_mul_f32 v[106:107], v[200:201], v[106:107] op_sel:[1,0]
	v_pk_mul_f32 v[104:105], v[200:201], v[104:105] op_sel:[1,0]
	v_pk_mul_f32 v[102:103], v[200:201], v[102:103] op_sel:[1,0]
	v_pk_mul_f32 v[100:101], v[86:87], v[100:101]
	v_pk_mul_f32 v[104:105], v[82:83], v[104:105]
	v_pk_mul_f32 v[106:107], v[84:85], v[106:107]
	v_pk_mul_f32 v[90:91], v[90:91], v[108:109]
	v_pk_mul_f32 v[92:93], v[92:93], v[110:111]
	v_pk_mul_f32 v[102:103], v[88:89], v[102:103]
	v_pk_mul_f32 v[94:95], v[94:95], v[100:101]
	v_pk_mul_f32 v[100:101], v[92:93], v[106:107]
	v_pk_mul_f32 v[92:93], v[90:91], v[104:105]
	v_pk_mul_f32 v[96:97], v[96:97], v[102:103]
	v_cvt_pk_bf16_f32 v92, v92, v93
	v_cvt_pk_bf16_f32 v93, v100, v101
	v_mul_f32_e32 v100, 0xbfb8aa3b, v78
	v_mul_f32_e32 v101, 0xbfb8aa3b, v79
	v_mul_f32_e32 v102, 0xbfb8aa3b, v80
	v_mul_f32_e32 v103, 0xbfb8aa3b, v81
	v_exp_f32_e32 v100, v100
	v_exp_f32_e32 v101, v101
	v_exp_f32_e32 v102, v102
	v_exp_f32_e32 v103, v103
	v_add_f32_e32 v100, 1.0, v100
	v_add_f32_e32 v101, 1.0, v101
	v_add_f32_e32 v102, 1.0, v102
	v_add_f32_e32 v103, 1.0, v103
	v_rcp_f32_e32 v100, v100
	v_rcp_f32_e32 v101, v101
	v_rcp_f32_e32 v102, v102
	v_rcp_f32_e32 v103, v103
	v_lshl_add_u64 v[98:99], s[34:35], 0, v[202:203]
	v_pk_mul_f32 v[78:79], v[78:79], v[100:101]
	v_mul_f32_e32 v100, 0xbfb8aa3b, v74
	v_pk_mul_f32 v[80:81], v[80:81], v[102:103]
	v_mul_f32_e32 v101, 0xbfb8aa3b, v75
	v_mul_f32_e32 v102, 0xbfb8aa3b, v76
	v_mul_f32_e32 v103, 0xbfb8aa3b, v77
	v_exp_f32_e32 v100, v100
	v_exp_f32_e32 v101, v101
	v_exp_f32_e32 v102, v102
	v_exp_f32_e32 v103, v103
	v_add_f32_e32 v100, 1.0, v100
	v_add_f32_e32 v101, 1.0, v101
	v_add_f32_e32 v102, 1.0, v102
	v_add_f32_e32 v103, 1.0, v103
	v_lshl_add_u64 v[98:99], v[98:99], 0, v[182:183]
	v_cvt_pk_bf16_f32 v90, v94, v95
	v_cvt_pk_bf16_f32 v91, v96, v97
	v_rcp_f32_e32 v100, v100
	v_rcp_f32_e32 v101, v101
	v_rcp_f32_e32 v102, v102
	v_rcp_f32_e32 v103, v103
	global_store_dwordx4 v[98:99], v[90:93], off
	v_lshlrev_b32_e32 v94, 16, v148
	v_and_b32_e32 v95, 0xffff0000, v148
	v_lshlrev_b32_e32 v90, 16, v146
	v_and_b32_e32 v91, 0xffff0000, v146
	v_lshlrev_b32_e32 v96, 16, v149
	v_and_b32_e32 v97, 0xffff0000, v149
	v_lshlrev_b32_e32 v92, 16, v147
	v_and_b32_e32 v93, 0xffff0000, v147
	v_sub_f32_e32 v91, v91, v200
	v_sub_f32_e32 v90, v90, v200
	v_sub_f32_e32 v95, v95, v200
	v_sub_f32_e32 v94, v94, v200
	v_sub_f32_e32 v97, v97, v200
	v_sub_f32_e32 v96, v96, v200
	v_sub_f32_e32 v93, v93, v200
	v_sub_f32_e32 v92, v92, v200
	v_pk_mul_f32 v[90:91], v[200:201], v[90:91] op_sel:[1,0]
	v_pk_mul_f32 v[96:97], v[200:201], v[96:97] op_sel:[1,0]
	v_pk_mul_f32 v[94:95], v[200:201], v[94:95] op_sel:[1,0]
	v_pk_mul_f32 v[92:93], v[200:201], v[92:93] op_sel:[1,0]
	v_pk_mul_f32 v[90:91], v[70:71], v[90:91]
	v_pk_mul_f32 v[94:95], v[66:67], v[94:95]
	v_pk_mul_f32 v[96:97], v[68:69], v[96:97]
	v_pk_mul_f32 v[74:75], v[74:75], v[100:101]
	v_pk_mul_f32 v[76:77], v[76:77], v[102:103]
	v_pk_mul_f32 v[92:93], v[72:73], v[92:93]
	v_pk_mul_f32 v[78:79], v[78:79], v[90:91]
	v_pk_mul_f32 v[90:91], v[76:77], v[96:97]
	v_pk_mul_f32 v[76:77], v[74:75], v[94:95]
	v_pk_mul_f32 v[80:81], v[80:81], v[92:93]
	v_cvt_pk_bf16_f32 v74, v78, v79
	v_cvt_pk_bf16_f32 v76, v76, v77
	v_cvt_pk_bf16_f32 v77, v90, v91
	s_nop 0
	v_cvt_pk_bf16_f32 v75, v80, v81
	global_store_dwordx4 v[98:99], v[74:77], off offset:256
	v_lshlrev_b64 v[118:119], 12, v[190:191]
	s_nop 0
	v_lshl_add_u64 v[74:75], v[198:199], 0, v[118:119]
	v_lshlrev_b64 v[120:121], 12, v[192:193]
	global_load_dwordx4 v[106:109], v[74:75], off
	global_load_dwordx4 v[110:113], v[74:75], off offset:256
	v_lshl_add_u64 v[74:75], v[198:199], 0, v[120:121]
	v_lshlrev_b64 v[104:105], 12, v[194:195]
	global_load_dwordx4 v[114:117], v[74:75], off
	global_load_dwordx4 v[98:101], v[74:75], off offset:256
	v_lshl_add_u64 v[74:75], v[198:199], 0, v[104:105]
	v_lshlrev_b64 v[102:103], 12, v[196:197]
	global_load_dwordx4 v[94:97], v[74:75], off
	global_load_dwordx4 v[90:93], v[74:75], off offset:256
	v_lshl_add_u64 v[74:75], v[198:199], 0, v[102:103]
	global_load_dwordx4 v[78:81], v[74:75], off
	s_nop 0
	global_load_dwordx4 v[74:77], v[74:75], off offset:256
	s_waitcnt vmcnt(0)
; __device__ __forceinline__ unsigned cvt_pk_bf16(float lo, float hi) { unsigned r; asm("v_cvt_pk_bf16_f32 %0, %1, %2" : "=v"(r) : "v"(lo), "v"(hi)); return r; }
; __device__ __forceinline__ float bf_lo(unsigned u) { return __uint_as_float(u << 16); }
; __device__ __forceinline__ float bf_hi(unsigned u) { return __uint_as_float(u & 0xffff0000u); }
;     __device__ __forceinline__ void operator()(const AccT& acc, const Unit& u, int wr, int wc, int fr, int fq) const {
;     ...
;                 for (int bj = 0; bj < 2; ++bj) yv[m][bj] = *(const u32x4*)(Y + (size_t)(row0 + ai * 128 + m * 16) * 2048 + col0 + bj * 128);
;             __builtin_amdgcn_sched_barrier(0);
; #pragma unroll
;             for (int m = 0; m < 4; ++m) { bf16_t* rowp = A2 + (size_t)(row0 + ai * 128 + m * 16) * 2048 + col0;
;                 const float mu = st[ai][m][0], rs = st[ai][m][1];
; #pragma unroll
;                 for (int bj = 0; bj < 2; ++bj) { const f32x4 v0 = acc[ai][bj][m][0], v1 = acc[ai][bj][m][1]; const u32x4 yw = yv[m][bj];
;                     const f32x4 y0 = (f32x4){bf_lo(yw.x), bf_hi(yw.x), bf_lo(yw.y), bf_hi(yw.y)}, y1 = (f32x4){bf_lo(yw.z), bf_hi(yw.z), bf_lo(yw.w), bf_hi(yw.w)};
;                     const f32x4 n0 = (y0 - mu) * rs * gw[bj][0], n1 = (y1 - mu) * rs * gw[bj][1];
;                     const f32x4 s0 = silu4(v0) * n0, s1 = silu4(v1) * n1;
;                     u32x4 w; w.x = cvt_pk_bf16(s0[0], s0[1]); w.y = cvt_pk_bf16(s0[2], s0[3]); w.z = cvt_pk_bf16(s1[0], s1[1]); w.w = cvt_pk_bf16(s1[2], s1[3]);
;                     *(u32x4*)(rowp + bj * 128) = w; } }
	v_lshlrev_b32_e32 v122, 16, v106
	v_and_b32_e32 v106, 0xffff0000, v106
	v_lshlrev_b32_e32 v123, 16, v107
	v_and_b32_e32 v124, 0xffff0000, v107
	v_lshlrev_b32_e32 v125, 16, v108
	v_and_b32_e32 v126, 0xffff0000, v108
	v_lshlrev_b32_e32 v127, 16, v109
	v_and_b32_e32 v128, 0xffff0000, v109
	v_sub_f32_e32 v107, v106, v188
	v_sub_f32_e32 v106, v122, v188
	v_sub_f32_e32 v109, v124, v188
	v_sub_f32_e32 v108, v123, v188
	v_sub_f32_e32 v123, v126, v188
	v_sub_f32_e32 v122, v125, v188
	v_sub_f32_e32 v125, v128, v188
	v_sub_f32_e32 v124, v127, v188
	v_mul_f32_e32 v126, 0xbfb8aa3b, v62
	v_mul_f32_e32 v127, 0xbfb8aa3b, v63
	v_mul_f32_e32 v128, 0xbfb8aa3b, v64
	v_mul_f32_e32 v129, 0xbfb8aa3b, v65
	v_exp_f32_e32 v126, v126
	v_exp_f32_e32 v127, v127
	v_exp_f32_e32 v128, v128
	v_exp_f32_e32 v129, v129
	v_add_f32_e32 v126, 1.0, v126
	v_add_f32_e32 v127, 1.0, v127
	v_add_f32_e32 v128, 1.0, v128
	v_add_f32_e32 v129, 1.0, v129
	v_rcp_f32_e32 v126, v126
	v_rcp_f32_e32 v127, v127
	v_rcp_f32_e32 v128, v128
	v_rcp_f32_e32 v129, v129
	v_pk_mul_f32 v[106:107], v[188:189], v[106:107] op_sel:[1,0]
	v_pk_mul_f32 v[62:63], v[62:63], v[126:127]
	v_mul_f32_e32 v126, 0xbfb8aa3b, v58
	v_pk_mul_f32 v[64:65], v[64:65], v[128:129]
	v_mul_f32_e32 v127, 0xbfb8aa3b, v59
	v_mul_f32_e32 v128, 0xbfb8aa3b, v60
	v_mul_f32_e32 v129, 0xbfb8aa3b, v61
	v_exp_f32_e32 v126, v126
	v_exp_f32_e32 v127, v127
	v_exp_f32_e32 v128, v128
	v_exp_f32_e32 v129, v129
	v_add_f32_e32 v126, 1.0, v126
	v_add_f32_e32 v127, 1.0, v127
	v_add_f32_e32 v128, 1.0, v128
	v_add_f32_e32 v129, 1.0, v129
	v_rcp_f32_e32 v126, v126
	v_rcp_f32_e32 v127, v127
	v_rcp_f32_e32 v128, v128
	v_rcp_f32_e32 v129, v129
	v_pk_mul_f32 v[124:125], v[188:189], v[124:125] op_sel:[1,0]
	v_pk_mul_f32 v[122:123], v[188:189], v[122:123] op_sel:[1,0]
	v_pk_mul_f32 v[108:109], v[188:189], v[108:109] op_sel:[1,0]
	v_pk_mul_f32 v[106:107], v[86:87], v[106:107]
	v_pk_mul_f32 v[122:123], v[82:83], v[122:123]
	v_pk_mul_f32 v[124:125], v[84:85], v[124:125]
	v_pk_mul_f32 v[58:59], v[58:59], v[126:127]
	v_pk_mul_f32 v[60:61], v[60:61], v[128:129]
	v_pk_mul_f32 v[108:109], v[88:89], v[108:109]
	v_pk_mul_f32 v[62:63], v[62:63], v[106:107]
	v_pk_mul_f32 v[106:107], v[60:61], v[124:125]
	v_pk_mul_f32 v[60:61], v[58:59], v[122:123]
	v_pk_mul_f32 v[64:65], v[64:65], v[108:109]
	v_cvt_pk_bf16_f32 v60, v60, v61
	v_cvt_pk_bf16_f32 v61, v106, v107
	v_mul_f32_e32 v106, 0xbfb8aa3b, v54
	v_mul_f32_e32 v107, 0xbfb8aa3b, v55
	v_mul_f32_e32 v108, 0xbfb8aa3b, v56
	v_mul_f32_e32 v109, 0xbfb8aa3b, v57
	v_exp_f32_e32 v106, v106
	v_exp_f32_e32 v107, v107
	v_exp_f32_e32 v108, v108
	v_exp_f32_e32 v109, v109
	v_add_f32_e32 v106, 1.0, v106
	v_add_f32_e32 v107, 1.0, v107
	v_add_f32_e32 v108, 1.0, v108
	v_add_f32_e32 v109, 1.0, v109
	v_rcp_f32_e32 v106, v106
	v_rcp_f32_e32 v107, v107
	v_rcp_f32_e32 v108, v108
	v_rcp_f32_e32 v109, v109
	v_lshl_add_u64 v[118:119], s[34:35], 0, v[118:119]
	v_pk_mul_f32 v[54:55], v[54:55], v[106:107]
	v_mul_f32_e32 v106, 0xbfb8aa3b, v50
	v_pk_mul_f32 v[56:57], v[56:57], v[108:109]
	v_mul_f32_e32 v107, 0xbfb8aa3b, v51
	v_mul_f32_e32 v108, 0xbfb8aa3b, v52
	v_mul_f32_e32 v109, 0xbfb8aa3b, v53
	v_exp_f32_e32 v106, v106
	v_exp_f32_e32 v107, v107
	v_exp_f32_e32 v108, v108
	v_exp_f32_e32 v109, v109
	v_add_f32_e32 v106, 1.0, v106
	v_add_f32_e32 v107, 1.0, v107
	v_add_f32_e32 v108, 1.0, v108
	v_add_f32_e32 v109, 1.0, v109
	v_lshl_add_u64 v[118:119], v[118:119], 0, v[182:183]
	v_cvt_pk_bf16_f32 v58, v62, v63
	v_cvt_pk_bf16_f32 v59, v64, v65
	v_rcp_f32_e32 v106, v106
	v_rcp_f32_e32 v107, v107
	v_rcp_f32_e32 v108, v108
	v_rcp_f32_e32 v109, v109
	global_store_dwordx4 v[118:119], v[58:61], off
	v_lshlrev_b32_e32 v62, 16, v112
	v_and_b32_e32 v63, 0xffff0000, v112
	v_lshlrev_b32_e32 v58, 16, v110
	v_and_b32_e32 v59, 0xffff0000, v110
	v_lshlrev_b32_e32 v60, 16, v111
	v_and_b32_e32 v61, 0xffff0000, v111
	v_lshlrev_b32_e32 v64, 16, v113
	v_and_b32_e32 v65, 0xffff0000, v113
	v_sub_f32_e32 v59, v59, v188
	v_sub_f32_e32 v58, v58, v188
	v_sub_f32_e32 v61, v61, v188
	v_sub_f32_e32 v60, v60, v188
	v_sub_f32_e32 v63, v63, v188
	v_sub_f32_e32 v62, v62, v188
	v_sub_f32_e32 v65, v65, v188
	v_sub_f32_e32 v64, v64, v188
	v_pk_mul_f32 v[60:61], v[188:189], v[60:61] op_sel:[1,0]
	v_pk_mul_f32 v[58:59], v[188:189], v[58:59] op_sel:[1,0]
	v_pk_mul_f32 v[64:65], v[188:189], v[64:65] op_sel:[1,0]
	v_pk_mul_f32 v[62:63], v[188:189], v[62:63] op_sel:[1,0]
	v_pk_mul_f32 v[58:59], v[70:71], v[58:59]
	v_pk_mul_f32 v[60:61], v[72:73], v[60:61]
	v_pk_mul_f32 v[62:63], v[66:67], v[62:63]
	v_pk_mul_f32 v[64:65], v[68:69], v[64:65]
	v_pk_mul_f32 v[50:51], v[50:51], v[106:107]
	v_pk_mul_f32 v[52:53], v[52:53], v[108:109]
	v_pk_mul_f32 v[56:57], v[56:57], v[60:61]
	v_pk_mul_f32 v[54:55], v[54:55], v[58:59]
	v_pk_mul_f32 v[58:59], v[52:53], v[64:65]
	v_pk_mul_f32 v[52:53], v[50:51], v[62:63]
	v_mul_f32_e32 v60, 0xbfb8aa3b, v46
	v_mul_f32_e32 v61, 0xbfb8aa3b, v47
	v_mul_f32_e32 v62, 0xbfb8aa3b, v48
	v_mul_f32_e32 v63, 0xbfb8aa3b, v49
	v_exp_f32_e32 v60, v60
	v_exp_f32_e32 v61, v61
	v_exp_f32_e32 v62, v62
	v_exp_f32_e32 v63, v63
	v_add_f32_e32 v60, 1.0, v60
	v_add_f32_e32 v61, 1.0, v61
	v_add_f32_e32 v62, 1.0, v62
	v_add_f32_e32 v63, 1.0, v63
	v_rcp_f32_e32 v60, v60
	v_rcp_f32_e32 v61, v61
	v_rcp_f32_e32 v62, v62
	v_rcp_f32_e32 v63, v63
	v_cvt_pk_bf16_f32 v52, v52, v53
	v_pk_mul_f32 v[46:47], v[46:47], v[60:61]
	v_mul_f32_e32 v60, 0xbfb8aa3b, v42
	v_pk_mul_f32 v[48:49], v[48:49], v[62:63]
	v_mul_f32_e32 v61, 0xbfb8aa3b, v43
	v_mul_f32_e32 v62, 0xbfb8aa3b, v44
	v_mul_f32_e32 v63, 0xbfb8aa3b, v45
	v_exp_f32_e32 v60, v60
	v_exp_f32_e32 v61, v61
	v_exp_f32_e32 v62, v62
	v_exp_f32_e32 v63, v63
; __device__ __forceinline__ unsigned cvt_pk_bf16(float lo, float hi) { unsigned r; asm("v_cvt_pk_bf16_f32 %0, %1, %2" : "=v"(r) : "v"(lo), "v"(hi)); return r; }
; __device__ __forceinline__ float bf_lo(unsigned u) { return __uint_as_float(u << 16); }
; __device__ __forceinline__ float bf_hi(unsigned u) { return __uint_as_float(u & 0xffff0000u); }
;     __device__ __forceinline__ void operator()(const AccT& acc, const Unit& u, int wr, int wc, int fr, int fq) const {
;     ...
;             for (int m = 0; m < 4; ++m) { bf16_t* rowp = A2 + (size_t)(row0 + ai * 128 + m * 16) * 2048 + col0;
;                 const float mu = st[ai][m][0], rs = st[ai][m][1];
; #pragma unroll
;                 for (int bj = 0; bj < 2; ++bj) { const f32x4 v0 = acc[ai][bj][m][0], v1 = acc[ai][bj][m][1]; const u32x4 yw = yv[m][bj];
;                     const f32x4 y0 = (f32x4){bf_lo(yw.x), bf_hi(yw.x), bf_lo(yw.y), bf_hi(yw.y)}, y1 = (f32x4){bf_lo(yw.z), bf_hi(yw.z), bf_lo(yw.w), bf_hi(yw.w)};
;                     const f32x4 n0 = (y0 - mu) * rs * gw[bj][0], n1 = (y1 - mu) * rs * gw[bj][1];
;                     const f32x4 s0 = silu4(v0) * n0, s1 = silu4(v1) * n1;
;                     u32x4 w; w.x = cvt_pk_bf16(s0[0], s0[1]); w.y = cvt_pk_bf16(s0[2], s0[3]); w.z = cvt_pk_bf16(s1[0], s1[1]); w.w = cvt_pk_bf16(s1[2], s1[3]);
;                     *(u32x4*)(rowp + bj * 128) = w; } }
	v_add_f32_e32 v60, 1.0, v60
	v_add_f32_e32 v61, 1.0, v61
	v_add_f32_e32 v62, 1.0, v62
	v_add_f32_e32 v63, 1.0, v63
	v_cvt_pk_bf16_f32 v53, v58, v59
	v_rcp_f32_e32 v60, v60
	v_rcp_f32_e32 v61, v61
	v_rcp_f32_e32 v62, v62
	v_rcp_f32_e32 v63, v63
	v_cvt_pk_bf16_f32 v50, v54, v55
	v_cvt_pk_bf16_f32 v51, v56, v57
	global_store_dwordx4 v[118:119], v[50:53], off offset:256
	v_lshlrev_b32_e32 v56, 16, v116
	v_and_b32_e32 v57, 0xffff0000, v116
	v_lshlrev_b32_e32 v52, 16, v114
	v_and_b32_e32 v53, 0xffff0000, v114
	v_lshlrev_b32_e32 v58, 16, v117
	v_and_b32_e32 v59, 0xffff0000, v117
	v_lshlrev_b32_e32 v54, 16, v115
	v_and_b32_e32 v55, 0xffff0000, v115
	v_sub_f32_e32 v53, v53, v186
	v_sub_f32_e32 v52, v52, v186
	v_sub_f32_e32 v57, v57, v186
	v_sub_f32_e32 v56, v56, v186
	v_sub_f32_e32 v59, v59, v186
	v_sub_f32_e32 v58, v58, v186
	v_sub_f32_e32 v55, v55, v186
	v_sub_f32_e32 v54, v54, v186
	v_pk_mul_f32 v[52:53], v[186:187], v[52:53] op_sel:[1,0]
	v_pk_mul_f32 v[58:59], v[186:187], v[58:59] op_sel:[1,0]
	v_pk_mul_f32 v[56:57], v[186:187], v[56:57] op_sel:[1,0]
	v_pk_mul_f32 v[54:55], v[186:187], v[54:55] op_sel:[1,0]
	v_pk_mul_f32 v[52:53], v[86:87], v[52:53]
	v_pk_mul_f32 v[56:57], v[82:83], v[56:57]
	v_pk_mul_f32 v[58:59], v[84:85], v[58:59]
	v_pk_mul_f32 v[42:43], v[42:43], v[60:61]
	v_pk_mul_f32 v[44:45], v[44:45], v[62:63]
	v_pk_mul_f32 v[54:55], v[88:89], v[54:55]
	v_pk_mul_f32 v[46:47], v[46:47], v[52:53]
	v_pk_mul_f32 v[52:53], v[44:45], v[58:59]
	v_pk_mul_f32 v[44:45], v[42:43], v[56:57]
	v_pk_mul_f32 v[48:49], v[48:49], v[54:55]
	v_cvt_pk_bf16_f32 v44, v44, v45
	v_cvt_pk_bf16_f32 v45, v52, v53
	v_mul_f32_e32 v52, 0xbfb8aa3b, v38
	v_mul_f32_e32 v53, 0xbfb8aa3b, v39
	v_mul_f32_e32 v54, 0xbfb8aa3b, v40
	v_mul_f32_e32 v55, 0xbfb8aa3b, v41
	v_exp_f32_e32 v52, v52
	v_exp_f32_e32 v53, v53
	v_exp_f32_e32 v54, v54
	v_exp_f32_e32 v55, v55
	v_add_f32_e32 v52, 1.0, v52
	v_add_f32_e32 v53, 1.0, v53
	v_add_f32_e32 v54, 1.0, v54
	v_add_f32_e32 v55, 1.0, v55
	v_rcp_f32_e32 v52, v52
	v_rcp_f32_e32 v53, v53
	v_rcp_f32_e32 v54, v54
	v_rcp_f32_e32 v55, v55
	v_lshl_add_u64 v[50:51], s[34:35], 0, v[120:121]
	v_pk_mul_f32 v[38:39], v[38:39], v[52:53]
	v_mul_f32_e32 v52, 0xbfb8aa3b, v34
	v_pk_mul_f32 v[40:41], v[40:41], v[54:55]
	v_mul_f32_e32 v53, 0xbfb8aa3b, v35
	v_mul_f32_e32 v54, 0xbfb8aa3b, v36
	v_mul_f32_e32 v55, 0xbfb8aa3b, v37
	v_exp_f32_e32 v52, v52
	v_exp_f32_e32 v53, v53
	v_exp_f32_e32 v54, v54
	v_exp_f32_e32 v55, v55
	v_add_f32_e32 v52, 1.0, v52
	v_add_f32_e32 v53, 1.0, v53
	v_add_f32_e32 v54, 1.0, v54
	v_add_f32_e32 v55, 1.0, v55
	v_lshl_add_u64 v[50:51], v[50:51], 0, v[182:183]
	v_cvt_pk_bf16_f32 v42, v46, v47
	v_cvt_pk_bf16_f32 v43, v48, v49
	v_rcp_f32_e32 v52, v52
	v_rcp_f32_e32 v53, v53
	v_rcp_f32_e32 v54, v54
	v_rcp_f32_e32 v55, v55
	global_store_dwordx4 v[50:51], v[42:45], off
	v_lshlrev_b32_e32 v46, 16, v100
	v_and_b32_e32 v47, 0xffff0000, v100
	v_lshlrev_b32_e32 v42, 16, v98
	v_and_b32_e32 v43, 0xffff0000, v98
	v_lshlrev_b32_e32 v44, 16, v99
	v_and_b32_e32 v45, 0xffff0000, v99
	v_lshlrev_b32_e32 v48, 16, v101
	v_and_b32_e32 v49, 0xffff0000, v101
	v_sub_f32_e32 v43, v43, v186
	v_sub_f32_e32 v42, v42, v186
	v_sub_f32_e32 v45, v45, v186
	v_sub_f32_e32 v44, v44, v186
	v_sub_f32_e32 v47, v47, v186
	v_sub_f32_e32 v46, v46, v186
	v_sub_f32_e32 v49, v49, v186
	v_sub_f32_e32 v48, v48, v186
	v_pk_mul_f32 v[44:45], v[186:187], v[44:45] op_sel:[1,0]
	v_pk_mul_f32 v[42:43], v[186:187], v[42:43] op_sel:[1,0]
	v_pk_mul_f32 v[48:49], v[186:187], v[48:49] op_sel:[1,0]
	v_pk_mul_f32 v[46:47], v[186:187], v[46:47] op_sel:[1,0]
	v_pk_mul_f32 v[42:43], v[70:71], v[42:43]
	v_pk_mul_f32 v[44:45], v[72:73], v[44:45]
	v_pk_mul_f32 v[46:47], v[66:67], v[46:47]
	v_pk_mul_f32 v[48:49], v[68:69], v[48:49]
	v_pk_mul_f32 v[34:35], v[34:35], v[52:53]
	v_pk_mul_f32 v[36:37], v[36:37], v[54:55]
	v_pk_mul_f32 v[40:41], v[40:41], v[44:45]
	v_pk_mul_f32 v[38:39], v[38:39], v[42:43]
	v_pk_mul_f32 v[42:43], v[36:37], v[48:49]
	v_pk_mul_f32 v[36:37], v[34:35], v[46:47]
	v_mul_f32_e32 v44, 0xbfb8aa3b, v30
	v_mul_f32_e32 v45, 0xbfb8aa3b, v31
	v_mul_f32_e32 v46, 0xbfb8aa3b, v32
	v_mul_f32_e32 v47, 0xbfb8aa3b, v33
	v_exp_f32_e32 v44, v44
	v_exp_f32_e32 v45, v45
	v_exp_f32_e32 v46, v46
	v_exp_f32_e32 v47, v47
	v_add_f32_e32 v44, 1.0, v44
	v_add_f32_e32 v45, 1.0, v45
	v_add_f32_e32 v46, 1.0, v46
	v_add_f32_e32 v47, 1.0, v47
	v_rcp_f32_e32 v44, v44
	v_rcp_f32_e32 v45, v45
	v_rcp_f32_e32 v46, v46
	v_rcp_f32_e32 v47, v47
	v_cvt_pk_bf16_f32 v36, v36, v37
	v_pk_mul_f32 v[30:31], v[30:31], v[44:45]
	v_mul_f32_e32 v44, 0xbfb8aa3b, v26
	v_pk_mul_f32 v[32:33], v[32:33], v[46:47]
	v_mul_f32_e32 v45, 0xbfb8aa3b, v27
	v_mul_f32_e32 v46, 0xbfb8aa3b, v28
	v_mul_f32_e32 v47, 0xbfb8aa3b, v29
	v_exp_f32_e32 v44, v44
	v_exp_f32_e32 v45, v45
	v_exp_f32_e32 v46, v46
	v_exp_f32_e32 v47, v47
	v_add_f32_e32 v44, 1.0, v44
	v_add_f32_e32 v45, 1.0, v45
	v_add_f32_e32 v46, 1.0, v46
	v_add_f32_e32 v47, 1.0, v47
	v_cvt_pk_bf16_f32 v37, v42, v43
	v_rcp_f32_e32 v44, v44
	v_rcp_f32_e32 v45, v45
	v_rcp_f32_e32 v46, v46
	v_rcp_f32_e32 v47, v47
	v_cvt_pk_bf16_f32 v34, v38, v39
	v_cvt_pk_bf16_f32 v35, v40, v41
	global_store_dwordx4 v[50:51], v[34:37], off offset:256
	v_lshlrev_b32_e32 v40, 16, v96
	v_and_b32_e32 v41, 0xffff0000, v96
	v_lshlrev_b32_e32 v36, 16, v94
	v_and_b32_e32 v37, 0xffff0000, v94
	v_lshlrev_b32_e32 v42, 16, v97
	v_and_b32_e32 v43, 0xffff0000, v97
	v_lshlrev_b32_e32 v38, 16, v95
	v_and_b32_e32 v39, 0xffff0000, v95
	v_sub_f32_e32 v37, v37, v184
	v_sub_f32_e32 v36, v36, v184
	v_sub_f32_e32 v41, v41, v184
	v_sub_f32_e32 v40, v40, v184
	v_sub_f32_e32 v43, v43, v184
	v_sub_f32_e32 v42, v42, v184
; __device__ __forceinline__ unsigned cvt_pk_bf16(float lo, float hi) { unsigned r; asm("v_cvt_pk_bf16_f32 %0, %1, %2" : "=v"(r) : "v"(lo), "v"(hi)); return r; }
; __device__ __forceinline__ float bf_lo(unsigned u) { return __uint_as_float(u << 16); }
; __device__ __forceinline__ float bf_hi(unsigned u) { return __uint_as_float(u & 0xffff0000u); }
;     __device__ __forceinline__ void operator()(const AccT& acc, const Unit& u, int wr, int wc, int fr, int fq) const {
;     ...
;             for (int m = 0; m < 4; ++m) { bf16_t* rowp = A2 + (size_t)(row0 + ai * 128 + m * 16) * 2048 + col0;
;                 const float mu = st[ai][m][0], rs = st[ai][m][1];
; #pragma unroll
;                 for (int bj = 0; bj < 2; ++bj) { const f32x4 v0 = acc[ai][bj][m][0], v1 = acc[ai][bj][m][1]; const u32x4 yw = yv[m][bj];
;                     const f32x4 y0 = (f32x4){bf_lo(yw.x), bf_hi(yw.x), bf_lo(yw.y), bf_hi(yw.y)}, y1 = (f32x4){bf_lo(yw.z), bf_hi(yw.z), bf_lo(yw.w), bf_hi(yw.w)};
;                     const f32x4 n0 = (y0 - mu) * rs * gw[bj][0], n1 = (y1 - mu) * rs * gw[bj][1];
;                     const f32x4 s0 = silu4(v0) * n0, s1 = silu4(v1) * n1;
;                     u32x4 w; w.x = cvt_pk_bf16(s0[0], s0[1]); w.y = cvt_pk_bf16(s0[2], s0[3]); w.z = cvt_pk_bf16(s1[0], s1[1]); w.w = cvt_pk_bf16(s1[2], s1[3]);
;                     *(u32x4*)(rowp + bj * 128) = w; } }
	v_sub_f32_e32 v39, v39, v184
	v_sub_f32_e32 v38, v38, v184
	v_pk_mul_f32 v[36:37], v[184:185], v[36:37] op_sel:[1,0]
	v_pk_mul_f32 v[42:43], v[184:185], v[42:43] op_sel:[1,0]
	v_pk_mul_f32 v[40:41], v[184:185], v[40:41] op_sel:[1,0]
	v_pk_mul_f32 v[38:39], v[184:185], v[38:39] op_sel:[1,0]
	v_pk_mul_f32 v[36:37], v[86:87], v[36:37]
	v_pk_mul_f32 v[40:41], v[82:83], v[40:41]
	v_pk_mul_f32 v[42:43], v[84:85], v[42:43]
	v_pk_mul_f32 v[26:27], v[26:27], v[44:45]
	v_pk_mul_f32 v[28:29], v[28:29], v[46:47]
	v_pk_mul_f32 v[38:39], v[88:89], v[38:39]
	v_pk_mul_f32 v[30:31], v[30:31], v[36:37]
	v_pk_mul_f32 v[36:37], v[28:29], v[42:43]
	v_pk_mul_f32 v[28:29], v[26:27], v[40:41]
	v_pk_mul_f32 v[32:33], v[32:33], v[38:39]
	v_cvt_pk_bf16_f32 v28, v28, v29
	v_cvt_pk_bf16_f32 v29, v36, v37
	v_mul_f32_e32 v36, 0xbfb8aa3b, v22
	v_mul_f32_e32 v37, 0xbfb8aa3b, v23
	v_mul_f32_e32 v38, 0xbfb8aa3b, v24
	v_mul_f32_e32 v39, 0xbfb8aa3b, v25
	v_exp_f32_e32 v36, v36
	v_exp_f32_e32 v37, v37
	v_exp_f32_e32 v38, v38
	v_exp_f32_e32 v39, v39
	v_add_f32_e32 v36, 1.0, v36
	v_add_f32_e32 v37, 1.0, v37
	v_add_f32_e32 v38, 1.0, v38
	v_add_f32_e32 v39, 1.0, v39
	v_rcp_f32_e32 v36, v36
	v_rcp_f32_e32 v37, v37
	v_rcp_f32_e32 v38, v38
	v_rcp_f32_e32 v39, v39
	v_lshl_add_u64 v[34:35], s[34:35], 0, v[104:105]
	v_pk_mul_f32 v[22:23], v[22:23], v[36:37]
	v_mul_f32_e32 v36, 0xbfb8aa3b, v18
	v_pk_mul_f32 v[24:25], v[24:25], v[38:39]
	v_mul_f32_e32 v37, 0xbfb8aa3b, v19
	v_mul_f32_e32 v38, 0xbfb8aa3b, v20
	v_mul_f32_e32 v39, 0xbfb8aa3b, v21
	v_exp_f32_e32 v36, v36
	v_exp_f32_e32 v37, v37
	v_exp_f32_e32 v38, v38
	v_exp_f32_e32 v39, v39
	v_add_f32_e32 v36, 1.0, v36
	v_add_f32_e32 v37, 1.0, v37
	v_add_f32_e32 v38, 1.0, v38
	v_add_f32_e32 v39, 1.0, v39
	v_lshl_add_u64 v[34:35], v[34:35], 0, v[182:183]
	v_cvt_pk_bf16_f32 v26, v30, v31
	v_cvt_pk_bf16_f32 v27, v32, v33
	v_rcp_f32_e32 v36, v36
	v_rcp_f32_e32 v37, v37
	v_rcp_f32_e32 v38, v38
	v_rcp_f32_e32 v39, v39
	global_store_dwordx4 v[34:35], v[26:29], off
	v_lshlrev_b32_e32 v30, 16, v92
	v_and_b32_e32 v31, 0xffff0000, v92
	v_lshlrev_b32_e32 v26, 16, v90
	v_and_b32_e32 v27, 0xffff0000, v90
	v_lshlrev_b32_e32 v28, 16, v91
	v_and_b32_e32 v29, 0xffff0000, v91
	v_lshlrev_b32_e32 v32, 16, v93
	v_and_b32_e32 v33, 0xffff0000, v93
	v_sub_f32_e32 v27, v27, v184
	v_sub_f32_e32 v26, v26, v184
	v_sub_f32_e32 v29, v29, v184
	v_sub_f32_e32 v28, v28, v184
	v_sub_f32_e32 v31, v31, v184
	v_sub_f32_e32 v30, v30, v184
	v_sub_f32_e32 v33, v33, v184
	v_sub_f32_e32 v32, v32, v184
	v_pk_mul_f32 v[28:29], v[184:185], v[28:29] op_sel:[1,0]
	v_pk_mul_f32 v[26:27], v[184:185], v[26:27] op_sel:[1,0]
	v_pk_mul_f32 v[32:33], v[184:185], v[32:33] op_sel:[1,0]
	v_pk_mul_f32 v[30:31], v[184:185], v[30:31] op_sel:[1,0]
	v_pk_mul_f32 v[26:27], v[70:71], v[26:27]
	v_pk_mul_f32 v[28:29], v[72:73], v[28:29]
	v_pk_mul_f32 v[30:31], v[66:67], v[30:31]
	v_pk_mul_f32 v[32:33], v[68:69], v[32:33]
	v_pk_mul_f32 v[18:19], v[18:19], v[36:37]
	v_pk_mul_f32 v[20:21], v[20:21], v[38:39]
	v_pk_mul_f32 v[24:25], v[24:25], v[28:29]
	v_pk_mul_f32 v[22:23], v[22:23], v[26:27]
	v_pk_mul_f32 v[26:27], v[20:21], v[32:33]
	v_pk_mul_f32 v[20:21], v[18:19], v[30:31]
	v_mul_f32_e32 v28, 0xbfb8aa3b, v14
	v_mul_f32_e32 v29, 0xbfb8aa3b, v15
	v_mul_f32_e32 v30, 0xbfb8aa3b, v16
	v_mul_f32_e32 v31, 0xbfb8aa3b, v17
	v_exp_f32_e32 v28, v28
	v_exp_f32_e32 v29, v29
	v_exp_f32_e32 v30, v30
	v_exp_f32_e32 v31, v31
	v_add_f32_e32 v28, 1.0, v28
	v_add_f32_e32 v29, 1.0, v29
	v_add_f32_e32 v30, 1.0, v30
	v_add_f32_e32 v31, 1.0, v31
	v_rcp_f32_e32 v28, v28
	v_rcp_f32_e32 v29, v29
	v_rcp_f32_e32 v30, v30
	v_rcp_f32_e32 v31, v31
	v_cvt_pk_bf16_f32 v20, v20, v21
	v_pk_mul_f32 v[14:15], v[14:15], v[28:29]
	v_mul_f32_e32 v28, 0xbfb8aa3b, v10
	v_pk_mul_f32 v[16:17], v[16:17], v[30:31]
	v_mul_f32_e32 v29, 0xbfb8aa3b, v11
	v_mul_f32_e32 v30, 0xbfb8aa3b, v12
	v_mul_f32_e32 v31, 0xbfb8aa3b, v13
	v_exp_f32_e32 v28, v28
	v_exp_f32_e32 v29, v29
	v_exp_f32_e32 v30, v30
	v_exp_f32_e32 v31, v31
	v_add_f32_e32 v28, 1.0, v28
	v_add_f32_e32 v29, 1.0, v29
	v_add_f32_e32 v30, 1.0, v30
	v_add_f32_e32 v31, 1.0, v31
	v_cvt_pk_bf16_f32 v21, v26, v27
	v_rcp_f32_e32 v28, v28
	v_rcp_f32_e32 v29, v29
; __device__ __forceinline__ unsigned cvt_pk_bf16(float lo, float hi) { unsigned r; asm("v_cvt_pk_bf16_f32 %0, %1, %2" : "=v"(r) : "v"(lo), "v"(hi)); return r; }
; __device__ __forceinline__ float bf_lo(unsigned u) { return __uint_as_float(u << 16); }
; __device__ __forceinline__ float bf_hi(unsigned u) { return __uint_as_float(u & 0xffff0000u); }
; #define PG8_WAIT_V(n) asm volatile("s_waitcnt vmcnt(" #n ")" ::: "memory")
; #define PG8_BAR __builtin_amdgcn_s_barrier()
; template <class Epi>
; __device__ __forceinline__ void gemm_phase(LAS unsigned char* lds, const Gemm g, const Epi& E) {
;     ...
;     PG8_WAIT_V(0);
;     if (wr == 0) PG8_BAR;
;     PG8_BAR;
;     __device__ __forceinline__ void operator()(const AccT& acc, const Unit& u, int wr, int wc, int fr, int fq) const {
;     ...
;             for (int m = 0; m < 4; ++m) { bf16_t* rowp = A2 + (size_t)(row0 + ai * 128 + m * 16) * 2048 + col0;
;                 const float mu = st[ai][m][0], rs = st[ai][m][1];
; #pragma unroll
;                 for (int bj = 0; bj < 2; ++bj) { const f32x4 v0 = acc[ai][bj][m][0], v1 = acc[ai][bj][m][1]; const u32x4 yw = yv[m][bj];
;                     const f32x4 y0 = (f32x4){bf_lo(yw.x), bf_hi(yw.x), bf_lo(yw.y), bf_hi(yw.y)}, y1 = (f32x4){bf_lo(yw.z), bf_hi(yw.z), bf_lo(yw.w), bf_hi(yw.w)};
;                     const f32x4 n0 = (y0 - mu) * rs * gw[bj][0], n1 = (y1 - mu) * rs * gw[bj][1];
;                     const f32x4 s0 = silu4(v0) * n0, s1 = silu4(v1) * n1;
;                     u32x4 w; w.x = cvt_pk_bf16(s0[0], s0[1]); w.y = cvt_pk_bf16(s0[2], s0[3]); w.z = cvt_pk_bf16(s1[0], s1[1]); w.w = cvt_pk_bf16(s1[2], s1[3]);
;                     *(u32x4*)(rowp + bj * 128) = w; } }
	v_rcp_f32_e32 v30, v30
	v_rcp_f32_e32 v31, v31
	v_cvt_pk_bf16_f32 v18, v22, v23
	v_cvt_pk_bf16_f32 v19, v24, v25
	global_store_dwordx4 v[34:35], v[18:21], off offset:256
	v_lshlrev_b32_e32 v24, 16, v80
	v_and_b32_e32 v25, 0xffff0000, v80
	v_lshlrev_b32_e32 v20, 16, v78
	v_and_b32_e32 v21, 0xffff0000, v78
	v_lshlrev_b32_e32 v26, 16, v81
	v_and_b32_e32 v27, 0xffff0000, v81
	v_lshlrev_b32_e32 v22, 16, v79
	v_and_b32_e32 v23, 0xffff0000, v79
	v_sub_f32_e32 v21, v21, v180
	v_sub_f32_e32 v20, v20, v180
	v_sub_f32_e32 v25, v25, v180
	v_sub_f32_e32 v24, v24, v180
	v_sub_f32_e32 v27, v27, v180
	v_sub_f32_e32 v26, v26, v180
	v_sub_f32_e32 v23, v23, v180
	v_sub_f32_e32 v22, v22, v180
	v_pk_mul_f32 v[20:21], v[180:181], v[20:21] op_sel:[1,0]
	v_pk_mul_f32 v[26:27], v[180:181], v[26:27] op_sel:[1,0]
	v_pk_mul_f32 v[24:25], v[180:181], v[24:25] op_sel:[1,0]
	v_pk_mul_f32 v[22:23], v[180:181], v[22:23] op_sel:[1,0]
	v_pk_mul_f32 v[20:21], v[86:87], v[20:21]
	v_pk_mul_f32 v[24:25], v[82:83], v[24:25]
	v_pk_mul_f32 v[26:27], v[84:85], v[26:27]
	v_pk_mul_f32 v[10:11], v[10:11], v[28:29]
	v_pk_mul_f32 v[12:13], v[12:13], v[30:31]
	v_pk_mul_f32 v[22:23], v[88:89], v[22:23]
	v_pk_mul_f32 v[14:15], v[14:15], v[20:21]
	v_pk_mul_f32 v[20:21], v[12:13], v[26:27]
	v_pk_mul_f32 v[12:13], v[10:11], v[24:25]
	v_pk_mul_f32 v[16:17], v[16:17], v[22:23]
	v_cvt_pk_bf16_f32 v12, v12, v13
	v_cvt_pk_bf16_f32 v13, v20, v21
	v_mul_f32_e32 v20, 0xbfb8aa3b, v6
	v_mul_f32_e32 v21, 0xbfb8aa3b, v7
	v_mul_f32_e32 v22, 0xbfb8aa3b, v8
	v_mul_f32_e32 v23, 0xbfb8aa3b, v9
	v_exp_f32_e32 v20, v20
	v_exp_f32_e32 v21, v21
	v_exp_f32_e32 v22, v22
	v_exp_f32_e32 v23, v23
	v_add_f32_e32 v20, 1.0, v20
	v_add_f32_e32 v21, 1.0, v21
	v_add_f32_e32 v22, 1.0, v22
	v_add_f32_e32 v23, 1.0, v23
	v_rcp_f32_e32 v20, v20
	v_rcp_f32_e32 v21, v21
	v_rcp_f32_e32 v22, v22
	v_rcp_f32_e32 v23, v23
	v_lshl_add_u64 v[18:19], s[34:35], 0, v[102:103]
	v_pk_mul_f32 v[6:7], v[6:7], v[20:21]
	v_mul_f32_e32 v20, 0xbfb8aa3b, v2
	v_pk_mul_f32 v[8:9], v[8:9], v[22:23]
	v_mul_f32_e32 v21, 0xbfb8aa3b, v3
	v_mul_f32_e32 v22, 0xbfb8aa3b, v4
	v_mul_f32_e32 v23, 0xbfb8aa3b, v5
	v_exp_f32_e32 v20, v20
	v_exp_f32_e32 v21, v21
	v_exp_f32_e32 v22, v22
	v_exp_f32_e32 v23, v23
	v_add_f32_e32 v20, 1.0, v20
	v_add_f32_e32 v21, 1.0, v21
	v_add_f32_e32 v22, 1.0, v22
	v_add_f32_e32 v23, 1.0, v23
	v_lshl_add_u64 v[18:19], v[18:19], 0, v[182:183]
	v_cvt_pk_bf16_f32 v10, v14, v15
	v_cvt_pk_bf16_f32 v11, v16, v17
	v_rcp_f32_e32 v20, v20
	v_rcp_f32_e32 v21, v21
	v_rcp_f32_e32 v22, v22
	v_rcp_f32_e32 v23, v23
	global_store_dwordx4 v[18:19], v[10:13], off
	v_lshlrev_b32_e32 v14, 16, v76
	v_and_b32_e32 v15, 0xffff0000, v76
	v_lshlrev_b32_e32 v10, 16, v74
	v_and_b32_e32 v11, 0xffff0000, v74
	v_lshlrev_b32_e32 v16, 16, v77
	v_and_b32_e32 v17, 0xffff0000, v77
	v_lshlrev_b32_e32 v12, 16, v75
	v_and_b32_e32 v13, 0xffff0000, v75
	v_sub_f32_e32 v11, v11, v180
	v_sub_f32_e32 v10, v10, v180
	v_sub_f32_e32 v15, v15, v180
	v_sub_f32_e32 v14, v14, v180
	v_sub_f32_e32 v17, v17, v180
	v_sub_f32_e32 v16, v16, v180
	v_sub_f32_e32 v13, v13, v180
	v_sub_f32_e32 v12, v12, v180
	v_pk_mul_f32 v[10:11], v[180:181], v[10:11] op_sel:[1,0]
	v_pk_mul_f32 v[16:17], v[180:181], v[16:17] op_sel:[1,0]
	v_pk_mul_f32 v[14:15], v[180:181], v[14:15] op_sel:[1,0]
	v_pk_mul_f32 v[12:13], v[180:181], v[12:13] op_sel:[1,0]
	v_pk_mul_f32 v[10:11], v[70:71], v[10:11]
	v_pk_mul_f32 v[14:15], v[66:67], v[14:15]
	v_pk_mul_f32 v[16:17], v[68:69], v[16:17]
	v_pk_mul_f32 v[2:3], v[2:3], v[20:21]
	v_pk_mul_f32 v[4:5], v[4:5], v[22:23]
	v_pk_mul_f32 v[12:13], v[72:73], v[12:13]
	v_pk_mul_f32 v[6:7], v[6:7], v[10:11]
	v_pk_mul_f32 v[10:11], v[4:5], v[16:17]
	v_pk_mul_f32 v[4:5], v[2:3], v[14:15]
	v_pk_mul_f32 v[8:9], v[8:9], v[12:13]
	v_cvt_pk_bf16_f32 v2, v6, v7
	v_cvt_pk_bf16_f32 v4, v4, v5
	v_cvt_pk_bf16_f32 v5, v10, v11
	s_nop 0
	v_cvt_pk_bf16_f32 v3, v8, v9
	global_store_dwordx4 v[18:19], v[2:5], off offset:256
	s_and_b64 vcc, exec, s[2:3]
	s_mov_b32 s12, s8
	s_mov_b32 s52, s64
	s_mov_b64 s[16:17], s[4:5]
	s_mov_b64 s[14:15], s[10:11]
	s_cbranch_vccz .LBB0_470
	s_waitcnt vmcnt(0)
	s_cmpk_gt_u32 s1, 0xff
	s_cbranch_scc1 .LBB0_479
	s_barrier

; #define PG8_STAGE(bufoff, gbase, voff) do { _Pragma("unroll") for (int _i = 0; _i < 2; ++_i) \
;         __builtin_amdgcn_global_load_lds((const unsigned*)((const char*)(gbase) + (voff)[_i]), (LAS unsigned*)(lds + (bufoff) + ldsw + _i * 8192), 16, 0, 0); } while (0)
; #define PG8_LDA(dst, b, h) do { _Pragma("unroll") for (int m = 0; m < 4; ++m) _Pragma("unroll") for (int k = 0; k < 2; ++k) dst[m][k] = *(const LAS bf16x8*)(lds + PG8_SA(b, h) + aoff + m * 2048 + k * 1024); } while (0)
; #define PG8_LDB(dst, b, h) do { _Pragma("unroll") for (int n = 0; n < 2; ++n) _Pragma("unroll") for (int k = 0; k < 2; ++k) dst[n][k] = *(const LAS bf16x8*)(lds + PG8_SB(b, h) + boff + n * 2048 + k * 1024); } while (0)
; #define PG8_MMA(ai, bj, At, Bt) do { __builtin_amdgcn_s_setprio(1); _Pragma("unroll") for (int m = 0; m < 4; ++m) _Pragma("unroll") for (int n = 0; n < 2; ++n) _Pragma("unroll") for (int k = 0; k < 2; ++k) \
;         acc[ai][bj][m][n] = __builtin_amdgcn_mfma_f32_16x16x32_bf16(Bt[n][k], At[m][k], acc[ai][bj][m][n], 0, 0, 0); __builtin_amdgcn_s_setprio(0); } while (0)
; #define PG8_WAIT_L(n) asm volatile("s_waitcnt lgkmcnt(" #n ")" ::: "memory")
; #define PG8_BAR __builtin_amdgcn_s_barrier()
; #define PG8_SCHED __builtin_amdgcn_sched_barrier(0)
; template <class Epi>
; __device__ __forceinline__ void gemm_phase(LAS unsigned char* lds, const Gemm g, const Epi& E) {
;     ...
;             PG8_LDB(B0, 0, 0); PG8_SCHED; PG8_LDA(At, 0, 0); PG8_STAGE(PG8_SA(1, 1), a1 + hstepA, voffA);
;             PG8_WAIT_L(8); PG8_BAR; PG8_WAIT_L(0); PG8_MMA(0, 0, At, B0); PG8_BAR; PG8_SCHED;
;     ...
;         for (int a = 0; a < 2; ++a)
; #pragma unroll
;             for (int b = 0; b < 2; ++b)
; #pragma unroll
;                 for (int m = 0; m < 4; ++m)
; #pragma unroll
;                     for (int n = 0; n < 2; ++n) acc[a][b][m][n] = (f32x4){0.f, 0.f, 0.f, 0.f};
.LBB0_494:
	s_ashr_i32 s7, s6, 31
	s_lshl_b64 s[16:17], s[6:7], 20
	s_add_u32 s7, s18, s16
	s_addc_u32 s16, s24, s17
	s_and_b64 s[4:5], s[4:5], exec
	s_cselect_b32 s5, s16, s15
	s_cselect_b32 s4, s7, s14
	s_add_u32 s12, s12, 0x80080
	s_addc_u32 s13, s13, 0
	s_add_u32 s7, s14, 0x100
	v_mov_b32_e32 v2, 0
	s_addc_u32 s64, s15, 0
	s_mov_b32 s65, -2
	v_mov_b32_e32 v3, v2
	v_mov_b64_e32 v[4:5], v[2:3]
	v_mov_b64_e32 v[6:7], v[2:3]
	v_mov_b64_e32 v[8:9], v[2:3]
	v_mov_b64_e32 v[10:11], v[2:3]
	v_mov_b64_e32 v[12:13], v[2:3]
	v_mov_b64_e32 v[14:15], v[2:3]
	v_mov_b64_e32 v[16:17], v[2:3]
	v_mov_b64_e32 v[18:19], v[2:3]
	v_mov_b64_e32 v[20:21], v[2:3]
	v_mov_b64_e32 v[22:23], v[2:3]
	v_mov_b64_e32 v[24:25], v[2:3]
	v_mov_b64_e32 v[26:27], v[2:3]
	v_mov_b64_e32 v[28:29], v[2:3]
	v_mov_b64_e32 v[30:31], v[2:3]
	v_mov_b64_e32 v[32:33], v[2:3]
	v_mov_b64_e32 v[34:35], v[2:3]
	v_mov_b64_e32 v[36:37], v[2:3]
	v_mov_b64_e32 v[38:39], v[2:3]
	v_mov_b64_e32 v[40:41], v[2:3]
	v_mov_b64_e32 v[42:43], v[2:3]
	v_mov_b64_e32 v[44:45], v[2:3]
	v_mov_b64_e32 v[46:47], v[2:3]
	v_mov_b64_e32 v[48:49], v[2:3]
	v_mov_b64_e32 v[50:51], v[2:3]
	v_mov_b64_e32 v[52:53], v[2:3]
	v_mov_b64_e32 v[54:55], v[2:3]
	v_mov_b64_e32 v[56:57], v[2:3]
	v_mov_b64_e32 v[58:59], v[2:3]
	v_mov_b64_e32 v[60:61], v[2:3]
	v_mov_b64_e32 v[62:63], v[2:3]
	v_mov_b64_e32 v[64:65], v[2:3]
	v_mov_b64_e32 v[66:67], v[2:3]
	v_mov_b64_e32 v[68:69], v[2:3]
	v_mov_b64_e32 v[70:71], v[2:3]
	v_mov_b64_e32 v[72:73], v[2:3]
	v_mov_b64_e32 v[74:75], v[2:3]
	v_mov_b64_e32 v[76:77], v[2:3]
	v_mov_b64_e32 v[78:79], v[2:3]
	v_mov_b64_e32 v[80:81], v[2:3]
	v_mov_b64_e32 v[82:83], v[2:3]
	v_mov_b64_e32 v[84:85], v[2:3]
	v_mov_b64_e32 v[86:87], v[2:3]
	v_mov_b64_e32 v[88:89], v[2:3]
	v_mov_b64_e32 v[90:91], v[2:3]
	v_mov_b64_e32 v[92:93], v[2:3]
	v_mov_b64_e32 v[94:95], v[2:3]
	v_mov_b64_e32 v[96:97], v[2:3]
	v_mov_b64_e32 v[98:99], v[2:3]
	v_mov_b64_e32 v[100:101], v[2:3]
	v_mov_b64_e32 v[102:103], v[2:3]
	v_mov_b64_e32 v[104:105], v[2:3]
	v_mov_b64_e32 v[106:107], v[2:3]
	v_mov_b64_e32 v[108:109], v[2:3]
	v_mov_b64_e32 v[110:111], v[2:3]
	v_mov_b64_e32 v[112:113], v[2:3]
	v_mov_b64_e32 v[114:115], v[2:3]
	v_mov_b64_e32 v[116:117], v[2:3]
	v_mov_b64_e32 v[118:119], v[2:3]
	v_mov_b64_e32 v[120:121], v[2:3]
	v_mov_b64_e32 v[122:123], v[2:3]
	v_mov_b64_e32 v[124:125], v[2:3]
	v_mov_b64_e32 v[126:127], v[2:3]
	v_mov_b64_e32 v[128:129], v[2:3]
	s_add_i32 s66, 0, 0x10000
	v_add_u32_e32 v142, s66, v159
.LBB0_495:
	ds_read_b128 v[130:133], v142
	ds_read_b128 v[134:137], v142 offset:1024
	ds_read_b128 v[138:141], v142 offset:2048
	ds_read_b128 v[142:145], v142 offset:3072
	ds_read_b128 v[154:157], v160
	ds_read_b128 v[162:165], v160 offset:1024
	ds_read_b128 v[166:169], v160 offset:2048
	ds_read_b128 v[170:173], v160 offset:3072
	ds_read_b128 v[174:177], v160 offset:4096
	ds_read_b128 v[180:183], v160 offset:5120
	ds_read_b128 v[184:187], v160 offset:6144
	ds_read_b128 v[188:191], v160 offset:7168
	s_add_u32 s14, s12, 0xfff80080
	s_addc_u32 s15, s13, -1
	s_cmp_eq_u32 s65, 28
	s_cselect_b32 s17, s9, s15
	s_cselect_b32 s16, s8, s14
	s_cselect_b32 s15, s5, s64
	s_cselect_b32 s14, s4, s7
	v_lshl_add_u64 v[192:193], s[12:13], 0, v[150:151]
	s_add_i32 m0, s11, 0xc000
	s_nop 0
	global_load_lds_dwordx4 v[192:193], off
	v_lshl_add_u64 v[192:193], s[12:13], 0, v[152:153]
	s_add_i32 m0, s11, 0xe000
	s_nop 0
	global_load_lds_dwordx4 v[192:193], off
	s_waitcnt lgkmcnt(8)
	s_barrier
	s_waitcnt lgkmcnt(0)
	v_mfma_f32_16x16x32_bf16 v[126:129], v[130:133], v[154:157], v[126:129]
	v_mfma_f32_16x16x32_bf16 v[122:125], v[138:141], v[154:157], v[122:125]
	v_mfma_f32_16x16x32_bf16 v[114:117], v[130:133], v[166:169], v[114:117]
	v_mfma_f32_16x16x32_bf16 v[106:109], v[138:141], v[166:169], v[106:109]
	v_mfma_f32_16x16x32_bf16 v[102:105], v[130:133], v[174:177], v[102:105]
	v_mfma_f32_16x16x32_bf16 v[90:93], v[138:141], v[174:177], v[90:93]
	v_mfma_f32_16x16x32_bf16 v[86:89], v[130:133], v[184:187], v[86:89]
	v_mfma_f32_16x16x32_bf16 v[74:77], v[138:141], v[184:187], v[74:77]
	v_mfma_f32_16x16x32_bf16 v[126:129], v[134:137], v[162:165], v[126:129]
	v_mfma_f32_16x16x32_bf16 v[122:125], v[142:145], v[162:165], v[122:125]
	v_mfma_f32_16x16x32_bf16 v[114:117], v[134:137], v[170:173], v[114:117]
	v_mfma_f32_16x16x32_bf16 v[106:109], v[142:145], v[170:173], v[106:109]
	v_mfma_f32_16x16x32_bf16 v[102:105], v[134:137], v[180:183], v[102:105]
	v_mfma_f32_16x16x32_bf16 v[90:93], v[142:145], v[180:183], v[90:93]
	v_mfma_f32_16x16x32_bf16 v[86:89], v[134:137], v[188:191], v[86:89]
	v_mfma_f32_16x16x32_bf16 v[74:77], v[142:145], v[188:191], v[74:77]
	s_barrier
	s_add_i32 s68, 0, 0x14000
	s_add_i32 s66, s66, s25
	v_add_u32_e32 v161, s68, v159
	v_lshl_add_u64 v[208:209], s[14:15], 0, v[148:149]
	s_mov_b32 m0, s66
	ds_read_b128 v[192:195], v161
	ds_read_b128 v[196:199], v161 offset:1024
	ds_read_b128 v[200:203], v161 offset:2048
	ds_read_b128 v[204:207], v161 offset:3072
	global_load_lds_dwordx4 v[208:209], off
	v_lshl_add_u64 v[226:227], s[14:15], 0, v[146:147]
	s_add_i32 m0, s66, 0x2000
	s_nop 0
	global_load_lds_dwordx4 v[226:227], off
	s_nop 1
	s_mov_b32 m0, s11
	v_lshl_add_u64 v[228:229], s[16:17], 0, v[148:149]
	s_barrier
; #define PG8_STAGE(bufoff, gbase, voff) do { _Pragma("unroll") for (int _i = 0; _i < 2; ++_i) \
;         __builtin_amdgcn_global_load_lds((const unsigned*)((const char*)(gbase) + (voff)[_i]), (LAS unsigned*)(lds + (bufoff) + ldsw + _i * 8192), 16, 0, 0); } while (0)
; #define PG8_LDA(dst, b, h) do { _Pragma("unroll") for (int m = 0; m < 4; ++m) _Pragma("unroll") for (int k = 0; k < 2; ++k) dst[m][k] = *(const LAS bf16x8*)(lds + PG8_SA(b, h) + aoff + m * 2048 + k * 1024); } while (0)
; #define PG8_LDB(dst, b, h) do { _Pragma("unroll") for (int n = 0; n < 2; ++n) _Pragma("unroll") for (int k = 0; k < 2; ++k) dst[n][k] = *(const LAS bf16x8*)(lds + PG8_SB(b, h) + boff + n * 2048 + k * 1024); } while (0)
; #define PG8_MMA(ai, bj, At, Bt) do { __builtin_amdgcn_s_setprio(1); _Pragma("unroll") for (int m = 0; m < 4; ++m) _Pragma("unroll") for (int n = 0; n < 2; ++n) _Pragma("unroll") for (int k = 0; k < 2; ++k) \
;         acc[ai][bj][m][n] = __builtin_amdgcn_mfma_f32_16x16x32_bf16(Bt[n][k], At[m][k], acc[ai][bj][m][n], 0, 0, 0); __builtin_amdgcn_s_setprio(0); } while (0)
; #define PG8_WAIT_V(n) asm volatile("s_waitcnt vmcnt(" #n ")" ::: "memory")
; #define PG8_WAIT_L(n) asm volatile("s_waitcnt lgkmcnt(" #n ")" ::: "memory")
; #define PG8_BAR __builtin_amdgcn_s_barrier()
; #define PG8_SCHED __builtin_amdgcn_sched_barrier(0)
; template <class Epi>
; __device__ __forceinline__ void gemm_phase(LAS unsigned char* lds, const Gemm g, const Epi& E) {
;     ...
;             PG8_WAIT_L(8); PG8_BAR; PG8_WAIT_L(0); PG8_MMA(0, 0, At, B0); PG8_BAR; PG8_SCHED;
;             PG8_LDB(B1, 0, 1); PG8_STAGE(PG8_SB(0, 0), b2, voffB);
;             PG8_BAR; PG8_WAIT_L(0); PG8_MMA(0, 1, At, B1); PG8_BAR;
;             PG8_LDA(At, 0, 1); PG8_STAGE(PG8_SA(0, 0), a2, voffA);
;             PG8_BAR; PG8_WAIT_L(0); PG8_MMA(1, 0, At, B0); PG8_BAR; PG8_SCHED;
;             PG8_STAGE(PG8_SB(0, 1), b2 + hstepB, voffB);
;             PG8_WAIT_V(6); PG8_BAR; PG8_MMA(1, 1, At, B1); PG8_BAR;
;             PG8_LDB(B0, 1, 0); PG8_SCHED; PG8_LDA(At, 1, 0); PG8_STAGE(PG8_SA(0, 1), a2 + hstepA, voffA);
	s_waitcnt lgkmcnt(0)
	v_mfma_f32_16x16x32_bf16 v[118:121], v[192:195], v[154:157], v[118:121]
	v_mfma_f32_16x16x32_bf16 v[110:113], v[200:203], v[154:157], v[110:113]
	v_mfma_f32_16x16x32_bf16 v[98:101], v[192:195], v[166:169], v[98:101]
	v_mfma_f32_16x16x32_bf16 v[94:97], v[200:203], v[166:169], v[94:97]
	v_mfma_f32_16x16x32_bf16 v[82:85], v[192:195], v[174:177], v[82:85]
	v_mfma_f32_16x16x32_bf16 v[78:81], v[200:203], v[174:177], v[78:81]
	v_mfma_f32_16x16x32_bf16 v[70:73], v[192:195], v[184:187], v[70:73]
	v_mfma_f32_16x16x32_bf16 v[66:69], v[200:203], v[184:187], v[66:69]
	v_mfma_f32_16x16x32_bf16 v[118:121], v[196:199], v[162:165], v[118:121]
	v_mfma_f32_16x16x32_bf16 v[110:113], v[204:207], v[162:165], v[110:113]
	v_mfma_f32_16x16x32_bf16 v[98:101], v[196:199], v[170:173], v[98:101]
	v_mfma_f32_16x16x32_bf16 v[94:97], v[204:207], v[170:173], v[94:97]
	v_mfma_f32_16x16x32_bf16 v[82:85], v[196:199], v[180:183], v[82:85]
	v_mfma_f32_16x16x32_bf16 v[78:81], v[204:207], v[180:183], v[78:81]
	v_mfma_f32_16x16x32_bf16 v[70:73], v[196:199], v[188:191], v[70:73]
	v_mfma_f32_16x16x32_bf16 v[66:69], v[204:207], v[188:191], v[66:69]
	s_barrier
	ds_read_b128 v[154:157], v160 offset:16384
	ds_read_b128 v[162:165], v160 offset:17408
	ds_read_b128 v[166:169], v160 offset:18432
	ds_read_b128 v[170:173], v160 offset:19456
	ds_read_b128 v[174:177], v160 offset:20480
	ds_read_b128 v[180:183], v160 offset:21504
	ds_read_b128 v[184:187], v160 offset:22528
	ds_read_b128 v[188:191], v160 offset:23552
	global_load_lds_dwordx4 v[228:229], off
	v_lshl_add_u64 v[230:231], s[16:17], 0, v[146:147]
	s_mov_b32 m0, s31
	s_nop 0
	global_load_lds_dwordx4 v[230:231], off
	s_barrier
	s_waitcnt lgkmcnt(0)
	v_mfma_f32_16x16x32_bf16 v[62:65], v[130:133], v[154:157], v[62:65]
	v_mfma_f32_16x16x32_bf16 v[58:61], v[138:141], v[154:157], v[58:61]
	v_mfma_f32_16x16x32_bf16 v[54:57], v[130:133], v[166:169], v[54:57]
	v_mfma_f32_16x16x32_bf16 v[42:45], v[138:141], v[166:169], v[42:45]
	v_mfma_f32_16x16x32_bf16 v[38:41], v[130:133], v[174:177], v[38:41]
	v_mfma_f32_16x16x32_bf16 v[26:29], v[138:141], v[174:177], v[26:29]
	v_mfma_f32_16x16x32_bf16 v[22:25], v[130:133], v[184:187], v[22:25]
	v_mfma_f32_16x16x32_bf16 v[10:13], v[138:141], v[184:187], v[10:13]
	v_mfma_f32_16x16x32_bf16 v[62:65], v[134:137], v[162:165], v[62:65]
	v_mfma_f32_16x16x32_bf16 v[58:61], v[142:145], v[162:165], v[58:61]
	v_mfma_f32_16x16x32_bf16 v[54:57], v[134:137], v[170:173], v[54:57]
	v_mfma_f32_16x16x32_bf16 v[42:45], v[142:145], v[170:173], v[42:45]
	v_mfma_f32_16x16x32_bf16 v[38:41], v[134:137], v[180:183], v[38:41]
	v_mfma_f32_16x16x32_bf16 v[26:29], v[142:145], v[180:183], v[26:29]
	v_mfma_f32_16x16x32_bf16 v[22:25], v[134:137], v[188:191], v[22:25]
	v_mfma_f32_16x16x32_bf16 v[10:13], v[142:145], v[188:191], v[10:13]
	s_barrier
	s_add_u32 s66, s14, 0x80000
	s_addc_u32 s67, s15, 0
	s_add_i32 s68, s68, s25
	v_lshl_add_u64 v[130:131], s[66:67], 0, v[148:149]
	s_mov_b32 m0, s68
	s_nop 0
	global_load_lds_dwordx4 v[130:131], off
	v_lshl_add_u64 v[130:131], s[66:67], 0, v[146:147]
	s_add_i32 m0, s68, 0x2000
	s_nop 0
	global_load_lds_dwordx4 v[130:131], off
	s_add_i32 s66, 0, 0x18000
	v_add_u32_e32 v142, s66, v159
	s_waitcnt vmcnt(6)
	s_barrier
	v_mfma_f32_16x16x32_bf16 v[50:53], v[192:195], v[154:157], v[50:53]
	v_mfma_f32_16x16x32_bf16 v[46:49], v[200:203], v[154:157], v[46:49]
	v_mfma_f32_16x16x32_bf16 v[34:37], v[192:195], v[166:169], v[34:37]
	v_mfma_f32_16x16x32_bf16 v[30:33], v[200:203], v[166:169], v[30:33]
	v_mfma_f32_16x16x32_bf16 v[18:21], v[192:195], v[174:177], v[18:21]
	v_mfma_f32_16x16x32_bf16 v[14:17], v[200:203], v[174:177], v[14:17]
	v_mfma_f32_16x16x32_bf16 v[6:9], v[192:195], v[184:187], v[6:9]
	v_mfma_f32_16x16x32_bf16 v[2:5], v[200:203], v[184:187], v[2:5]
	v_mfma_f32_16x16x32_bf16 v[50:53], v[196:199], v[162:165], v[50:53]
	v_mfma_f32_16x16x32_bf16 v[46:49], v[204:207], v[162:165], v[46:49]
	v_mfma_f32_16x16x32_bf16 v[34:37], v[196:199], v[170:173], v[34:37]
	v_mfma_f32_16x16x32_bf16 v[30:33], v[204:207], v[170:173], v[30:33]
	v_mfma_f32_16x16x32_bf16 v[18:21], v[196:199], v[180:183], v[18:21]
	v_mfma_f32_16x16x32_bf16 v[14:17], v[204:207], v[180:183], v[14:17]
	v_mfma_f32_16x16x32_bf16 v[6:9], v[196:199], v[188:191], v[6:9]
	v_mfma_f32_16x16x32_bf16 v[2:5], v[204:207], v[188:191], v[2:5]
	s_barrier
	ds_read_b128 v[130:133], v142
	ds_read_b128 v[134:137], v142 offset:1024
	ds_read_b128 v[138:141], v142 offset:2048
	ds_read_b128 v[142:145], v142 offset:3072
	s_add_u32 s16, s16, 0x80000
	s_addc_u32 s17, s17, 0
	s_mov_b32 m0, s36
	v_lshl_add_u64 v[192:193], s[16:17], 0, v[148:149]
	ds_read_b128 v[154:157], v160 offset:32768
	ds_read_b128 v[162:165], v160 offset:33792
	ds_read_b128 v[166:169], v160 offset:34816
	ds_read_b128 v[170:173], v160 offset:35840
	ds_read_b128 v[174:177], v160 offset:36864
	ds_read_b128 v[180:183], v160 offset:37888
	ds_read_b128 v[184:187], v160 offset:38912
	ds_read_b128 v[188:191], v160 offset:39936
	global_load_lds_dwordx4 v[192:193], off
	v_lshl_add_u64 v[192:193], s[16:17], 0, v[146:147]
	s_mov_b32 m0, s44
	s_nop 0
	global_load_lds_dwordx4 v[192:193], off
	s_waitcnt lgkmcnt(8)
	s_barrier
; #define PG8_STAGE(bufoff, gbase, voff) do { _Pragma("unroll") for (int _i = 0; _i < 2; ++_i) \
;         __builtin_amdgcn_global_load_lds((const unsigned*)((const char*)(gbase) + (voff)[_i]), (LAS unsigned*)(lds + (bufoff) + ldsw + _i * 8192), 16, 0, 0); } while (0)
; #define PG8_LDA(dst, b, h) do { _Pragma("unroll") for (int m = 0; m < 4; ++m) _Pragma("unroll") for (int k = 0; k < 2; ++k) dst[m][k] = *(const LAS bf16x8*)(lds + PG8_SA(b, h) + aoff + m * 2048 + k * 1024); } while (0)
; #define PG8_LDB(dst, b, h) do { _Pragma("unroll") for (int n = 0; n < 2; ++n) _Pragma("unroll") for (int k = 0; k < 2; ++k) dst[n][k] = *(const LAS bf16x8*)(lds + PG8_SB(b, h) + boff + n * 2048 + k * 1024); } while (0)
; #define PG8_MMA(ai, bj, At, Bt) do { __builtin_amdgcn_s_setprio(1); _Pragma("unroll") for (int m = 0; m < 4; ++m) _Pragma("unroll") for (int n = 0; n < 2; ++n) _Pragma("unroll") for (int k = 0; k < 2; ++k) \
;         acc[ai][bj][m][n] = __builtin_amdgcn_mfma_f32_16x16x32_bf16(Bt[n][k], At[m][k], acc[ai][bj][m][n], 0, 0, 0); __builtin_amdgcn_s_setprio(0); } while (0)
; #define PG8_WAIT_V(n) asm volatile("s_waitcnt vmcnt(" #n ")" ::: "memory")
; #define PG8_WAIT_L(n) asm volatile("s_waitcnt lgkmcnt(" #n ")" ::: "memory")
; #define PG8_BAR __builtin_amdgcn_s_barrier()
; #define PG8_SCHED __builtin_amdgcn_sched_barrier(0)
; template <class Epi>
; __device__ __forceinline__ void gemm_phase(LAS unsigned char* lds, const Gemm g, const Epi& E) {
;     ...
;             PG8_WAIT_L(8); PG8_BAR; PG8_WAIT_L(0); PG8_MMA(0, 0, At, B0); PG8_BAR; PG8_SCHED;
;             PG8_LDB(B1, 1, 1); PG8_STAGE(PG8_SB(1, 0), b3, voffB);
;             PG8_BAR; PG8_WAIT_L(0); PG8_MMA(0, 1, At, B1); PG8_BAR;
;             PG8_LDA(At, 1, 1); PG8_STAGE(PG8_SA(1, 0), a3, voffA);
;             PG8_BAR; PG8_WAIT_L(0); PG8_MMA(1, 0, At, B0); PG8_BAR; PG8_SCHED;
;             PG8_STAGE(PG8_SB(1, 1), b3 + hstepB, voffB);
;             PG8_WAIT_V(6); PG8_BAR; PG8_MMA(1, 1, At, B1); PG8_BAR;
	s_waitcnt lgkmcnt(0)
	v_mfma_f32_16x16x32_bf16 v[126:129], v[130:133], v[154:157], v[126:129]
	v_mfma_f32_16x16x32_bf16 v[122:125], v[138:141], v[154:157], v[122:125]
	v_mfma_f32_16x16x32_bf16 v[114:117], v[130:133], v[166:169], v[114:117]
	v_mfma_f32_16x16x32_bf16 v[106:109], v[138:141], v[166:169], v[106:109]
	v_mfma_f32_16x16x32_bf16 v[102:105], v[130:133], v[174:177], v[102:105]
	v_mfma_f32_16x16x32_bf16 v[90:93], v[138:141], v[174:177], v[90:93]
	v_mfma_f32_16x16x32_bf16 v[86:89], v[130:133], v[184:187], v[86:89]
	v_mfma_f32_16x16x32_bf16 v[74:77], v[138:141], v[184:187], v[74:77]
	v_mfma_f32_16x16x32_bf16 v[126:129], v[134:137], v[162:165], v[126:129]
	v_mfma_f32_16x16x32_bf16 v[122:125], v[142:145], v[162:165], v[122:125]
	v_mfma_f32_16x16x32_bf16 v[114:117], v[134:137], v[170:173], v[114:117]
	v_mfma_f32_16x16x32_bf16 v[106:109], v[142:145], v[170:173], v[106:109]
	v_mfma_f32_16x16x32_bf16 v[102:105], v[134:137], v[180:183], v[102:105]
	v_mfma_f32_16x16x32_bf16 v[90:93], v[142:145], v[180:183], v[90:93]
	v_mfma_f32_16x16x32_bf16 v[86:89], v[134:137], v[188:191], v[86:89]
	v_mfma_f32_16x16x32_bf16 v[74:77], v[142:145], v[188:191], v[74:77]
	s_barrier
	s_add_i32 s16, 0, 0x1c000
	s_add_i32 s17, s66, s25
	v_add_u32_e32 v161, s16, v159
	v_lshl_add_u64 v[208:209], v[208:209], 0, s[86:87]
	s_mov_b32 m0, s17
	ds_read_b128 v[192:195], v161
	ds_read_b128 v[196:199], v161 offset:1024
	ds_read_b128 v[200:203], v161 offset:2048
	ds_read_b128 v[204:207], v161 offset:3072
	global_load_lds_dwordx4 v[208:209], off
	v_lshl_add_u64 v[208:209], v[226:227], 0, s[86:87]
	s_add_i32 m0, s17, 0x2000
	s_nop 0
	global_load_lds_dwordx4 v[208:209], off
	s_nop 1
	s_mov_b32 m0, s53
	v_lshl_add_u64 v[208:209], v[228:229], 0, s[86:87]
	s_barrier
	s_waitcnt lgkmcnt(0)
	v_mfma_f32_16x16x32_bf16 v[118:121], v[192:195], v[154:157], v[118:121]
	v_mfma_f32_16x16x32_bf16 v[110:113], v[200:203], v[154:157], v[110:113]
	v_mfma_f32_16x16x32_bf16 v[98:101], v[192:195], v[166:169], v[98:101]
	v_mfma_f32_16x16x32_bf16 v[94:97], v[200:203], v[166:169], v[94:97]
	v_mfma_f32_16x16x32_bf16 v[82:85], v[192:195], v[174:177], v[82:85]
	v_mfma_f32_16x16x32_bf16 v[78:81], v[200:203], v[174:177], v[78:81]
	v_mfma_f32_16x16x32_bf16 v[70:73], v[192:195], v[184:187], v[70:73]
	v_mfma_f32_16x16x32_bf16 v[66:69], v[200:203], v[184:187], v[66:69]
	v_mfma_f32_16x16x32_bf16 v[118:121], v[196:199], v[162:165], v[118:121]
	v_mfma_f32_16x16x32_bf16 v[110:113], v[204:207], v[162:165], v[110:113]
	v_mfma_f32_16x16x32_bf16 v[98:101], v[196:199], v[170:173], v[98:101]
	v_mfma_f32_16x16x32_bf16 v[94:97], v[204:207], v[170:173], v[94:97]
	v_mfma_f32_16x16x32_bf16 v[82:85], v[196:199], v[180:183], v[82:85]
	v_mfma_f32_16x16x32_bf16 v[78:81], v[204:207], v[180:183], v[78:81]
	v_mfma_f32_16x16x32_bf16 v[70:73], v[196:199], v[188:191], v[70:73]
	v_mfma_f32_16x16x32_bf16 v[66:69], v[204:207], v[188:191], v[66:69]
	s_barrier
	ds_read_b128 v[154:157], v160 offset:49152
	ds_read_b128 v[162:165], v160 offset:50176
	ds_read_b128 v[166:169], v160 offset:51200
	ds_read_b128 v[170:173], v160 offset:52224
	ds_read_b128 v[174:177], v160 offset:53248
	ds_read_b128 v[180:183], v160 offset:54272
	ds_read_b128 v[184:187], v160 offset:55296
	ds_read_b128 v[188:191], v160 offset:56320
	global_load_lds_dwordx4 v[208:209], off
	v_lshl_add_u64 v[208:209], v[230:231], 0, s[86:87]
	s_mov_b32 m0, s58
	s_nop 0
	global_load_lds_dwordx4 v[208:209], off
	s_barrier
	s_waitcnt lgkmcnt(0)
	v_mfma_f32_16x16x32_bf16 v[62:65], v[130:133], v[154:157], v[62:65]
	v_mfma_f32_16x16x32_bf16 v[58:61], v[138:141], v[154:157], v[58:61]
	v_mfma_f32_16x16x32_bf16 v[54:57], v[130:133], v[166:169], v[54:57]
	v_mfma_f32_16x16x32_bf16 v[42:45], v[138:141], v[166:169], v[42:45]
	v_mfma_f32_16x16x32_bf16 v[38:41], v[130:133], v[174:177], v[38:41]
	v_mfma_f32_16x16x32_bf16 v[26:29], v[138:141], v[174:177], v[26:29]
	v_mfma_f32_16x16x32_bf16 v[22:25], v[130:133], v[184:187], v[22:25]
	v_mfma_f32_16x16x32_bf16 v[10:13], v[138:141], v[184:187], v[10:13]
	v_mfma_f32_16x16x32_bf16 v[62:65], v[134:137], v[162:165], v[62:65]
	v_mfma_f32_16x16x32_bf16 v[58:61], v[142:145], v[162:165], v[58:61]
	v_mfma_f32_16x16x32_bf16 v[54:57], v[134:137], v[170:173], v[54:57]
	v_mfma_f32_16x16x32_bf16 v[42:45], v[142:145], v[170:173], v[42:45]
	v_mfma_f32_16x16x32_bf16 v[38:41], v[134:137], v[180:183], v[38:41]
	v_mfma_f32_16x16x32_bf16 v[26:29], v[142:145], v[180:183], v[26:29]
	v_mfma_f32_16x16x32_bf16 v[22:25], v[134:137], v[188:191], v[22:25]
	v_mfma_f32_16x16x32_bf16 v[10:13], v[142:145], v[188:191], v[10:13]
	s_barrier
	s_add_u32 s14, s14, 0x80080
	s_addc_u32 s15, s15, 0
	s_add_i32 s16, s16, s25
	v_lshl_add_u64 v[130:131], s[14:15], 0, v[148:149]
	s_mov_b32 m0, s16
	s_nop 0
	global_load_lds_dwordx4 v[130:131], off
	v_lshl_add_u64 v[130:131], s[14:15], 0, v[146:147]
	s_add_i32 m0, s16, 0x2000
	s_nop 0
	global_load_lds_dwordx4 v[130:131], off
	s_add_i32 s65, s65, 2
	s_add_u32 s12, s12, 0x100
	s_addc_u32 s13, s13, 0
	s_add_u32 s7, s7, 0x100
	s_addc_u32 s64, s64, 0
	s_add_i32 s66, 0, 0x10000
	v_add_u32_e32 v142, s66, v159
	s_cmp_gt_u32 s65, 29
	s_waitcnt vmcnt(6)
	s_barrier
;     __device__ __forceinline__ void operator()(const AccT& acc, const Unit& u, int wr, int wc, int fr, int fq) const {
;     ...
;         const int gpm = mapA.src(u.pm);
;         const int mb = gpm < 32 ? 32 : (gpm - 32) >> 3;
;         const int row0 = gpm * 256 + wr * 64 + fr, col0 = u.pn * 256 + wc * 32 + 4 * fq;
;         const float* gp = modl + ((size_t)mb * 6 + gi) * 1024;
;         f32x4 gv[2][2];
; #pragma unroll
;         for (int bj = 0; bj < 2; ++bj)
; #pragma unroll
;             for (int n = 0; n < 2; ++n) { gv[bj][n] = *(const f32x4*)(gp + col0 + bj * 128 + n * 16); if (scale) gv[bj][n] = gv[bj][n] * *(const f32x4*)(scale + col0 + bj * 128 + n * 16); }
;         const float* sbase = (gpm < 32 ? Xc : Xl) + (size_t)row0 * 1024 + col0;
; #pragma unroll
;         for (int ai = 0; ai < 2; ++ai) {
;             f32x4 xo[4][2][2];
; #pragma unroll
;             for (int m = 0; m < 4; ++m)
; #pragma unroll
;                 for (int bj = 0; bj < 2; ++bj)
; #pragma unroll
;                     for (int n = 0; n < 2; ++n) xo[m][bj][n] = *(const f32x4*)(sbase + (size_t)(ai * 128 + m * 16) * 1024 + bj * 128 + n * 16);
;             __builtin_amdgcn_sched_barrier(0);
; #pragma unroll
;             for (int m = 0; m < 4; ++m) { float* rowp = X + (size_t)(row0 + ai * 128 + m * 16) * 1024 + col0;
; #pragma unroll
;                 for (int bj = 0; bj < 2; ++bj)
; #pragma unroll
;                     for (int n = 0; n < 2; ++n) *(f32x4*)(rowp + bj * 128 + n * 16) = xo[m][bj][n] + gv[bj][n] * acc[ai][bj][m][n]; }
	v_mfma_f32_16x16x32_bf16 v[50:53], v[192:195], v[154:157], v[50:53]
	v_mfma_f32_16x16x32_bf16 v[46:49], v[200:203], v[154:157], v[46:49]
	v_mfma_f32_16x16x32_bf16 v[34:37], v[192:195], v[166:169], v[34:37]
	v_mfma_f32_16x16x32_bf16 v[30:33], v[200:203], v[166:169], v[30:33]
	v_mfma_f32_16x16x32_bf16 v[18:21], v[192:195], v[174:177], v[18:21]
	v_mfma_f32_16x16x32_bf16 v[14:17], v[200:203], v[174:177], v[14:17]
	v_mfma_f32_16x16x32_bf16 v[6:9], v[192:195], v[184:187], v[6:9]
	v_mfma_f32_16x16x32_bf16 v[2:5], v[200:203], v[184:187], v[2:5]
	v_mfma_f32_16x16x32_bf16 v[50:53], v[196:199], v[162:165], v[50:53]
	v_mfma_f32_16x16x32_bf16 v[46:49], v[204:207], v[162:165], v[46:49]
	v_mfma_f32_16x16x32_bf16 v[34:37], v[196:199], v[170:173], v[34:37]
	v_mfma_f32_16x16x32_bf16 v[30:33], v[204:207], v[170:173], v[30:33]
	v_mfma_f32_16x16x32_bf16 v[18:21], v[196:199], v[180:183], v[18:21]
	v_mfma_f32_16x16x32_bf16 v[14:17], v[204:207], v[180:183], v[14:17]
	v_mfma_f32_16x16x32_bf16 v[6:9], v[196:199], v[188:191], v[6:9]
	v_mfma_f32_16x16x32_bf16 v[2:5], v[204:207], v[188:191], v[2:5]
	s_barrier
	s_cbranch_scc0 .LBB0_495
	v_readlane_b32 s7, v255, 27
	s_cmp_ge_i32 s61, s7
	s_cselect_b32 s7, s29, 0
	s_add_i32 s7, s61, s7
	s_cmp_lt_i32 s7, 32
	v_mov_b32_e32 v156, v158
	v_mov_b32_e32 v130, v1
	s_cselect_b64 s[12:13], -1, 0
	s_sub_i32 s14, s7, 32
	s_lshl_b32 s10, s10, 8
	s_ashr_i32 s14, s14, 3
	s_or_b32 s10, s10, s52
	v_lshl_add_u32 v130, v130, 2, s10
	s_mul_i32 s10, s14, 6
	s_and_b64 s[14:15], s[12:13], exec
	s_cselect_b32 s14, 0xc0, s10
	s_ashr_i32 s15, s14, 31
	s_lshl_b64 s[14:15], s[14:15], 12
	s_add_u32 s14, s88, s14
	s_addc_u32 s15, s89, s15
	s_lshl_b32 s7, s7, 8
	s_add_i32 s7, s7, s50
	v_ashrrev_i32_e32 v131, 31, v130
	v_add_u32_e32 v156, s7, v156
	s_and_b64 s[12:13], s[12:13], exec
	v_readlane_b32 s7, v255, 16
	v_readlane_b32 s10, v255, 18
	v_lshlrev_b64 v[154:155], 2, v[130:131]
	s_cselect_b32 s13, s7, s10
	v_readlane_b32 s7, v255, 17
	v_readlane_b32 s10, v255, 19
	v_ashrrev_i32_e32 v157, 31, v156
	v_lshl_add_u64 v[130:131], s[14:15], 0, v[154:155]
	s_mov_b64 s[14:15], 0x2000
	s_cselect_b32 s12, s7, s10
	v_lshlrev_b64 v[208:209], 12, v[156:157]
	v_lshl_add_u64 v[132:133], v[130:131], 0, s[14:15]
	v_add_co_u32_e32 v130, vcc, s71, v130
	v_lshl_add_u64 v[156:157], s[12:13], 0, v[208:209]
	s_nop 0
	v_addc_co_u32_e32 v131, vcc, 0, v131, vcc
	v_lshl_add_u64 v[156:157], v[156:157], 0, v[154:155]
	v_add_co_u32_e32 v192, vcc, s45, v156
	global_load_dwordx4 v[138:141], v[132:133], off offset:64
	global_load_dwordx4 v[134:137], v[132:133], off offset:512
	global_load_dwordx4 v[142:145], v[130:131], off
	s_nop 0
	global_load_dwordx4 v[130:133], v[132:133], off offset:576
	v_addc_co_u32_e32 v193, vcc, 0, v157, vcc
	v_add_co_u32_e32 v226, vcc, s19, v156
	global_load_dwordx4 v[162:165], v[156:157], off
	global_load_dwordx4 v[166:169], v[156:157], off offset:64
	global_load_dwordx4 v[170:173], v[156:157], off offset:512
	global_load_dwordx4 v[174:177], v[156:157], off offset:576
	v_addc_co_u32_e32 v227, vcc, 0, v157, vcc
	v_add_co_u32_e32 v242, vcc, s69, v156
	global_load_dwordx4 v[180:183], v[192:193], off
	global_load_dwordx4 v[184:187], v[192:193], off offset:64
	global_load_dwordx4 v[188:191], v[192:193], off offset:512
	s_nop 0
	global_load_dwordx4 v[192:195], v[192:193], off offset:576
	v_addc_co_u32_e32 v243, vcc, 0, v157, vcc
	global_load_dwordx4 v[196:199], v[226:227], off
	global_load_dwordx4 v[200:203], v[226:227], off offset:64
	global_load_dwordx4 v[204:207], v[226:227], off offset:512
	s_nop 0
	global_load_dwordx4 v[226:229], v[226:227], off offset:576
	s_nop 0
	global_load_dwordx4 v[230:233], v[242:243], off
	global_load_dwordx4 v[234:237], v[242:243], off offset:64
	global_load_dwordx4 v[238:241], v[242:243], off offset:512
	s_nop 0
	global_load_dwordx4 v[242:245], v[242:243], off offset:576
	v_readlane_b32 s12, v254, 0
	v_readlane_b32 s13, v254, 1
	s_waitcnt vmcnt(0)
	v_pk_fma_f32 v[112:113], v[112:113], v[132:133], v[176:177]
	v_pk_fma_f32 v[110:111], v[110:111], v[130:131], v[174:175]
	v_lshl_add_u64 v[208:209], s[12:13], 0, v[208:209]
	v_lshl_add_u64 v[154:155], v[208:209], 0, v[154:155]
	v_pk_fma_f32 v[120:121], v[120:121], v[136:137], v[172:173]
	v_pk_fma_f32 v[118:119], v[118:119], v[134:135], v[170:171]
	global_store_dwordx4 v[154:155], v[110:113], off offset:576
	global_store_dwordx4 v[154:155], v[118:121], off offset:512
	v_pk_fma_f32 v[100:101], v[100:101], v[136:137], v[190:191]
	v_pk_fma_f32 v[110:111], v[114:115], v[142:143], v[180:181]
	v_add_co_u32_e32 v114, vcc, s45, v154
	v_lshl_add_u64 v[118:119], v[154:155], 0, s[84:85]
	s_nop 0
	v_addc_co_u32_e32 v115, vcc, 0, v155, vcc
	v_pk_fma_f32 v[98:99], v[98:99], v[134:135], v[188:189]
	global_store_dwordx4 v[118:119], v[98:101], off offset:512
	v_pk_fma_f32 v[84:85], v[84:85], v[136:137], v[206:207]
	v_pk_fma_f32 v[82:83], v[82:83], v[134:135], v[204:205]
	v_add_co_u32_e32 v100, vcc, s19, v154
	v_lshl_add_u64 v[98:99], v[154:155], 0, s[82:83]
	s_nop 0
	v_addc_co_u32_e32 v101, vcc, 0, v155, vcc
	v_pk_fma_f32 v[96:97], v[96:97], v[132:133], v[194:195]
	v_pk_fma_f32 v[94:95], v[94:95], v[130:131], v[192:193]
	global_store_dwordx4 v[98:99], v[82:85], off offset:512
	v_pk_fma_f32 v[80:81], v[80:81], v[132:133], v[228:229]
	v_pk_fma_f32 v[78:79], v[78:79], v[130:131], v[226:227]
	s_mov_b64 s[12:13], 0x30000
	v_add_co_u32_e32 v84, vcc, s69, v154
	v_pk_fma_f32 v[128:129], v[128:129], v[144:145], v[164:165]
	v_pk_fma_f32 v[126:127], v[126:127], v[142:143], v[162:163]
	v_pk_fma_f32 v[124:125], v[124:125], v[140:141], v[168:169]
	v_pk_fma_f32 v[122:123], v[122:123], v[138:139], v[166:167]
;     __device__ __forceinline__ void operator()(const AccT& acc, const Unit& u, int wr, int wc, int fr, int fq) const {
;     ...
;         for (int ai = 0; ai < 2; ++ai) {
;             f32x4 xo[4][2][2];
; #pragma unroll
;             for (int m = 0; m < 4; ++m)
; #pragma unroll
;                 for (int bj = 0; bj < 2; ++bj)
; #pragma unroll
;                     for (int n = 0; n < 2; ++n) xo[m][bj][n] = *(const f32x4*)(sbase + (size_t)(ai * 128 + m * 16) * 1024 + bj * 128 + n * 16);
;             __builtin_amdgcn_sched_barrier(0);
; #pragma unroll
;             for (int m = 0; m < 4; ++m) { float* rowp = X + (size_t)(row0 + ai * 128 + m * 16) * 1024 + col0;
; #pragma unroll
;                 for (int bj = 0; bj < 2; ++bj)
; #pragma unroll
;                     for (int n = 0; n < 2; ++n) *(f32x4*)(rowp + bj * 128 + n * 16) = xo[m][bj][n] + gv[bj][n] * acc[ai][bj][m][n]; }
	v_pk_fma_f32 v[112:113], v[116:117], v[144:145], v[182:183]
	v_pk_fma_f32 v[108:109], v[108:109], v[140:141], v[186:187]
	v_pk_fma_f32 v[106:107], v[106:107], v[138:139], v[184:185]
	global_store_dwordx4 v[118:119], v[94:97], off offset:576
	v_pk_fma_f32 v[92:93], v[92:93], v[140:141], v[202:203]
	v_pk_fma_f32 v[90:91], v[90:91], v[138:139], v[200:201]
	v_pk_fma_f32 v[96:97], v[104:105], v[144:145], v[198:199]
	v_pk_fma_f32 v[94:95], v[102:103], v[142:143], v[196:197]
	global_store_dwordx4 v[98:99], v[78:81], off offset:576
	v_lshl_add_u64 v[82:83], v[154:155], 0, s[12:13]
	v_addc_co_u32_e32 v85, vcc, 0, v155, vcc
	v_pk_fma_f32 v[80:81], v[88:89], v[144:145], v[232:233]
	v_pk_fma_f32 v[78:79], v[86:87], v[142:143], v[230:231]
	v_pk_fma_f32 v[76:77], v[76:77], v[140:141], v[236:237]
	v_pk_fma_f32 v[74:75], v[74:75], v[138:139], v[234:235]
	v_pk_fma_f32 v[72:73], v[72:73], v[136:137], v[240:241]
	v_pk_fma_f32 v[70:71], v[70:71], v[134:135], v[238:239]
	v_pk_fma_f32 v[68:69], v[68:69], v[132:133], v[244:245]
	v_pk_fma_f32 v[66:67], v[66:67], v[130:131], v[242:243]
	global_store_dwordx4 v[154:155], v[126:129], off
	global_store_dwordx4 v[154:155], v[122:125], off offset:64
	global_store_dwordx4 v[114:115], v[110:113], off
	global_store_dwordx4 v[118:119], v[106:109], off offset:64
	global_store_dwordx4 v[100:101], v[94:97], off
	global_store_dwordx4 v[98:99], v[90:93], off offset:64
	global_store_dwordx4 v[84:85], v[78:81], off
	global_store_dwordx4 v[82:83], v[74:77], off offset:64
	global_store_dwordx4 v[82:83], v[70:73], off offset:512
	global_store_dwordx4 v[82:83], v[66:69], off offset:576
	s_mov_b32 s7, 0x80000
	v_add_co_u32_e32 v78, vcc, s7, v156
	s_mov_b32 s10, 0x90000
	s_nop 0
	v_addc_co_u32_e32 v79, vcc, 0, v157, vcc
	v_add_co_u32_e32 v94, vcc, s10, v156
	s_mov_b32 s12, 0xa0000
	s_nop 0
	v_addc_co_u32_e32 v95, vcc, 0, v157, vcc
	v_add_co_u32_e32 v110, vcc, s12, v156
	s_mov_b32 s13, 0xb0000
	s_nop 0
	v_addc_co_u32_e32 v111, vcc, 0, v157, vcc
	v_add_co_u32_e32 v126, vcc, s13, v156
	global_load_dwordx4 v[66:69], v[78:79], off
	global_load_dwordx4 v[70:73], v[78:79], off offset:64
	global_load_dwordx4 v[74:77], v[78:79], off offset:512
	s_nop 0
	global_load_dwordx4 v[78:81], v[78:79], off offset:576
	v_addc_co_u32_e32 v127, vcc, 0, v157, vcc
	global_load_dwordx4 v[82:85], v[94:95], off
	global_load_dwordx4 v[86:89], v[94:95], off offset:64
	global_load_dwordx4 v[90:93], v[94:95], off offset:512
	s_nop 0
	global_load_dwordx4 v[94:97], v[94:95], off offset:576
	s_nop 0
	global_load_dwordx4 v[98:101], v[110:111], off
	global_load_dwordx4 v[102:105], v[110:111], off offset:64
	global_load_dwordx4 v[106:109], v[110:111], off offset:512
	s_nop 0
	global_load_dwordx4 v[110:113], v[110:111], off offset:576
	s_nop 0
	global_load_dwordx4 v[114:117], v[126:127], off
	global_load_dwordx4 v[118:121], v[126:127], off offset:64
	global_load_dwordx4 v[122:125], v[126:127], off offset:512
	s_nop 0
	global_load_dwordx4 v[126:129], v[126:127], off offset:576
	s_mov_b64 s[14:15], 0x80000
	s_waitcnt vmcnt(0)
	v_pk_fma_f32 v[62:63], v[62:63], v[142:143], v[66:67]
	v_add_co_u32_e32 v66, vcc, s7, v154
	v_lshl_add_u64 v[156:157], v[154:155], 0, s[14:15]
	s_nop 0
	v_addc_co_u32_e32 v67, vcc, 0, v155, vcc
	v_pk_fma_f32 v[52:53], v[52:53], v[136:137], v[76:77]
	v_pk_fma_f32 v[50:51], v[50:51], v[134:135], v[74:75]
	global_store_dwordx4 v[156:157], v[50:53], off offset:512
	s_mov_b64 s[14:15], 0x90000
	v_pk_fma_f32 v[36:37], v[36:37], v[136:137], v[92:93]
	v_add_co_u32_e32 v52, vcc, s10, v154
	v_lshl_add_u64 v[50:51], v[154:155], 0, s[14:15]
	s_nop 0
	v_addc_co_u32_e32 v53, vcc, 0, v155, vcc
	v_pk_fma_f32 v[34:35], v[34:35], v[134:135], v[90:91]
	global_store_dwordx4 v[50:51], v[34:37], off offset:512
	s_mov_b64 s[14:15], 0xa0000
	v_pk_fma_f32 v[20:21], v[20:21], v[136:137], v[108:109]
	v_add_co_u32_e32 v36, vcc, s12, v154
	v_lshl_add_u64 v[34:35], v[154:155], 0, s[14:15]
	s_nop 0
	v_addc_co_u32_e32 v37, vcc, 0, v155, vcc
	v_pk_fma_f32 v[18:19], v[18:19], v[134:135], v[106:107]
	v_pk_fma_f32 v[48:49], v[48:49], v[132:133], v[80:81]
	v_pk_fma_f32 v[46:47], v[46:47], v[130:131], v[78:79]
	v_pk_fma_f32 v[32:33], v[32:33], v[132:133], v[96:97]
	v_pk_fma_f32 v[30:31], v[30:31], v[130:131], v[94:95]
	global_store_dwordx4 v[34:35], v[18:21], off offset:512
	v_pk_fma_f32 v[16:17], v[16:17], v[132:133], v[112:113]
	v_pk_fma_f32 v[14:15], v[14:15], v[130:131], v[110:111]
	s_mov_b64 s[14:15], 0xb0000
	v_add_co_u32_e32 v20, vcc, s13, v154
	v_pk_fma_f32 v[64:65], v[64:65], v[144:145], v[68:69]
	v_pk_fma_f32 v[60:61], v[60:61], v[140:141], v[72:73]
	v_pk_fma_f32 v[58:59], v[58:59], v[138:139], v[70:71]
	global_store_dwordx4 v[156:157], v[46:49], off offset:576
	v_pk_fma_f32 v[44:45], v[44:45], v[140:141], v[88:89]
	v_pk_fma_f32 v[42:43], v[42:43], v[138:139], v[86:87]
	v_pk_fma_f32 v[48:49], v[56:57], v[144:145], v[84:85]
	v_pk_fma_f32 v[46:47], v[54:55], v[142:143], v[82:83]
	global_store_dwordx4 v[50:51], v[30:33], off offset:576
	v_pk_fma_f32 v[28:29], v[28:29], v[140:141], v[104:105]
	v_pk_fma_f32 v[26:27], v[26:27], v[138:139], v[102:103]
	v_pk_fma_f32 v[32:33], v[40:41], v[144:145], v[100:101]
	v_pk_fma_f32 v[30:31], v[38:39], v[142:143], v[98:99]
	global_store_dwordx4 v[34:35], v[14:17], off offset:576
	v_lshl_add_u64 v[18:19], v[154:155], 0, s[14:15]
	v_addc_co_u32_e32 v21, vcc, 0, v155, vcc
	v_pk_fma_f32 v[16:17], v[24:25], v[144:145], v[116:117]
	v_pk_fma_f32 v[14:15], v[22:23], v[142:143], v[114:115]
	v_pk_fma_f32 v[12:13], v[12:13], v[140:141], v[120:121]
	v_pk_fma_f32 v[10:11], v[10:11], v[138:139], v[118:119]
	v_pk_fma_f32 v[8:9], v[8:9], v[136:137], v[124:125]
	v_pk_fma_f32 v[6:7], v[6:7], v[134:135], v[122:123]
	v_pk_fma_f32 v[4:5], v[4:5], v[132:133], v[128:129]
	v_pk_fma_f32 v[2:3], v[2:3], v[130:131], v[126:127]
	global_store_dwordx4 v[66:67], v[62:65], off
	global_store_dwordx4 v[156:157], v[58:61], off offset:64
	global_store_dwordx4 v[52:53], v[46:49], off
	global_store_dwordx4 v[50:51], v[42:45], off offset:64
	global_store_dwordx4 v[36:37], v[30:33], off
	global_store_dwordx4 v[34:35], v[26:29], off offset:64
	global_store_dwordx4 v[20:21], v[14:17], off
	global_store_dwordx4 v[18:19], v[10:13], off offset:64
	global_store_dwordx4 v[18:19], v[6:9], off offset:512
	global_store_dwordx4 v[18:19], v[2:5], off offset:576
	s_and_b64 vcc, exec, s[2:3]
	s_mov_b32 s10, s6
	s_mov_b32 s61, s60
	s_mov_b64 s[14:15], s[4:5]
	s_mov_b64 s[12:13], s[8:9]
	s_cbranch_vccz .LBB0_490
	s_waitcnt vmcnt(0)
	s_cmpk_gt_u32 s1, 0xff
	s_cbranch_scc1 .LBB0_499
	s_barrier

; #define PG8_STAGE(bufoff, gbase, voff) do { _Pragma("unroll") for (int _i = 0; _i < 2; ++_i) \
;         __builtin_amdgcn_global_load_lds((const unsigned*)((const char*)(gbase) + (voff)[_i]), (LAS unsigned*)(lds + (bufoff) + ldsw + _i * 8192), 16, 0, 0); } while (0)
; #define PG8_LDA(dst, b, h) do { _Pragma("unroll") for (int m = 0; m < 4; ++m) _Pragma("unroll") for (int k = 0; k < 2; ++k) dst[m][k] = *(const LAS bf16x8*)(lds + PG8_SA(b, h) + aoff + m * 2048 + k * 1024); } while (0)
; #define PG8_LDB(dst, b, h) do { _Pragma("unroll") for (int n = 0; n < 2; ++n) _Pragma("unroll") for (int k = 0; k < 2; ++k) dst[n][k] = *(const LAS bf16x8*)(lds + PG8_SB(b, h) + boff + n * 2048 + k * 1024); } while (0)
; #define PG8_MMA(ai, bj, At, Bt) do { __builtin_amdgcn_s_setprio(1); _Pragma("unroll") for (int m = 0; m < 4; ++m) _Pragma("unroll") for (int n = 0; n < 2; ++n) _Pragma("unroll") for (int k = 0; k < 2; ++k) \
;         acc[ai][bj][m][n] = __builtin_amdgcn_mfma_f32_16x16x32_bf16(Bt[n][k], At[m][k], acc[ai][bj][m][n], 0, 0, 0); __builtin_amdgcn_s_setprio(0); } while (0)
; #define PG8_WAIT_L(n) asm volatile("s_waitcnt lgkmcnt(" #n ")" ::: "memory")
; #define PG8_BAR __builtin_amdgcn_s_barrier()
; #define PG8_SCHED __builtin_amdgcn_sched_barrier(0)
; template <class Epi>
; __device__ __forceinline__ void gemm_phase(LAS unsigned char* lds, const Gemm g, const Epi& E) {
;     ...
;             PG8_LDB(B0, 0, 0); PG8_SCHED; PG8_LDA(At, 0, 0); PG8_STAGE(PG8_SA(1, 1), a1 + hstepA, voffA);
;             PG8_WAIT_L(8); PG8_BAR; PG8_WAIT_L(0); PG8_MMA(0, 0, At, B0); PG8_BAR; PG8_SCHED;
;     ...
;         for (int a = 0; a < 2; ++a)
; #pragma unroll
;             for (int b = 0; b < 2; ++b)
; #pragma unroll
;                 for (int m = 0; m < 4; ++m)
; #pragma unroll
;                     for (int n = 0; n < 2; ++n) acc[a][b][m][n] = (f32x4){0.f, 0.f, 0.f, 0.f};
.LBB0_524:
	s_ashr_i32 s7, s6, 31
	s_lshl_b64 s[16:17], s[6:7], 19
	s_add_u32 s7, s18, s16
	s_addc_u32 s16, s24, s17
	s_and_b64 s[4:5], s[4:5], exec
	s_cselect_b32 s5, s16, s15
	s_cselect_b32 s4, s7, s14
	s_add_u32 s12, s12, 0x40080
	s_addc_u32 s13, s13, 0
	s_add_u32 s7, s14, 0x100
	v_mov_b32_e32 v2, 0
	s_addc_u32 s65, s15, 0
	s_mov_b32 s66, -2
	v_mov_b32_e32 v3, v2
	v_mov_b64_e32 v[4:5], v[2:3]
	v_mov_b64_e32 v[6:7], v[2:3]
	v_mov_b64_e32 v[8:9], v[2:3]
	v_mov_b64_e32 v[10:11], v[2:3]
	v_mov_b64_e32 v[12:13], v[2:3]
	v_mov_b64_e32 v[14:15], v[2:3]
	v_mov_b64_e32 v[16:17], v[2:3]
	v_mov_b64_e32 v[18:19], v[2:3]
	v_mov_b64_e32 v[20:21], v[2:3]
	v_mov_b64_e32 v[22:23], v[2:3]
	v_mov_b64_e32 v[24:25], v[2:3]
	v_mov_b64_e32 v[26:27], v[2:3]
	v_mov_b64_e32 v[28:29], v[2:3]
	v_mov_b64_e32 v[30:31], v[2:3]
	v_mov_b64_e32 v[32:33], v[2:3]
	v_mov_b64_e32 v[34:35], v[2:3]
	v_mov_b64_e32 v[36:37], v[2:3]
	v_mov_b64_e32 v[38:39], v[2:3]
	v_mov_b64_e32 v[40:41], v[2:3]
	v_mov_b64_e32 v[42:43], v[2:3]
	v_mov_b64_e32 v[44:45], v[2:3]
	v_mov_b64_e32 v[46:47], v[2:3]
	v_mov_b64_e32 v[48:49], v[2:3]
	v_mov_b64_e32 v[50:51], v[2:3]
	v_mov_b64_e32 v[52:53], v[2:3]
	v_mov_b64_e32 v[54:55], v[2:3]
	v_mov_b64_e32 v[56:57], v[2:3]
	v_mov_b64_e32 v[58:59], v[2:3]
	v_mov_b64_e32 v[60:61], v[2:3]
	v_mov_b64_e32 v[62:63], v[2:3]
	v_mov_b64_e32 v[64:65], v[2:3]
	v_mov_b64_e32 v[66:67], v[2:3]
	v_mov_b64_e32 v[68:69], v[2:3]
	v_mov_b64_e32 v[70:71], v[2:3]
	v_mov_b64_e32 v[72:73], v[2:3]
	v_mov_b64_e32 v[74:75], v[2:3]
	v_mov_b64_e32 v[76:77], v[2:3]
	v_mov_b64_e32 v[78:79], v[2:3]
	v_mov_b64_e32 v[80:81], v[2:3]
	v_mov_b64_e32 v[82:83], v[2:3]
	v_mov_b64_e32 v[84:85], v[2:3]
	v_mov_b64_e32 v[86:87], v[2:3]
	v_mov_b64_e32 v[88:89], v[2:3]
	v_mov_b64_e32 v[90:91], v[2:3]
	v_mov_b64_e32 v[92:93], v[2:3]
	v_mov_b64_e32 v[94:95], v[2:3]
	v_mov_b64_e32 v[96:97], v[2:3]
	v_mov_b64_e32 v[98:99], v[2:3]
	v_mov_b64_e32 v[100:101], v[2:3]
	v_mov_b64_e32 v[102:103], v[2:3]
	v_mov_b64_e32 v[104:105], v[2:3]
	v_mov_b64_e32 v[106:107], v[2:3]
	v_mov_b64_e32 v[108:109], v[2:3]
	v_mov_b64_e32 v[110:111], v[2:3]
	v_mov_b64_e32 v[112:113], v[2:3]
	v_mov_b64_e32 v[114:115], v[2:3]
	v_mov_b64_e32 v[116:117], v[2:3]
	v_mov_b64_e32 v[118:119], v[2:3]
	v_mov_b64_e32 v[120:121], v[2:3]
	v_mov_b64_e32 v[122:123], v[2:3]
	v_mov_b64_e32 v[124:125], v[2:3]
	v_mov_b64_e32 v[126:127], v[2:3]
	v_mov_b64_e32 v[128:129], v[2:3]
	s_add_i32 s26, 0, 0x10000
	v_add_u32_e32 v149, s26, v147
.LBB0_525:
	ds_read_b128 v[142:145], v149
	ds_read_b128 v[150:153], v149 offset:1024
	ds_read_b128 v[154:157], v149 offset:2048
	ds_read_b128 v[158:161], v149 offset:3072
	ds_read_b128 v[162:165], v148
	ds_read_b128 v[166:169], v148 offset:1024
	ds_read_b128 v[170:173], v148 offset:2048
	ds_read_b128 v[174:177], v148 offset:3072
	ds_read_b128 v[180:183], v148 offset:4096
	ds_read_b128 v[184:187], v148 offset:5120
	ds_read_b128 v[188:191], v148 offset:6144
	ds_read_b128 v[192:195], v148 offset:7168
	s_add_u32 s14, s12, 0xfffc0080
	s_addc_u32 s15, s13, -1
	s_cmp_eq_u32 s66, 12
	s_cselect_b32 s17, s9, s15
	s_cselect_b32 s16, s8, s14
	s_cselect_b32 s15, s5, s65
	s_cselect_b32 s14, s4, s7
	v_lshl_add_u64 v[196:197], s[12:13], 0, v[138:139]
	s_add_i32 m0, s11, 0xc000
	s_nop 0
	global_load_lds_dwordx4 v[196:197], off
	v_lshl_add_u64 v[196:197], s[12:13], 0, v[140:141]
	s_add_i32 m0, s11, 0xe000
	s_nop 0
	global_load_lds_dwordx4 v[196:197], off
	s_waitcnt lgkmcnt(8)
	s_barrier
	s_waitcnt lgkmcnt(0)
	v_mfma_f32_16x16x32_bf16 v[126:129], v[142:145], v[162:165], v[126:129]
	v_mfma_f32_16x16x32_bf16 v[118:121], v[154:157], v[162:165], v[118:121]
	v_mfma_f32_16x16x32_bf16 v[110:113], v[142:145], v[170:173], v[110:113]
	v_mfma_f32_16x16x32_bf16 v[102:105], v[154:157], v[170:173], v[102:105]
	v_mfma_f32_16x16x32_bf16 v[94:97], v[142:145], v[180:183], v[94:97]
	v_mfma_f32_16x16x32_bf16 v[86:89], v[154:157], v[180:183], v[86:89]
	v_mfma_f32_16x16x32_bf16 v[78:81], v[142:145], v[188:191], v[78:81]
	v_mfma_f32_16x16x32_bf16 v[70:73], v[154:157], v[188:191], v[70:73]
	v_mfma_f32_16x16x32_bf16 v[126:129], v[150:153], v[166:169], v[126:129]
	v_mfma_f32_16x16x32_bf16 v[118:121], v[158:161], v[166:169], v[118:121]
	v_mfma_f32_16x16x32_bf16 v[110:113], v[150:153], v[174:177], v[110:113]
	v_mfma_f32_16x16x32_bf16 v[102:105], v[158:161], v[174:177], v[102:105]
	v_mfma_f32_16x16x32_bf16 v[94:97], v[150:153], v[184:187], v[94:97]
	v_mfma_f32_16x16x32_bf16 v[86:89], v[158:161], v[184:187], v[86:89]
	v_mfma_f32_16x16x32_bf16 v[78:81], v[150:153], v[192:195], v[78:81]
	v_mfma_f32_16x16x32_bf16 v[70:73], v[158:161], v[192:195], v[70:73]
	s_barrier
	s_add_i32 s27, 0, 0x14000
	s_add_i32 s26, s26, s25
	v_add_u32_e32 v149, s27, v147
	v_lshl_add_u64 v[208:209], s[14:15], 0, v[134:135]
	s_mov_b32 m0, s26
	ds_read_b128 v[196:199], v149
	ds_read_b128 v[200:203], v149 offset:1024
	ds_read_b128 v[204:207], v149 offset:2048
	ds_read_b128 v[226:229], v149 offset:3072
	global_load_lds_dwordx4 v[208:209], off
	v_lshl_add_u64 v[230:231], s[14:15], 0, v[130:131]
	s_add_i32 m0, s26, 0x2000
	s_nop 0
	global_load_lds_dwordx4 v[230:231], off
	s_nop 1
	s_mov_b32 m0, s11
	v_lshl_add_u64 v[232:233], s[16:17], 0, v[136:137]
	s_barrier
; #define PG8_STAGE(bufoff, gbase, voff) do { _Pragma("unroll") for (int _i = 0; _i < 2; ++_i) \
;         __builtin_amdgcn_global_load_lds((const unsigned*)((const char*)(gbase) + (voff)[_i]), (LAS unsigned*)(lds + (bufoff) + ldsw + _i * 8192), 16, 0, 0); } while (0)
; #define PG8_LDA(dst, b, h) do { _Pragma("unroll") for (int m = 0; m < 4; ++m) _Pragma("unroll") for (int k = 0; k < 2; ++k) dst[m][k] = *(const LAS bf16x8*)(lds + PG8_SA(b, h) + aoff + m * 2048 + k * 1024); } while (0)
; #define PG8_LDB(dst, b, h) do { _Pragma("unroll") for (int n = 0; n < 2; ++n) _Pragma("unroll") for (int k = 0; k < 2; ++k) dst[n][k] = *(const LAS bf16x8*)(lds + PG8_SB(b, h) + boff + n * 2048 + k * 1024); } while (0)
; #define PG8_MMA(ai, bj, At, Bt) do { __builtin_amdgcn_s_setprio(1); _Pragma("unroll") for (int m = 0; m < 4; ++m) _Pragma("unroll") for (int n = 0; n < 2; ++n) _Pragma("unroll") for (int k = 0; k < 2; ++k) \
;         acc[ai][bj][m][n] = __builtin_amdgcn_mfma_f32_16x16x32_bf16(Bt[n][k], At[m][k], acc[ai][bj][m][n], 0, 0, 0); __builtin_amdgcn_s_setprio(0); } while (0)
; #define PG8_WAIT_V(n) asm volatile("s_waitcnt vmcnt(" #n ")" ::: "memory")
; #define PG8_WAIT_L(n) asm volatile("s_waitcnt lgkmcnt(" #n ")" ::: "memory")
; #define PG8_BAR __builtin_amdgcn_s_barrier()
; #define PG8_SCHED __builtin_amdgcn_sched_barrier(0)
; template <class Epi>
; __device__ __forceinline__ void gemm_phase(LAS unsigned char* lds, const Gemm g, const Epi& E) {
;     ...
;             PG8_WAIT_L(8); PG8_BAR; PG8_WAIT_L(0); PG8_MMA(0, 0, At, B0); PG8_BAR; PG8_SCHED;
;             PG8_LDB(B1, 0, 1); PG8_STAGE(PG8_SB(0, 0), b2, voffB);
;             PG8_BAR; PG8_WAIT_L(0); PG8_MMA(0, 1, At, B1); PG8_BAR;
;             PG8_LDA(At, 0, 1); PG8_STAGE(PG8_SA(0, 0), a2, voffA);
;             PG8_BAR; PG8_WAIT_L(0); PG8_MMA(1, 0, At, B0); PG8_BAR; PG8_SCHED;
;             PG8_STAGE(PG8_SB(0, 1), b2 + hstepB, voffB);
;             PG8_WAIT_V(6); PG8_BAR; PG8_MMA(1, 1, At, B1); PG8_BAR;
;             PG8_LDB(B0, 1, 0); PG8_SCHED; PG8_LDA(At, 1, 0); PG8_STAGE(PG8_SA(0, 1), a2 + hstepA, voffA);
	s_waitcnt lgkmcnt(0)
	v_mfma_f32_16x16x32_bf16 v[122:125], v[196:199], v[162:165], v[122:125]
	v_mfma_f32_16x16x32_bf16 v[114:117], v[204:207], v[162:165], v[114:117]
	v_mfma_f32_16x16x32_bf16 v[106:109], v[196:199], v[170:173], v[106:109]
	v_mfma_f32_16x16x32_bf16 v[98:101], v[204:207], v[170:173], v[98:101]
	v_mfma_f32_16x16x32_bf16 v[90:93], v[196:199], v[180:183], v[90:93]
	v_mfma_f32_16x16x32_bf16 v[82:85], v[204:207], v[180:183], v[82:85]
	v_mfma_f32_16x16x32_bf16 v[74:77], v[196:199], v[188:191], v[74:77]
	v_mfma_f32_16x16x32_bf16 v[66:69], v[204:207], v[188:191], v[66:69]
	v_mfma_f32_16x16x32_bf16 v[122:125], v[200:203], v[166:169], v[122:125]
	v_mfma_f32_16x16x32_bf16 v[114:117], v[226:229], v[166:169], v[114:117]
	v_mfma_f32_16x16x32_bf16 v[106:109], v[200:203], v[174:177], v[106:109]
	v_mfma_f32_16x16x32_bf16 v[98:101], v[226:229], v[174:177], v[98:101]
	v_mfma_f32_16x16x32_bf16 v[90:93], v[200:203], v[184:187], v[90:93]
	v_mfma_f32_16x16x32_bf16 v[82:85], v[226:229], v[184:187], v[82:85]
	v_mfma_f32_16x16x32_bf16 v[74:77], v[200:203], v[192:195], v[74:77]
	v_mfma_f32_16x16x32_bf16 v[66:69], v[226:229], v[192:195], v[66:69]
	s_barrier
	ds_read_b128 v[162:165], v148 offset:16384
	ds_read_b128 v[166:169], v148 offset:17408
	ds_read_b128 v[170:173], v148 offset:18432
	ds_read_b128 v[174:177], v148 offset:19456
	ds_read_b128 v[180:183], v148 offset:20480
	ds_read_b128 v[184:187], v148 offset:21504
	ds_read_b128 v[188:191], v148 offset:22528
	ds_read_b128 v[192:195], v148 offset:23552
	global_load_lds_dwordx4 v[232:233], off
	v_lshl_add_u64 v[234:235], s[16:17], 0, v[132:133]
	s_mov_b32 m0, s36
	s_nop 0
	global_load_lds_dwordx4 v[234:235], off
	s_barrier
	s_waitcnt lgkmcnt(0)
	v_mfma_f32_16x16x32_bf16 v[62:65], v[142:145], v[162:165], v[62:65]
	v_mfma_f32_16x16x32_bf16 v[54:57], v[154:157], v[162:165], v[54:57]
	v_mfma_f32_16x16x32_bf16 v[46:49], v[142:145], v[170:173], v[46:49]
	v_mfma_f32_16x16x32_bf16 v[38:41], v[154:157], v[170:173], v[38:41]
	v_mfma_f32_16x16x32_bf16 v[30:33], v[142:145], v[180:183], v[30:33]
	v_mfma_f32_16x16x32_bf16 v[22:25], v[154:157], v[180:183], v[22:25]
	v_mfma_f32_16x16x32_bf16 v[14:17], v[142:145], v[188:191], v[14:17]
	v_mfma_f32_16x16x32_bf16 v[6:9], v[154:157], v[188:191], v[6:9]
	v_mfma_f32_16x16x32_bf16 v[62:65], v[150:153], v[166:169], v[62:65]
	v_mfma_f32_16x16x32_bf16 v[54:57], v[158:161], v[166:169], v[54:57]
	v_mfma_f32_16x16x32_bf16 v[46:49], v[150:153], v[174:177], v[46:49]
	v_mfma_f32_16x16x32_bf16 v[38:41], v[158:161], v[174:177], v[38:41]
	v_mfma_f32_16x16x32_bf16 v[30:33], v[150:153], v[184:187], v[30:33]
	v_mfma_f32_16x16x32_bf16 v[22:25], v[158:161], v[184:187], v[22:25]
	v_mfma_f32_16x16x32_bf16 v[14:17], v[150:153], v[192:195], v[14:17]
	v_mfma_f32_16x16x32_bf16 v[6:9], v[158:161], v[192:195], v[6:9]
	s_barrier
	s_add_u32 s68, s14, 0x40000
	s_addc_u32 s69, s15, 0
	s_add_i32 s26, s27, s25
	v_lshl_add_u64 v[142:143], s[68:69], 0, v[134:135]
	s_mov_b32 m0, s26
	s_nop 0
	global_load_lds_dwordx4 v[142:143], off
	v_lshl_add_u64 v[142:143], s[68:69], 0, v[130:131]
	s_add_i32 m0, s26, 0x2000
	s_nop 0
	global_load_lds_dwordx4 v[142:143], off
	s_add_i32 s26, 0, 0x18000
	v_add_u32_e32 v149, s26, v147
	s_waitcnt vmcnt(6)
	s_barrier
	v_mfma_f32_16x16x32_bf16 v[58:61], v[196:199], v[162:165], v[58:61]
	v_mfma_f32_16x16x32_bf16 v[50:53], v[204:207], v[162:165], v[50:53]
	v_mfma_f32_16x16x32_bf16 v[42:45], v[196:199], v[170:173], v[42:45]
	v_mfma_f32_16x16x32_bf16 v[34:37], v[204:207], v[170:173], v[34:37]
	v_mfma_f32_16x16x32_bf16 v[26:29], v[196:199], v[180:183], v[26:29]
	v_mfma_f32_16x16x32_bf16 v[18:21], v[204:207], v[180:183], v[18:21]
	v_mfma_f32_16x16x32_bf16 v[10:13], v[196:199], v[188:191], v[10:13]
	v_mfma_f32_16x16x32_bf16 v[2:5], v[204:207], v[188:191], v[2:5]
	v_mfma_f32_16x16x32_bf16 v[58:61], v[200:203], v[166:169], v[58:61]
	v_mfma_f32_16x16x32_bf16 v[50:53], v[226:229], v[166:169], v[50:53]
	v_mfma_f32_16x16x32_bf16 v[42:45], v[200:203], v[174:177], v[42:45]
	v_mfma_f32_16x16x32_bf16 v[34:37], v[226:229], v[174:177], v[34:37]
	v_mfma_f32_16x16x32_bf16 v[26:29], v[200:203], v[184:187], v[26:29]
	v_mfma_f32_16x16x32_bf16 v[18:21], v[226:229], v[184:187], v[18:21]
	v_mfma_f32_16x16x32_bf16 v[10:13], v[200:203], v[192:195], v[10:13]
	v_mfma_f32_16x16x32_bf16 v[2:5], v[226:229], v[192:195], v[2:5]
	s_barrier
	ds_read_b128 v[142:145], v149
	ds_read_b128 v[150:153], v149 offset:1024
	ds_read_b128 v[154:157], v149 offset:2048
	ds_read_b128 v[158:161], v149 offset:3072
	s_add_u32 s16, s16, 0x40000
	s_addc_u32 s17, s17, 0
	s_mov_b32 m0, s44
	v_lshl_add_u64 v[196:197], s[16:17], 0, v[136:137]
	ds_read_b128 v[162:165], v148 offset:32768
	ds_read_b128 v[166:169], v148 offset:33792
	ds_read_b128 v[170:173], v148 offset:34816
	ds_read_b128 v[174:177], v148 offset:35840
	ds_read_b128 v[180:183], v148 offset:36864
	ds_read_b128 v[184:187], v148 offset:37888
	ds_read_b128 v[188:191], v148 offset:38912
	ds_read_b128 v[192:195], v148 offset:39936
	global_load_lds_dwordx4 v[196:197], off
	v_lshl_add_u64 v[196:197], s[16:17], 0, v[132:133]
	s_mov_b32 m0, s50
	s_nop 0
	global_load_lds_dwordx4 v[196:197], off
	s_waitcnt lgkmcnt(8)
	s_barrier
; #define PG8_STAGE(bufoff, gbase, voff) do { _Pragma("unroll") for (int _i = 0; _i < 2; ++_i) \
;         __builtin_amdgcn_global_load_lds((const unsigned*)((const char*)(gbase) + (voff)[_i]), (LAS unsigned*)(lds + (bufoff) + ldsw + _i * 8192), 16, 0, 0); } while (0)
; #define PG8_LDA(dst, b, h) do { _Pragma("unroll") for (int m = 0; m < 4; ++m) _Pragma("unroll") for (int k = 0; k < 2; ++k) dst[m][k] = *(const LAS bf16x8*)(lds + PG8_SA(b, h) + aoff + m * 2048 + k * 1024); } while (0)
; #define PG8_LDB(dst, b, h) do { _Pragma("unroll") for (int n = 0; n < 2; ++n) _Pragma("unroll") for (int k = 0; k < 2; ++k) dst[n][k] = *(const LAS bf16x8*)(lds + PG8_SB(b, h) + boff + n * 2048 + k * 1024); } while (0)
; #define PG8_MMA(ai, bj, At, Bt) do { __builtin_amdgcn_s_setprio(1); _Pragma("unroll") for (int m = 0; m < 4; ++m) _Pragma("unroll") for (int n = 0; n < 2; ++n) _Pragma("unroll") for (int k = 0; k < 2; ++k) \
;         acc[ai][bj][m][n] = __builtin_amdgcn_mfma_f32_16x16x32_bf16(Bt[n][k], At[m][k], acc[ai][bj][m][n], 0, 0, 0); __builtin_amdgcn_s_setprio(0); } while (0)
; #define PG8_WAIT_V(n) asm volatile("s_waitcnt vmcnt(" #n ")" ::: "memory")
; #define PG8_WAIT_L(n) asm volatile("s_waitcnt lgkmcnt(" #n ")" ::: "memory")
; #define PG8_BAR __builtin_amdgcn_s_barrier()
; #define PG8_SCHED __builtin_amdgcn_sched_barrier(0)
; template <class Epi>
; __device__ __forceinline__ void gemm_phase(LAS unsigned char* lds, const Gemm g, const Epi& E) {
;     ...
;             PG8_WAIT_L(8); PG8_BAR; PG8_WAIT_L(0); PG8_MMA(0, 0, At, B0); PG8_BAR; PG8_SCHED;
;             PG8_LDB(B1, 1, 1); PG8_STAGE(PG8_SB(1, 0), b3, voffB);
;             PG8_BAR; PG8_WAIT_L(0); PG8_MMA(0, 1, At, B1); PG8_BAR;
;             PG8_LDA(At, 1, 1); PG8_STAGE(PG8_SA(1, 0), a3, voffA);
;             PG8_BAR; PG8_WAIT_L(0); PG8_MMA(1, 0, At, B0); PG8_BAR; PG8_SCHED;
;             PG8_STAGE(PG8_SB(1, 1), b3 + hstepB, voffB);
;             PG8_WAIT_V(6); PG8_BAR; PG8_MMA(1, 1, At, B1); PG8_BAR;
	s_waitcnt lgkmcnt(0)
	v_mfma_f32_16x16x32_bf16 v[126:129], v[142:145], v[162:165], v[126:129]
	v_mfma_f32_16x16x32_bf16 v[118:121], v[154:157], v[162:165], v[118:121]
	v_mfma_f32_16x16x32_bf16 v[110:113], v[142:145], v[170:173], v[110:113]
	v_mfma_f32_16x16x32_bf16 v[102:105], v[154:157], v[170:173], v[102:105]
	v_mfma_f32_16x16x32_bf16 v[94:97], v[142:145], v[180:183], v[94:97]
	v_mfma_f32_16x16x32_bf16 v[86:89], v[154:157], v[180:183], v[86:89]
	v_mfma_f32_16x16x32_bf16 v[78:81], v[142:145], v[188:191], v[78:81]
	v_mfma_f32_16x16x32_bf16 v[70:73], v[154:157], v[188:191], v[70:73]
	v_mfma_f32_16x16x32_bf16 v[126:129], v[150:153], v[166:169], v[126:129]
	v_mfma_f32_16x16x32_bf16 v[118:121], v[158:161], v[166:169], v[118:121]
	v_mfma_f32_16x16x32_bf16 v[110:113], v[150:153], v[174:177], v[110:113]
	v_mfma_f32_16x16x32_bf16 v[102:105], v[158:161], v[174:177], v[102:105]
	v_mfma_f32_16x16x32_bf16 v[94:97], v[150:153], v[184:187], v[94:97]
	v_mfma_f32_16x16x32_bf16 v[86:89], v[158:161], v[184:187], v[86:89]
	v_mfma_f32_16x16x32_bf16 v[78:81], v[150:153], v[192:195], v[78:81]
	v_mfma_f32_16x16x32_bf16 v[70:73], v[158:161], v[192:195], v[70:73]
	s_barrier
	s_add_i32 s16, 0, 0x1c000
	s_add_i32 s17, s26, s25
	v_add_u32_e32 v149, s16, v147
	v_lshl_add_u64 v[208:209], v[208:209], 0, s[86:87]
	s_mov_b32 m0, s17
	ds_read_b128 v[196:199], v149
	ds_read_b128 v[200:203], v149 offset:1024
	ds_read_b128 v[204:207], v149 offset:2048
	ds_read_b128 v[226:229], v149 offset:3072
	global_load_lds_dwordx4 v[208:209], off
	v_lshl_add_u64 v[208:209], v[230:231], 0, s[86:87]
	s_add_i32 m0, s17, 0x2000
	s_nop 0
	global_load_lds_dwordx4 v[208:209], off
	s_nop 1
	s_mov_b32 m0, s58
	v_lshl_add_u64 v[208:209], v[232:233], 0, s[86:87]
	s_barrier
	s_waitcnt lgkmcnt(0)
	v_mfma_f32_16x16x32_bf16 v[122:125], v[196:199], v[162:165], v[122:125]
	v_mfma_f32_16x16x32_bf16 v[114:117], v[204:207], v[162:165], v[114:117]
	v_mfma_f32_16x16x32_bf16 v[106:109], v[196:199], v[170:173], v[106:109]
	v_mfma_f32_16x16x32_bf16 v[98:101], v[204:207], v[170:173], v[98:101]
	v_mfma_f32_16x16x32_bf16 v[90:93], v[196:199], v[180:183], v[90:93]
	v_mfma_f32_16x16x32_bf16 v[82:85], v[204:207], v[180:183], v[82:85]
	v_mfma_f32_16x16x32_bf16 v[74:77], v[196:199], v[188:191], v[74:77]
	v_mfma_f32_16x16x32_bf16 v[66:69], v[204:207], v[188:191], v[66:69]
	v_mfma_f32_16x16x32_bf16 v[122:125], v[200:203], v[166:169], v[122:125]
	v_mfma_f32_16x16x32_bf16 v[114:117], v[226:229], v[166:169], v[114:117]
	v_mfma_f32_16x16x32_bf16 v[106:109], v[200:203], v[174:177], v[106:109]
	v_mfma_f32_16x16x32_bf16 v[98:101], v[226:229], v[174:177], v[98:101]
	v_mfma_f32_16x16x32_bf16 v[90:93], v[200:203], v[184:187], v[90:93]
	v_mfma_f32_16x16x32_bf16 v[82:85], v[226:229], v[184:187], v[82:85]
	v_mfma_f32_16x16x32_bf16 v[74:77], v[200:203], v[192:195], v[74:77]
	v_mfma_f32_16x16x32_bf16 v[66:69], v[226:229], v[192:195], v[66:69]
	s_barrier
	ds_read_b128 v[162:165], v148 offset:49152
	ds_read_b128 v[166:169], v148 offset:50176
	ds_read_b128 v[170:173], v148 offset:51200
	ds_read_b128 v[174:177], v148 offset:52224
	ds_read_b128 v[180:183], v148 offset:53248
	ds_read_b128 v[184:187], v148 offset:54272
	ds_read_b128 v[188:191], v148 offset:55296
	ds_read_b128 v[192:195], v148 offset:56320
	global_load_lds_dwordx4 v[208:209], off
	v_lshl_add_u64 v[208:209], v[234:235], 0, s[86:87]
	s_mov_b32 m0, s59
	s_nop 0
	global_load_lds_dwordx4 v[208:209], off
	s_barrier
	s_waitcnt lgkmcnt(0)
	v_mfma_f32_16x16x32_bf16 v[62:65], v[142:145], v[162:165], v[62:65]
	v_mfma_f32_16x16x32_bf16 v[54:57], v[154:157], v[162:165], v[54:57]
	v_mfma_f32_16x16x32_bf16 v[46:49], v[142:145], v[170:173], v[46:49]
	v_mfma_f32_16x16x32_bf16 v[38:41], v[154:157], v[170:173], v[38:41]
	v_mfma_f32_16x16x32_bf16 v[30:33], v[142:145], v[180:183], v[30:33]
	v_mfma_f32_16x16x32_bf16 v[22:25], v[154:157], v[180:183], v[22:25]
	v_mfma_f32_16x16x32_bf16 v[14:17], v[142:145], v[188:191], v[14:17]
	v_mfma_f32_16x16x32_bf16 v[6:9], v[154:157], v[188:191], v[6:9]
	v_mfma_f32_16x16x32_bf16 v[62:65], v[150:153], v[166:169], v[62:65]
	v_mfma_f32_16x16x32_bf16 v[54:57], v[158:161], v[166:169], v[54:57]
	v_mfma_f32_16x16x32_bf16 v[46:49], v[150:153], v[174:177], v[46:49]
	v_mfma_f32_16x16x32_bf16 v[38:41], v[158:161], v[174:177], v[38:41]
	v_mfma_f32_16x16x32_bf16 v[30:33], v[150:153], v[184:187], v[30:33]
	v_mfma_f32_16x16x32_bf16 v[22:25], v[158:161], v[184:187], v[22:25]
	v_mfma_f32_16x16x32_bf16 v[14:17], v[150:153], v[192:195], v[14:17]
	v_mfma_f32_16x16x32_bf16 v[6:9], v[158:161], v[192:195], v[6:9]
	s_barrier
	s_add_u32 s14, s14, 0x40080
	s_addc_u32 s15, s15, 0
	s_add_i32 s16, s16, s25
	v_lshl_add_u64 v[142:143], s[14:15], 0, v[134:135]
	s_mov_b32 m0, s16
	s_nop 0
	global_load_lds_dwordx4 v[142:143], off
	v_lshl_add_u64 v[142:143], s[14:15], 0, v[130:131]
	s_add_i32 m0, s16, 0x2000
	s_nop 0
	global_load_lds_dwordx4 v[142:143], off
	s_add_i32 s66, s66, 2
	s_add_u32 s12, s12, 0x100
	s_addc_u32 s13, s13, 0
	s_add_u32 s7, s7, 0x100
	s_addc_u32 s65, s65, 0
	s_add_i32 s26, 0, 0x10000
	v_add_u32_e32 v149, s26, v147
	s_cmp_gt_u32 s66, 13
	s_waitcnt vmcnt(6)
	s_barrier
; __device__ __forceinline__ unsigned cvt_pk_bf16(float lo, float hi) { unsigned r; asm("v_cvt_pk_bf16_f32 %0, %1, %2" : "=v"(r) : "v"(lo), "v"(hi)); return r; }
;     __device__ __forceinline__ void operator()(const AccT& acc, const Unit& u, int wr, int wc, int fr, int fq) const {
;     ...
;         const int gpm = mapA.src(u.pm);
;         const int row0 = gpm * 256 + wr * 64 + fr, col0 = u.pn * 128 + wc * 32 + 8 * fq;
; #pragma unroll
;         for (int ai = 0; ai < 2; ++ai)
; #pragma unroll
;             for (int m = 0; m < 4; ++m) { bf16_t* rowp = U + (size_t)(row0 + ai * 128 + m * 16) * HID + col0;
;                 const f32x4 s0 = silu4(acc[ai][0][m][0]) * acc[ai][1][m][0], s1 = silu4(acc[ai][0][m][1]) * acc[ai][1][m][1];
;                 u32x4 w; w.x = cvt_pk_bf16(s0[0], s0[1]); w.y = cvt_pk_bf16(s0[2], s0[3]); w.z = cvt_pk_bf16(s1[0], s1[1]); w.w = cvt_pk_bf16(s1[2], s1[3]);
;                 *(u32x4*)rowp = w; }
	v_mfma_f32_16x16x32_bf16 v[58:61], v[196:199], v[162:165], v[58:61]
	v_mfma_f32_16x16x32_bf16 v[50:53], v[204:207], v[162:165], v[50:53]
	v_mfma_f32_16x16x32_bf16 v[42:45], v[196:199], v[170:173], v[42:45]
	v_mfma_f32_16x16x32_bf16 v[34:37], v[204:207], v[170:173], v[34:37]
	v_mfma_f32_16x16x32_bf16 v[26:29], v[196:199], v[180:183], v[26:29]
	v_mfma_f32_16x16x32_bf16 v[18:21], v[204:207], v[180:183], v[18:21]
	v_mfma_f32_16x16x32_bf16 v[10:13], v[196:199], v[188:191], v[10:13]
	v_mfma_f32_16x16x32_bf16 v[2:5], v[204:207], v[188:191], v[2:5]
	v_mfma_f32_16x16x32_bf16 v[58:61], v[200:203], v[166:169], v[58:61]
	v_mfma_f32_16x16x32_bf16 v[50:53], v[226:229], v[166:169], v[50:53]
	v_mfma_f32_16x16x32_bf16 v[42:45], v[200:203], v[174:177], v[42:45]
	v_mfma_f32_16x16x32_bf16 v[34:37], v[226:229], v[174:177], v[34:37]
	v_mfma_f32_16x16x32_bf16 v[26:29], v[200:203], v[184:187], v[26:29]
	v_mfma_f32_16x16x32_bf16 v[18:21], v[226:229], v[184:187], v[18:21]
	v_mfma_f32_16x16x32_bf16 v[10:13], v[200:203], v[192:195], v[10:13]
	v_mfma_f32_16x16x32_bf16 v[2:5], v[226:229], v[192:195], v[2:5]
	s_barrier
	s_cbranch_scc0 .LBB0_525
	v_mul_f32_e32 v152, 0xbfb8aa3b, v126
	v_mul_f32_e32 v153, 0xbfb8aa3b, v127
	v_mul_f32_e32 v154, 0xbfb8aa3b, v128
	v_mul_f32_e32 v155, 0xbfb8aa3b, v129
	v_exp_f32_e32 v152, v152
	v_exp_f32_e32 v153, v153
	v_exp_f32_e32 v154, v154
	v_exp_f32_e32 v155, v155
	v_add_f32_e32 v152, 1.0, v152
	v_add_f32_e32 v153, 1.0, v153
	v_add_f32_e32 v154, 1.0, v154
	v_add_f32_e32 v155, 1.0, v155
	v_rcp_f32_e32 v152, v152
	v_rcp_f32_e32 v153, v153
	v_rcp_f32_e32 v154, v154
	v_rcp_f32_e32 v155, v155
	v_readlane_b32 s7, v255, 27
	v_pk_mul_f32 v[126:127], v[126:127], v[152:153]
	s_cmp_ge_i32 s64, s7
	v_pk_mul_f32 v[128:129], v[128:129], v[154:155]
	v_pk_mul_f32 v[122:123], v[126:127], v[122:123]
	v_pk_mul_f32 v[124:125], v[128:129], v[124:125]
	v_mul_f32_e32 v126, 0xbfb8aa3b, v118
	v_mul_f32_e32 v127, 0xbfb8aa3b, v119
	v_mul_f32_e32 v128, 0xbfb8aa3b, v120
	v_mul_f32_e32 v129, 0xbfb8aa3b, v121
	v_exp_f32_e32 v126, v126
	v_exp_f32_e32 v127, v127
	v_exp_f32_e32 v128, v128
	v_exp_f32_e32 v129, v129
	v_add_f32_e32 v126, 1.0, v126
	v_add_f32_e32 v127, 1.0, v127
	v_add_f32_e32 v128, 1.0, v128
	v_add_f32_e32 v129, 1.0, v129
	s_cselect_b32 s7, s31, 0
	v_rcp_f32_e32 v126, v126
	v_rcp_f32_e32 v127, v127
	v_rcp_f32_e32 v128, v128
	v_rcp_f32_e32 v129, v129
	s_add_i32 s7, s64, s7
	s_lshl_b32 s10, s10, 7
	v_mov_b32_e32 v142, v146
	v_mov_b32_e32 v143, v1
	s_lshl_b32 s7, s7, 8
	s_or_b32 s10, s10, s53
	s_add_i32 s7, s7, s52
	v_lshl_add_u32 v144, v143, 3, s10
	v_add_u32_e32 v149, s7, v142
	v_ashrrev_i32_e32 v145, 31, v144
	v_mov_b64_e32 v[142:143], s[34:35]
	s_movk_i32 s7, 0x1600
	v_pk_mul_f32 v[118:119], v[118:119], v[126:127]
	v_pk_mul_f32 v[120:121], v[120:121], v[128:129]
	v_mad_i64_i32 v[150:151], s[12:13], v149, s7, v[142:143]
	v_lshlrev_b64 v[144:145], 1, v[144:145]
	v_pk_mul_f32 v[120:121], v[120:121], v[116:117]
	v_pk_mul_f32 v[116:117], v[118:119], v[114:115]
	v_lshl_add_u64 v[150:151], v[150:151], 0, v[144:145]
	v_cvt_pk_bf16_f32 v116, v116, v117
	v_cvt_pk_bf16_f32 v117, v120, v121
	v_cvt_pk_bf16_f32 v114, v122, v123
	v_cvt_pk_bf16_f32 v115, v124, v125
	global_store_dwordx4 v[150:151], v[114:117], off
	v_mul_f32_e32 v118, 0xbfb8aa3b, v112
	v_mul_f32_e32 v119, 0xbfb8aa3b, v113
	v_mul_f32_e32 v116, 0xbfb8aa3b, v110
	v_mul_f32_e32 v117, 0xbfb8aa3b, v111
	v_exp_f32_e32 v116, v116
	v_exp_f32_e32 v117, v117
	v_exp_f32_e32 v118, v118
	v_exp_f32_e32 v119, v119
	v_add_f32_e32 v116, 1.0, v116
	v_add_f32_e32 v117, 1.0, v117
	v_add_f32_e32 v118, 1.0, v118
	v_add_f32_e32 v119, 1.0, v119
	v_rcp_f32_e32 v116, v116
	v_rcp_f32_e32 v117, v117
	v_rcp_f32_e32 v118, v118
	v_rcp_f32_e32 v119, v119
	v_add_u32_e32 v114, 16, v149
	v_pk_mul_f32 v[110:111], v[110:111], v[116:117]
	v_mad_i64_i32 v[114:115], s[12:13], v114, s7, v[142:143]
	v_pk_mul_f32 v[112:113], v[112:113], v[118:119]
	v_pk_mul_f32 v[106:107], v[110:111], v[106:107]
	v_pk_mul_f32 v[108:109], v[112:113], v[108:109]
	v_mul_f32_e32 v110, 0xbfb8aa3b, v102
	v_mul_f32_e32 v111, 0xbfb8aa3b, v103
	v_mul_f32_e32 v112, 0xbfb8aa3b, v104
	v_mul_f32_e32 v113, 0xbfb8aa3b, v105
	v_exp_f32_e32 v110, v110
	v_exp_f32_e32 v111, v111
	v_exp_f32_e32 v112, v112
	v_exp_f32_e32 v113, v113
	v_add_f32_e32 v110, 1.0, v110
	v_add_f32_e32 v111, 1.0, v111
	v_add_f32_e32 v112, 1.0, v112
	v_add_f32_e32 v113, 1.0, v113
	v_rcp_f32_e32 v110, v110
	v_rcp_f32_e32 v111, v111
	v_rcp_f32_e32 v112, v112
	v_rcp_f32_e32 v113, v113
	v_lshl_add_u64 v[114:115], v[114:115], 0, v[144:145]
	v_pk_mul_f32 v[102:103], v[102:103], v[110:111]
	s_and_b64 vcc, exec, s[2:3]
	v_pk_mul_f32 v[104:105], v[104:105], v[112:113]
	s_mov_b32 s10, s6
	v_pk_mul_f32 v[104:105], v[104:105], v[100:101]
	v_pk_mul_f32 v[100:101], v[102:103], v[98:99]
	v_cvt_pk_bf16_f32 v98, v106, v107
	v_cvt_pk_bf16_f32 v99, v108, v109
	v_mul_f32_e32 v102, 0xbfb8aa3b, v96
	v_cvt_pk_bf16_f32 v100, v100, v101
	v_cvt_pk_bf16_f32 v101, v104, v105
	global_store_dwordx4 v[114:115], v[98:101], off
	v_mul_f32_e32 v103, 0xbfb8aa3b, v97
	v_exp_f32_e32 v102, v102
	v_mul_f32_e32 v100, 0xbfb8aa3b, v94
	v_mul_f32_e32 v101, 0xbfb8aa3b, v95
	v_exp_f32_e32 v100, v100
	v_exp_f32_e32 v101, v101
	v_exp_f32_e32 v103, v103
	v_add_f32_e32 v102, 1.0, v102
	v_add_f32_e32 v100, 1.0, v100
	v_add_f32_e32 v101, 1.0, v101
	v_add_f32_e32 v103, 1.0, v103
	v_rcp_f32_e32 v100, v100
	v_rcp_f32_e32 v101, v101
	v_rcp_f32_e32 v102, v102
	v_rcp_f32_e32 v103, v103
	v_add_u32_e32 v98, 32, v149
	v_pk_mul_f32 v[94:95], v[94:95], v[100:101]
	v_mad_i64_i32 v[98:99], s[12:13], v98, s7, v[142:143]
	v_pk_mul_f32 v[96:97], v[96:97], v[102:103]
; __device__ __forceinline__ unsigned cvt_pk_bf16(float lo, float hi) { unsigned r; asm("v_cvt_pk_bf16_f32 %0, %1, %2" : "=v"(r) : "v"(lo), "v"(hi)); return r; }
;     __device__ __forceinline__ void operator()(const AccT& acc, const Unit& u, int wr, int wc, int fr, int fq) const {
;     ...
;         for (int ai = 0; ai < 2; ++ai)
; #pragma unroll
;             for (int m = 0; m < 4; ++m) { bf16_t* rowp = U + (size_t)(row0 + ai * 128 + m * 16) * HID + col0;
;                 const f32x4 s0 = silu4(acc[ai][0][m][0]) * acc[ai][1][m][0], s1 = silu4(acc[ai][0][m][1]) * acc[ai][1][m][1];
;                 u32x4 w; w.x = cvt_pk_bf16(s0[0], s0[1]); w.y = cvt_pk_bf16(s0[2], s0[3]); w.z = cvt_pk_bf16(s1[0], s1[1]); w.w = cvt_pk_bf16(s1[2], s1[3]);
;                 *(u32x4*)rowp = w; }
	v_pk_mul_f32 v[90:91], v[94:95], v[90:91]
	v_pk_mul_f32 v[92:93], v[96:97], v[92:93]
	v_mul_f32_e32 v94, 0xbfb8aa3b, v86
	v_mul_f32_e32 v95, 0xbfb8aa3b, v87
	v_mul_f32_e32 v96, 0xbfb8aa3b, v88
	v_mul_f32_e32 v97, 0xbfb8aa3b, v89
	v_exp_f32_e32 v94, v94
	v_exp_f32_e32 v95, v95
	v_exp_f32_e32 v96, v96
	v_exp_f32_e32 v97, v97
	v_add_f32_e32 v94, 1.0, v94
	v_add_f32_e32 v95, 1.0, v95
	v_add_f32_e32 v96, 1.0, v96
	v_add_f32_e32 v97, 1.0, v97
	v_rcp_f32_e32 v94, v94
	v_rcp_f32_e32 v95, v95
	v_rcp_f32_e32 v96, v96
	v_rcp_f32_e32 v97, v97
	v_lshl_add_u64 v[98:99], v[98:99], 0, v[144:145]
	v_pk_mul_f32 v[86:87], v[86:87], v[94:95]
	s_mov_b32 s64, s61
	v_pk_mul_f32 v[88:89], v[88:89], v[96:97]
	s_mov_b64 s[14:15], s[4:5]
	v_pk_mul_f32 v[88:89], v[88:89], v[84:85]
	v_pk_mul_f32 v[84:85], v[86:87], v[82:83]
	v_cvt_pk_bf16_f32 v82, v90, v91
	v_cvt_pk_bf16_f32 v83, v92, v93
	v_mul_f32_e32 v86, 0xbfb8aa3b, v80
	v_cvt_pk_bf16_f32 v84, v84, v85
	v_cvt_pk_bf16_f32 v85, v88, v89
	global_store_dwordx4 v[98:99], v[82:85], off
	v_mul_f32_e32 v87, 0xbfb8aa3b, v81
	v_exp_f32_e32 v86, v86
	v_mul_f32_e32 v84, 0xbfb8aa3b, v78
	v_mul_f32_e32 v85, 0xbfb8aa3b, v79
	v_exp_f32_e32 v84, v84
	v_exp_f32_e32 v85, v85
	v_exp_f32_e32 v87, v87
	v_add_f32_e32 v86, 1.0, v86
	v_add_f32_e32 v84, 1.0, v84
	v_add_f32_e32 v85, 1.0, v85
	v_add_f32_e32 v87, 1.0, v87
	v_rcp_f32_e32 v84, v84
	v_rcp_f32_e32 v85, v85
	v_rcp_f32_e32 v86, v86
	v_rcp_f32_e32 v87, v87
	v_add_u32_e32 v82, 48, v149
	v_pk_mul_f32 v[78:79], v[78:79], v[84:85]
	v_mad_i64_i32 v[82:83], s[12:13], v82, s7, v[142:143]
	v_pk_mul_f32 v[80:81], v[80:81], v[86:87]
	v_pk_mul_f32 v[74:75], v[78:79], v[74:75]
	v_pk_mul_f32 v[76:77], v[80:81], v[76:77]
	v_mul_f32_e32 v78, 0xbfb8aa3b, v70
	v_mul_f32_e32 v79, 0xbfb8aa3b, v71
	v_mul_f32_e32 v80, 0xbfb8aa3b, v72
	v_mul_f32_e32 v81, 0xbfb8aa3b, v73
	v_exp_f32_e32 v78, v78
	v_exp_f32_e32 v79, v79
	v_exp_f32_e32 v80, v80
	v_exp_f32_e32 v81, v81
	v_add_f32_e32 v78, 1.0, v78
	v_add_f32_e32 v79, 1.0, v79
	v_add_f32_e32 v80, 1.0, v80
	v_add_f32_e32 v81, 1.0, v81
	v_rcp_f32_e32 v78, v78
	v_rcp_f32_e32 v79, v79
	v_rcp_f32_e32 v80, v80
	v_rcp_f32_e32 v81, v81
	v_lshl_add_u64 v[82:83], v[82:83], 0, v[144:145]
	v_pk_mul_f32 v[70:71], v[70:71], v[78:79]
	s_mov_b64 s[68:69], 0x1000
	v_pk_mul_f32 v[72:73], v[72:73], v[80:81]
	s_nop 0
	v_pk_mul_f32 v[72:73], v[72:73], v[68:69]
	v_pk_mul_f32 v[68:69], v[70:71], v[66:67]
	v_cvt_pk_bf16_f32 v66, v74, v75
	v_cvt_pk_bf16_f32 v67, v76, v77
	v_mul_f32_e32 v70, 0xbfb8aa3b, v64
	v_cvt_pk_bf16_f32 v68, v68, v69
	v_cvt_pk_bf16_f32 v69, v72, v73
	global_store_dwordx4 v[82:83], v[66:69], off
	v_mul_f32_e32 v71, 0xbfb8aa3b, v65
	v_exp_f32_e32 v70, v70
	v_mul_f32_e32 v68, 0xbfb8aa3b, v62
	v_mul_f32_e32 v69, 0xbfb8aa3b, v63
	v_exp_f32_e32 v68, v68
	v_exp_f32_e32 v69, v69
	v_exp_f32_e32 v71, v71
	v_add_f32_e32 v70, 1.0, v70
	v_add_f32_e32 v68, 1.0, v68
	v_add_f32_e32 v69, 1.0, v69
	v_add_f32_e32 v71, 1.0, v71
	v_rcp_f32_e32 v68, v68
	v_rcp_f32_e32 v69, v69
	v_rcp_f32_e32 v70, v70
	v_rcp_f32_e32 v71, v71
	v_add_u32_e32 v66, 0x80, v149
	v_pk_mul_f32 v[62:63], v[62:63], v[68:69]
	v_mad_i64_i32 v[66:67], s[12:13], v66, s7, v[142:143]
	v_pk_mul_f32 v[64:65], v[64:65], v[70:71]
	v_pk_mul_f32 v[58:59], v[62:63], v[58:59]
	v_pk_mul_f32 v[60:61], v[64:65], v[60:61]
	v_mul_f32_e32 v62, 0xbfb8aa3b, v54
	v_mul_f32_e32 v63, 0xbfb8aa3b, v55
	v_mul_f32_e32 v64, 0xbfb8aa3b, v56
	v_mul_f32_e32 v65, 0xbfb8aa3b, v57
	v_exp_f32_e32 v62, v62
	v_exp_f32_e32 v63, v63
	v_exp_f32_e32 v64, v64
	v_exp_f32_e32 v65, v65
	v_add_f32_e32 v62, 1.0, v62
	v_add_f32_e32 v63, 1.0, v63
	v_add_f32_e32 v64, 1.0, v64
	v_add_f32_e32 v65, 1.0, v65
	v_rcp_f32_e32 v62, v62
	v_rcp_f32_e32 v63, v63
	v_rcp_f32_e32 v64, v64
	v_rcp_f32_e32 v65, v65
	v_lshl_add_u64 v[66:67], v[66:67], 0, v[144:145]
	v_pk_mul_f32 v[54:55], v[54:55], v[62:63]
	v_pk_mul_f32 v[56:57], v[56:57], v[64:65]
	s_nop 0
	v_pk_mul_f32 v[56:57], v[56:57], v[52:53]
	v_pk_mul_f32 v[52:53], v[54:55], v[50:51]
	v_cvt_pk_bf16_f32 v50, v58, v59
	v_cvt_pk_bf16_f32 v51, v60, v61
	v_mul_f32_e32 v54, 0xbfb8aa3b, v48
	v_cvt_pk_bf16_f32 v52, v52, v53
	v_cvt_pk_bf16_f32 v53, v56, v57
	global_store_dwordx4 v[66:67], v[50:53], off
	v_mul_f32_e32 v55, 0xbfb8aa3b, v49
	v_exp_f32_e32 v54, v54
	v_mul_f32_e32 v52, 0xbfb8aa3b, v46
	v_mul_f32_e32 v53, 0xbfb8aa3b, v47
	v_exp_f32_e32 v52, v52
	v_exp_f32_e32 v53, v53
	v_exp_f32_e32 v55, v55
	v_add_f32_e32 v54, 1.0, v54
	v_add_f32_e32 v52, 1.0, v52
	v_add_f32_e32 v53, 1.0, v53
; __device__ __forceinline__ unsigned cvt_pk_bf16(float lo, float hi) { unsigned r; asm("v_cvt_pk_bf16_f32 %0, %1, %2" : "=v"(r) : "v"(lo), "v"(hi)); return r; }
;     __device__ __forceinline__ void operator()(const AccT& acc, const Unit& u, int wr, int wc, int fr, int fq) const {
;     ...
;         for (int ai = 0; ai < 2; ++ai)
; #pragma unroll
;             for (int m = 0; m < 4; ++m) { bf16_t* rowp = U + (size_t)(row0 + ai * 128 + m * 16) * HID + col0;
;                 const f32x4 s0 = silu4(acc[ai][0][m][0]) * acc[ai][1][m][0], s1 = silu4(acc[ai][0][m][1]) * acc[ai][1][m][1];
;                 u32x4 w; w.x = cvt_pk_bf16(s0[0], s0[1]); w.y = cvt_pk_bf16(s0[2], s0[3]); w.z = cvt_pk_bf16(s1[0], s1[1]); w.w = cvt_pk_bf16(s1[2], s1[3]);
;                 *(u32x4*)rowp = w; }
	v_add_f32_e32 v55, 1.0, v55
	v_rcp_f32_e32 v52, v52
	v_rcp_f32_e32 v53, v53
	v_rcp_f32_e32 v54, v54
	v_rcp_f32_e32 v55, v55
	v_add_u32_e32 v50, 0x90, v149
	v_pk_mul_f32 v[46:47], v[46:47], v[52:53]
	v_mad_i64_i32 v[50:51], s[12:13], v50, s7, v[142:143]
	v_pk_mul_f32 v[48:49], v[48:49], v[54:55]
	v_pk_mul_f32 v[42:43], v[46:47], v[42:43]
	v_pk_mul_f32 v[44:45], v[48:49], v[44:45]
	v_mul_f32_e32 v46, 0xbfb8aa3b, v38
	v_mul_f32_e32 v47, 0xbfb8aa3b, v39
	v_mul_f32_e32 v48, 0xbfb8aa3b, v40
	v_mul_f32_e32 v49, 0xbfb8aa3b, v41
	v_exp_f32_e32 v46, v46
	v_exp_f32_e32 v47, v47
	v_exp_f32_e32 v48, v48
	v_exp_f32_e32 v49, v49
	v_add_f32_e32 v46, 1.0, v46
	v_add_f32_e32 v47, 1.0, v47
	v_add_f32_e32 v48, 1.0, v48
	v_add_f32_e32 v49, 1.0, v49
	v_rcp_f32_e32 v46, v46
	v_rcp_f32_e32 v47, v47
	v_rcp_f32_e32 v48, v48
	v_rcp_f32_e32 v49, v49
	v_lshl_add_u64 v[50:51], v[50:51], 0, v[144:145]
	v_pk_mul_f32 v[38:39], v[38:39], v[46:47]
	v_pk_mul_f32 v[40:41], v[40:41], v[48:49]
	s_nop 0
	v_pk_mul_f32 v[40:41], v[40:41], v[36:37]
	v_pk_mul_f32 v[36:37], v[38:39], v[34:35]
	v_cvt_pk_bf16_f32 v34, v42, v43
	v_cvt_pk_bf16_f32 v35, v44, v45
	v_mul_f32_e32 v38, 0xbfb8aa3b, v32
	v_cvt_pk_bf16_f32 v36, v36, v37
	v_cvt_pk_bf16_f32 v37, v40, v41
	global_store_dwordx4 v[50:51], v[34:37], off
	v_mul_f32_e32 v39, 0xbfb8aa3b, v33
	v_exp_f32_e32 v38, v38
	v_mul_f32_e32 v36, 0xbfb8aa3b, v30
	v_mul_f32_e32 v37, 0xbfb8aa3b, v31
	v_exp_f32_e32 v36, v36
	v_exp_f32_e32 v37, v37
	v_exp_f32_e32 v39, v39
	v_add_f32_e32 v38, 1.0, v38
	v_add_f32_e32 v36, 1.0, v36
	v_add_f32_e32 v37, 1.0, v37
	v_add_f32_e32 v39, 1.0, v39
	v_rcp_f32_e32 v36, v36
	v_rcp_f32_e32 v37, v37
	v_rcp_f32_e32 v38, v38
	v_rcp_f32_e32 v39, v39
	v_add_u32_e32 v34, 0xa0, v149
	v_pk_mul_f32 v[30:31], v[30:31], v[36:37]
	v_mad_i64_i32 v[34:35], s[12:13], v34, s7, v[142:143]
	v_pk_mul_f32 v[32:33], v[32:33], v[38:39]
	v_pk_mul_f32 v[26:27], v[30:31], v[26:27]
	v_pk_mul_f32 v[28:29], v[32:33], v[28:29]
	v_mul_f32_e32 v30, 0xbfb8aa3b, v22
	v_mul_f32_e32 v31, 0xbfb8aa3b, v23
	v_mul_f32_e32 v32, 0xbfb8aa3b, v24
	v_mul_f32_e32 v33, 0xbfb8aa3b, v25
	v_exp_f32_e32 v30, v30
	v_exp_f32_e32 v31, v31
	v_exp_f32_e32 v32, v32
	v_exp_f32_e32 v33, v33
	v_add_f32_e32 v30, 1.0, v30
	v_add_f32_e32 v31, 1.0, v31
	v_add_f32_e32 v32, 1.0, v32
	v_add_f32_e32 v33, 1.0, v33
	v_rcp_f32_e32 v30, v30
	v_rcp_f32_e32 v31, v31
	v_rcp_f32_e32 v32, v32
	v_rcp_f32_e32 v33, v33
	v_lshl_add_u64 v[34:35], v[34:35], 0, v[144:145]
	v_pk_mul_f32 v[22:23], v[22:23], v[30:31]
	v_pk_mul_f32 v[24:25], v[24:25], v[32:33]
	s_nop 0
	v_pk_mul_f32 v[24:25], v[24:25], v[20:21]
	v_pk_mul_f32 v[20:21], v[22:23], v[18:19]
	v_cvt_pk_bf16_f32 v18, v26, v27
	v_cvt_pk_bf16_f32 v19, v28, v29
	v_mul_f32_e32 v22, 0xbfb8aa3b, v16
	v_cvt_pk_bf16_f32 v20, v20, v21
	v_cvt_pk_bf16_f32 v21, v24, v25
	global_store_dwordx4 v[34:35], v[18:21], off
	v_mul_f32_e32 v23, 0xbfb8aa3b, v17
	v_exp_f32_e32 v22, v22
	v_mul_f32_e32 v20, 0xbfb8aa3b, v14
	v_mul_f32_e32 v21, 0xbfb8aa3b, v15
	v_exp_f32_e32 v20, v20
	v_exp_f32_e32 v21, v21
	v_exp_f32_e32 v23, v23
	v_add_f32_e32 v22, 1.0, v22
	v_add_f32_e32 v20, 1.0, v20
	v_add_f32_e32 v21, 1.0, v21
	v_add_f32_e32 v23, 1.0, v23
	v_rcp_f32_e32 v20, v20
	v_rcp_f32_e32 v21, v21
	v_rcp_f32_e32 v22, v22
	v_rcp_f32_e32 v23, v23
	v_add_u32_e32 v18, 0xb0, v149
	v_pk_mul_f32 v[14:15], v[14:15], v[20:21]
	v_mad_i64_i32 v[18:19], s[12:13], v18, s7, v[142:143]
	v_pk_mul_f32 v[16:17], v[16:17], v[22:23]
	v_pk_mul_f32 v[10:11], v[14:15], v[10:11]
	v_pk_mul_f32 v[12:13], v[16:17], v[12:13]
	v_mul_f32_e32 v14, 0xbfb8aa3b, v6
	v_mul_f32_e32 v15, 0xbfb8aa3b, v7
	v_mul_f32_e32 v16, 0xbfb8aa3b, v8
	v_mul_f32_e32 v17, 0xbfb8aa3b, v9
	v_exp_f32_e32 v14, v14
	v_exp_f32_e32 v15, v15
	v_exp_f32_e32 v16, v16
	v_exp_f32_e32 v17, v17
	v_add_f32_e32 v14, 1.0, v14
	v_add_f32_e32 v15, 1.0, v15
	v_add_f32_e32 v16, 1.0, v16
	v_add_f32_e32 v17, 1.0, v17
	v_rcp_f32_e32 v14, v14
	v_rcp_f32_e32 v15, v15
	v_rcp_f32_e32 v16, v16
	v_rcp_f32_e32 v17, v17
	v_lshl_add_u64 v[18:19], v[18:19], 0, v[144:145]
	v_pk_mul_f32 v[6:7], v[6:7], v[14:15]
	s_mov_b64 s[12:13], s[8:9]
	v_pk_mul_f32 v[8:9], v[8:9], v[16:17]
	s_nop 0
	v_pk_mul_f32 v[8:9], v[8:9], v[4:5]
	v_pk_mul_f32 v[4:5], v[6:7], v[2:3]
	v_cvt_pk_bf16_f32 v2, v10, v11
	v_cvt_pk_bf16_f32 v3, v12, v13
	s_nop 0
	v_cvt_pk_bf16_f32 v4, v4, v5
	v_cvt_pk_bf16_f32 v5, v8, v9
	global_store_dwordx4 v[18:19], v[2:5], off
	s_cbranch_vccz .LBB0_520
	s_waitcnt vmcnt(0)
	s_cmpk_gt_u32 s1, 0xff
	s_cbranch_scc1 .LBB0_529
	s_barrier

; #define PG8_STAGE(bufoff, gbase, voff) do { _Pragma("unroll") for (int _i = 0; _i < 2; ++_i) \
;         __builtin_amdgcn_global_load_lds((const unsigned*)((const char*)(gbase) + (voff)[_i]), (LAS unsigned*)(lds + (bufoff) + ldsw + _i * 8192), 16, 0, 0); } while (0)
; #define PG8_LDA(dst, b, h) do { _Pragma("unroll") for (int m = 0; m < 4; ++m) _Pragma("unroll") for (int k = 0; k < 2; ++k) dst[m][k] = *(const LAS bf16x8*)(lds + PG8_SA(b, h) + aoff + m * 2048 + k * 1024); } while (0)
; #define PG8_LDB(dst, b, h) do { _Pragma("unroll") for (int n = 0; n < 2; ++n) _Pragma("unroll") for (int k = 0; k < 2; ++k) dst[n][k] = *(const LAS bf16x8*)(lds + PG8_SB(b, h) + boff + n * 2048 + k * 1024); } while (0)
; #define PG8_MMA(ai, bj, At, Bt) do { __builtin_amdgcn_s_setprio(1); _Pragma("unroll") for (int m = 0; m < 4; ++m) _Pragma("unroll") for (int n = 0; n < 2; ++n) _Pragma("unroll") for (int k = 0; k < 2; ++k) \
;         acc[ai][bj][m][n] = __builtin_amdgcn_mfma_f32_16x16x32_bf16(Bt[n][k], At[m][k], acc[ai][bj][m][n], 0, 0, 0); __builtin_amdgcn_s_setprio(0); } while (0)
; #define PG8_WAIT_L(n) asm volatile("s_waitcnt lgkmcnt(" #n ")" ::: "memory")
; #define PG8_BAR __builtin_amdgcn_s_barrier()
; #define PG8_SCHED __builtin_amdgcn_sched_barrier(0)
; template <class Epi>
; __device__ __forceinline__ void gemm_phase(LAS unsigned char* lds, const Gemm g, const Epi& E) {
;     ...
;             PG8_LDB(B0, 0, 0); PG8_SCHED; PG8_LDA(At, 0, 0); PG8_STAGE(PG8_SA(1, 1), a1 + hstepA, voffA);
;             PG8_WAIT_L(8); PG8_BAR; PG8_WAIT_L(0); PG8_MMA(0, 0, At, B0); PG8_BAR; PG8_SCHED;
;             PG8_LDB(B1, 0, 1); PG8_STAGE(PG8_SB(0, 0), b2, voffB);
;             PG8_BAR; PG8_WAIT_L(0); PG8_MMA(0, 1, At, B1); PG8_BAR;
;     ...
;         for (int a = 0; a < 2; ++a)
; #pragma unroll
;             for (int b = 0; b < 2; ++b)
; #pragma unroll
;                 for (int m = 0; m < 4; ++m)
; #pragma unroll
;                     for (int n = 0; n < 2; ++n) acc[a][b][m][n] = (f32x4){0.f, 0.f, 0.f, 0.f};
.LBB0_546:
	s_add_u32 s65, s10, 0x100
	v_mov_b32_e32 v2, 0
	s_addc_u32 s66, s11, 0
	s_mov_b32 s67, -2
	v_mov_b32_e32 v3, v2
	v_mov_b64_e32 v[4:5], v[2:3]
	v_mov_b64_e32 v[6:7], v[2:3]
	v_mov_b64_e32 v[8:9], v[2:3]
	v_mov_b64_e32 v[10:11], v[2:3]
	v_mov_b64_e32 v[12:13], v[2:3]
	v_mov_b64_e32 v[14:15], v[2:3]
	v_mov_b64_e32 v[16:17], v[2:3]
	v_mov_b64_e32 v[18:19], v[2:3]
	v_mov_b64_e32 v[20:21], v[2:3]
	v_mov_b64_e32 v[22:23], v[2:3]
	v_mov_b64_e32 v[24:25], v[2:3]
	v_mov_b64_e32 v[26:27], v[2:3]
	v_mov_b64_e32 v[28:29], v[2:3]
	v_mov_b64_e32 v[30:31], v[2:3]
	v_mov_b64_e32 v[32:33], v[2:3]
	v_mov_b64_e32 v[34:35], v[2:3]
	v_mov_b64_e32 v[36:37], v[2:3]
	v_mov_b64_e32 v[38:39], v[2:3]
	v_mov_b64_e32 v[40:41], v[2:3]
	v_mov_b64_e32 v[42:43], v[2:3]
	v_mov_b64_e32 v[44:45], v[2:3]
	v_mov_b64_e32 v[46:47], v[2:3]
	v_mov_b64_e32 v[48:49], v[2:3]
	v_mov_b64_e32 v[50:51], v[2:3]
	v_mov_b64_e32 v[52:53], v[2:3]
	v_mov_b64_e32 v[54:55], v[2:3]
	v_mov_b64_e32 v[56:57], v[2:3]
	v_mov_b64_e32 v[58:59], v[2:3]
	v_mov_b64_e32 v[60:61], v[2:3]
	v_mov_b64_e32 v[62:63], v[2:3]
	v_mov_b64_e32 v[64:65], v[2:3]
	v_mov_b64_e32 v[66:67], v[2:3]
	v_mov_b64_e32 v[68:69], v[2:3]
	v_mov_b64_e32 v[70:71], v[2:3]
	v_mov_b64_e32 v[72:73], v[2:3]
	v_mov_b64_e32 v[74:75], v[2:3]
	v_mov_b64_e32 v[76:77], v[2:3]
	v_mov_b64_e32 v[78:79], v[2:3]
	v_mov_b64_e32 v[80:81], v[2:3]
	v_mov_b64_e32 v[82:83], v[2:3]
	v_mov_b64_e32 v[84:85], v[2:3]
	v_mov_b64_e32 v[86:87], v[2:3]
	v_mov_b64_e32 v[88:89], v[2:3]
	v_mov_b64_e32 v[90:91], v[2:3]
	v_mov_b64_e32 v[92:93], v[2:3]
	v_mov_b64_e32 v[94:95], v[2:3]
	v_mov_b64_e32 v[96:97], v[2:3]
	v_mov_b64_e32 v[98:99], v[2:3]
	v_mov_b64_e32 v[100:101], v[2:3]
	v_mov_b64_e32 v[102:103], v[2:3]
	v_mov_b64_e32 v[104:105], v[2:3]
	v_mov_b64_e32 v[106:107], v[2:3]
	v_mov_b64_e32 v[108:109], v[2:3]
	v_mov_b64_e32 v[110:111], v[2:3]
	v_mov_b64_e32 v[112:113], v[2:3]
	v_mov_b64_e32 v[114:115], v[2:3]
	v_mov_b64_e32 v[116:117], v[2:3]
	v_mov_b64_e32 v[118:119], v[2:3]
	v_mov_b64_e32 v[120:121], v[2:3]
	v_mov_b64_e32 v[122:123], v[2:3]
	v_mov_b64_e32 v[124:125], v[2:3]
	v_mov_b64_e32 v[126:127], v[2:3]
	v_mov_b64_e32 v[128:129], v[2:3]
	s_add_i32 s26, 0, 0x10000
	v_add_u32_e32 v142, s26, v157
.LBB0_547:
	ds_read_b128 v[130:133], v142
	ds_read_b128 v[134:137], v142 offset:1024
	ds_read_b128 v[138:141], v142 offset:2048
	ds_read_b128 v[142:145], v142 offset:3072
	ds_read_b128 v[160:163], v158
	ds_read_b128 v[164:167], v158 offset:1024
	ds_read_b128 v[168:171], v158 offset:2048
	ds_read_b128 v[172:175], v158 offset:3072
	ds_read_b128 v[180:183], v158 offset:4096
	ds_read_b128 v[184:187], v158 offset:5120
	ds_read_b128 v[188:191], v158 offset:6144
	ds_read_b128 v[192:195], v158 offset:7168
	s_add_u32 s10, s8, 0x100
	s_addc_u32 s11, s9, 0
	s_cmp_eq_u32 s67, 40
	s_cselect_b32 s15, s5, s11
	s_cselect_b32 s14, s4, s10
	s_cselect_b32 s13, s7, s66
	s_cselect_b32 s12, s6, s65
	v_lshl_add_u64 v[154:155], s[8:9], 0, v[150:151]
	s_add_i32 m0, s29, 0xc000
	s_nop 0
	global_load_lds_dwordx4 v[154:155], off
	v_lshl_add_u64 v[154:155], s[8:9], 0, v[152:153]
	s_add_i32 m0, s29, 0xe000
	s_nop 0
	global_load_lds_dwordx4 v[154:155], off
	s_waitcnt lgkmcnt(8)
	s_barrier
	s_waitcnt lgkmcnt(0)
	v_mfma_f32_16x16x32_bf16 v[126:129], v[130:133], v[160:163], v[126:129]
	v_mfma_f32_16x16x32_bf16 v[122:125], v[138:141], v[160:163], v[122:125]
	v_mfma_f32_16x16x32_bf16 v[118:121], v[130:133], v[168:171], v[118:121]
	v_mfma_f32_16x16x32_bf16 v[110:113], v[138:141], v[168:171], v[110:113]
	v_mfma_f32_16x16x32_bf16 v[102:105], v[130:133], v[180:183], v[102:105]
	v_mfma_f32_16x16x32_bf16 v[94:97], v[138:141], v[180:183], v[94:97]
	v_mfma_f32_16x16x32_bf16 v[86:89], v[130:133], v[188:191], v[86:89]
	v_mfma_f32_16x16x32_bf16 v[78:81], v[138:141], v[188:191], v[78:81]
	v_mfma_f32_16x16x32_bf16 v[126:129], v[134:137], v[164:167], v[126:129]
	v_mfma_f32_16x16x32_bf16 v[122:125], v[142:145], v[164:167], v[122:125]
	v_mfma_f32_16x16x32_bf16 v[118:121], v[134:137], v[172:175], v[118:121]
	v_mfma_f32_16x16x32_bf16 v[110:113], v[142:145], v[172:175], v[110:113]
	v_mfma_f32_16x16x32_bf16 v[102:105], v[134:137], v[184:187], v[102:105]
	v_mfma_f32_16x16x32_bf16 v[94:97], v[142:145], v[184:187], v[94:97]
	v_mfma_f32_16x16x32_bf16 v[86:89], v[134:137], v[192:195], v[86:89]
	v_mfma_f32_16x16x32_bf16 v[78:81], v[142:145], v[192:195], v[78:81]
	s_barrier
	s_add_i32 s27, 0, 0x14000
	v_add_u32_e32 v154, s27, v157
	s_add_i32 s8, s26, s18
	ds_read_b128 v[196:199], v154
	ds_read_b128 v[200:203], v154 offset:1024
	ds_read_b128 v[204:207], v154 offset:2048
	ds_read_b128 v[226:229], v154 offset:3072
	v_lshl_add_u64 v[154:155], s[12:13], 0, v[148:149]
	s_mov_b32 m0, s8
	v_lshl_add_u64 v[176:177], s[12:13], 0, v[146:147]
	global_load_lds_dwordx4 v[154:155], off
	s_add_i32 m0, s8, 0x2000
	s_nop 0
	global_load_lds_dwordx4 v[176:177], off
	s_nop 1
	s_mov_b32 m0, s29
	v_lshl_add_u64 v[208:209], s[14:15], 0, v[148:149]
	s_barrier
	s_waitcnt lgkmcnt(0)
	v_mfma_f32_16x16x32_bf16 v[114:117], v[196:199], v[160:163], v[114:117]
	v_mfma_f32_16x16x32_bf16 v[106:109], v[204:207], v[160:163], v[106:109]
	v_mfma_f32_16x16x32_bf16 v[98:101], v[196:199], v[168:171], v[98:101]
	v_mfma_f32_16x16x32_bf16 v[90:93], v[204:207], v[168:171], v[90:93]
	v_mfma_f32_16x16x32_bf16 v[82:85], v[196:199], v[180:183], v[82:85]
	v_mfma_f32_16x16x32_bf16 v[74:77], v[204:207], v[180:183], v[74:77]
	v_mfma_f32_16x16x32_bf16 v[70:73], v[196:199], v[188:191], v[70:73]
	v_mfma_f32_16x16x32_bf16 v[66:69], v[204:207], v[188:191], v[66:69]
	v_mfma_f32_16x16x32_bf16 v[114:117], v[200:203], v[164:167], v[114:117]
	v_mfma_f32_16x16x32_bf16 v[106:109], v[226:229], v[164:167], v[106:109]
	v_mfma_f32_16x16x32_bf16 v[98:101], v[200:203], v[172:175], v[98:101]
	v_mfma_f32_16x16x32_bf16 v[90:93], v[226:229], v[172:175], v[90:93]
	v_mfma_f32_16x16x32_bf16 v[82:85], v[200:203], v[184:187], v[82:85]
	v_mfma_f32_16x16x32_bf16 v[74:77], v[226:229], v[184:187], v[74:77]
	v_mfma_f32_16x16x32_bf16 v[70:73], v[200:203], v[192:195], v[70:73]
	v_mfma_f32_16x16x32_bf16 v[66:69], v[226:229], v[192:195], v[66:69]
	s_barrier
; #define PG8_STAGE(bufoff, gbase, voff) do { _Pragma("unroll") for (int _i = 0; _i < 2; ++_i) \
;         __builtin_amdgcn_global_load_lds((const unsigned*)((const char*)(gbase) + (voff)[_i]), (LAS unsigned*)(lds + (bufoff) + ldsw + _i * 8192), 16, 0, 0); } while (0)
; #define PG8_LDA(dst, b, h) do { _Pragma("unroll") for (int m = 0; m < 4; ++m) _Pragma("unroll") for (int k = 0; k < 2; ++k) dst[m][k] = *(const LAS bf16x8*)(lds + PG8_SA(b, h) + aoff + m * 2048 + k * 1024); } while (0)
; #define PG8_LDB(dst, b, h) do { _Pragma("unroll") for (int n = 0; n < 2; ++n) _Pragma("unroll") for (int k = 0; k < 2; ++k) dst[n][k] = *(const LAS bf16x8*)(lds + PG8_SB(b, h) + boff + n * 2048 + k * 1024); } while (0)
; #define PG8_MMA(ai, bj, At, Bt) do { __builtin_amdgcn_s_setprio(1); _Pragma("unroll") for (int m = 0; m < 4; ++m) _Pragma("unroll") for (int n = 0; n < 2; ++n) _Pragma("unroll") for (int k = 0; k < 2; ++k) \
;         acc[ai][bj][m][n] = __builtin_amdgcn_mfma_f32_16x16x32_bf16(Bt[n][k], At[m][k], acc[ai][bj][m][n], 0, 0, 0); __builtin_amdgcn_s_setprio(0); } while (0)
; #define PG8_WAIT_V(n) asm volatile("s_waitcnt vmcnt(" #n ")" ::: "memory")
; #define PG8_WAIT_L(n) asm volatile("s_waitcnt lgkmcnt(" #n ")" ::: "memory")
; #define PG8_BAR __builtin_amdgcn_s_barrier()
; #define PG8_SCHED __builtin_amdgcn_sched_barrier(0)
; template <class Epi>
; __device__ __forceinline__ void gemm_phase(LAS unsigned char* lds, const Gemm g, const Epi& E) {
;     ...
;             PG8_LDA(At, 0, 1); PG8_STAGE(PG8_SA(0, 0), a2, voffA);
;             PG8_BAR; PG8_WAIT_L(0); PG8_MMA(1, 0, At, B0); PG8_BAR; PG8_SCHED;
;             PG8_STAGE(PG8_SB(0, 1), b2 + hstepB, voffB);
;             PG8_WAIT_V(6); PG8_BAR; PG8_MMA(1, 1, At, B1); PG8_BAR;
;             PG8_LDB(B0, 1, 0); PG8_SCHED; PG8_LDA(At, 1, 0); PG8_STAGE(PG8_SA(0, 1), a2 + hstepA, voffA);
;             PG8_WAIT_L(8); PG8_BAR; PG8_WAIT_L(0); PG8_MMA(0, 0, At, B0); PG8_BAR; PG8_SCHED;
;             PG8_LDB(B1, 1, 1); PG8_STAGE(PG8_SB(1, 0), b3, voffB);
	ds_read_b128 v[160:163], v158 offset:16384
	ds_read_b128 v[164:167], v158 offset:17408
	ds_read_b128 v[168:171], v158 offset:18432
	ds_read_b128 v[172:175], v158 offset:19456
	ds_read_b128 v[180:183], v158 offset:20480
	ds_read_b128 v[184:187], v158 offset:21504
	ds_read_b128 v[188:191], v158 offset:22528
	ds_read_b128 v[192:195], v158 offset:23552
	global_load_lds_dwordx4 v[208:209], off
	v_lshl_add_u64 v[230:231], s[14:15], 0, v[146:147]
	s_mov_b32 m0, s30
	s_nop 0
	global_load_lds_dwordx4 v[230:231], off
	s_barrier
	s_waitcnt lgkmcnt(0)
	v_mfma_f32_16x16x32_bf16 v[62:65], v[130:133], v[160:163], v[62:65]
	v_mfma_f32_16x16x32_bf16 v[58:61], v[138:141], v[160:163], v[58:61]
	v_mfma_f32_16x16x32_bf16 v[54:57], v[130:133], v[168:171], v[54:57]
	v_mfma_f32_16x16x32_bf16 v[46:49], v[138:141], v[168:171], v[46:49]
	v_mfma_f32_16x16x32_bf16 v[38:41], v[130:133], v[180:183], v[38:41]
	v_mfma_f32_16x16x32_bf16 v[30:33], v[138:141], v[180:183], v[30:33]
	v_mfma_f32_16x16x32_bf16 v[22:25], v[130:133], v[188:191], v[22:25]
	v_mfma_f32_16x16x32_bf16 v[14:17], v[138:141], v[188:191], v[14:17]
	v_mfma_f32_16x16x32_bf16 v[62:65], v[134:137], v[164:167], v[62:65]
	v_mfma_f32_16x16x32_bf16 v[58:61], v[142:145], v[164:167], v[58:61]
	v_mfma_f32_16x16x32_bf16 v[54:57], v[134:137], v[172:175], v[54:57]
	v_mfma_f32_16x16x32_bf16 v[46:49], v[142:145], v[172:175], v[46:49]
	v_mfma_f32_16x16x32_bf16 v[38:41], v[134:137], v[184:187], v[38:41]
	v_mfma_f32_16x16x32_bf16 v[30:33], v[142:145], v[184:187], v[30:33]
	v_mfma_f32_16x16x32_bf16 v[22:25], v[134:137], v[192:195], v[22:25]
	v_mfma_f32_16x16x32_bf16 v[14:17], v[142:145], v[192:195], v[14:17]
	s_barrier
	s_add_u32 s8, s12, 0xb0000
	s_addc_u32 s9, s13, 0
	s_add_i32 s26, s27, s18
	v_lshl_add_u64 v[130:131], s[8:9], 0, v[148:149]
	s_mov_b32 m0, s26
	s_nop 0
	global_load_lds_dwordx4 v[130:131], off
	v_lshl_add_u64 v[130:131], s[8:9], 0, v[146:147]
	s_add_i32 m0, s26, 0x2000
	s_nop 0
	global_load_lds_dwordx4 v[130:131], off
	s_add_i32 s26, 0, 0x18000
	v_add_u32_e32 v142, s26, v157
	s_waitcnt vmcnt(6)
	s_barrier
	v_mfma_f32_16x16x32_bf16 v[50:53], v[196:199], v[160:163], v[50:53]
	v_mfma_f32_16x16x32_bf16 v[42:45], v[204:207], v[160:163], v[42:45]
	v_mfma_f32_16x16x32_bf16 v[34:37], v[196:199], v[168:171], v[34:37]
	v_mfma_f32_16x16x32_bf16 v[26:29], v[204:207], v[168:171], v[26:29]
	v_mfma_f32_16x16x32_bf16 v[18:21], v[196:199], v[180:183], v[18:21]
	v_mfma_f32_16x16x32_bf16 v[10:13], v[204:207], v[180:183], v[10:13]
	v_mfma_f32_16x16x32_bf16 v[6:9], v[196:199], v[188:191], v[6:9]
	v_mfma_f32_16x16x32_bf16 v[2:5], v[204:207], v[188:191], v[2:5]
	v_mfma_f32_16x16x32_bf16 v[50:53], v[200:203], v[164:167], v[50:53]
	v_mfma_f32_16x16x32_bf16 v[42:45], v[226:229], v[164:167], v[42:45]
	v_mfma_f32_16x16x32_bf16 v[34:37], v[200:203], v[172:175], v[34:37]
	v_mfma_f32_16x16x32_bf16 v[26:29], v[226:229], v[172:175], v[26:29]
	v_mfma_f32_16x16x32_bf16 v[18:21], v[200:203], v[184:187], v[18:21]
	v_mfma_f32_16x16x32_bf16 v[10:13], v[226:229], v[184:187], v[10:13]
	v_mfma_f32_16x16x32_bf16 v[6:9], v[200:203], v[192:195], v[6:9]
	v_mfma_f32_16x16x32_bf16 v[2:5], v[226:229], v[192:195], v[2:5]
	s_barrier
	ds_read_b128 v[130:133], v142
	ds_read_b128 v[134:137], v142 offset:1024
	ds_read_b128 v[138:141], v142 offset:2048
	ds_read_b128 v[142:145], v142 offset:3072
	s_add_u32 s8, s14, 0xb0000
	s_addc_u32 s9, s15, 0
	s_mov_b32 m0, s31
	v_lshl_add_u64 v[196:197], s[8:9], 0, v[148:149]
	ds_read_b128 v[160:163], v158 offset:32768
	ds_read_b128 v[164:167], v158 offset:33792
	ds_read_b128 v[168:171], v158 offset:34816
	ds_read_b128 v[172:175], v158 offset:35840
	ds_read_b128 v[180:183], v158 offset:36864
	ds_read_b128 v[184:187], v158 offset:37888
	ds_read_b128 v[188:191], v158 offset:38912
	ds_read_b128 v[192:195], v158 offset:39936
	global_load_lds_dwordx4 v[196:197], off
	v_lshl_add_u64 v[196:197], s[8:9], 0, v[146:147]
	s_mov_b32 m0, s36
	s_nop 0
	global_load_lds_dwordx4 v[196:197], off
	s_waitcnt lgkmcnt(8)
	s_barrier
	s_waitcnt lgkmcnt(0)
	v_mfma_f32_16x16x32_bf16 v[126:129], v[130:133], v[160:163], v[126:129]
	v_mfma_f32_16x16x32_bf16 v[122:125], v[138:141], v[160:163], v[122:125]
	v_mfma_f32_16x16x32_bf16 v[118:121], v[130:133], v[168:171], v[118:121]
	v_mfma_f32_16x16x32_bf16 v[110:113], v[138:141], v[168:171], v[110:113]
	v_mfma_f32_16x16x32_bf16 v[102:105], v[130:133], v[180:183], v[102:105]
	v_mfma_f32_16x16x32_bf16 v[94:97], v[138:141], v[180:183], v[94:97]
	v_mfma_f32_16x16x32_bf16 v[86:89], v[130:133], v[188:191], v[86:89]
	v_mfma_f32_16x16x32_bf16 v[78:81], v[138:141], v[188:191], v[78:81]
	v_mfma_f32_16x16x32_bf16 v[126:129], v[134:137], v[164:167], v[126:129]
	v_mfma_f32_16x16x32_bf16 v[122:125], v[142:145], v[164:167], v[122:125]
	v_mfma_f32_16x16x32_bf16 v[118:121], v[134:137], v[172:175], v[118:121]
	v_mfma_f32_16x16x32_bf16 v[110:113], v[142:145], v[172:175], v[110:113]
	v_mfma_f32_16x16x32_bf16 v[102:105], v[134:137], v[184:187], v[102:105]
	v_mfma_f32_16x16x32_bf16 v[94:97], v[142:145], v[184:187], v[94:97]
	v_mfma_f32_16x16x32_bf16 v[86:89], v[134:137], v[192:195], v[86:89]
	v_mfma_f32_16x16x32_bf16 v[78:81], v[142:145], v[192:195], v[78:81]
	s_barrier
	s_add_i32 s14, 0, 0x1c000
	s_add_i32 s8, s26, s18
	v_add_u32_e32 v159, s14, v157
	v_lshl_add_u64 v[154:155], v[154:155], 0, s[86:87]
	s_mov_b32 m0, s8
	ds_read_b128 v[196:199], v159
	ds_read_b128 v[200:203], v159 offset:1024
	ds_read_b128 v[204:207], v159 offset:2048
	ds_read_b128 v[226:229], v159 offset:3072
	global_load_lds_dwordx4 v[154:155], off
	v_lshl_add_u64 v[154:155], v[176:177], 0, s[86:87]
	s_add_i32 m0, s8, 0x2000
	s_nop 0
	global_load_lds_dwordx4 v[154:155], off
	s_nop 1
	s_mov_b32 m0, s52
	v_lshl_add_u64 v[154:155], v[208:209], 0, s[86:87]
	s_barrier
; #define PG8_STAGE(bufoff, gbase, voff) do { _Pragma("unroll") for (int _i = 0; _i < 2; ++_i) \
;         __builtin_amdgcn_global_load_lds((const unsigned*)((const char*)(gbase) + (voff)[_i]), (LAS unsigned*)(lds + (bufoff) + ldsw + _i * 8192), 16, 0, 0); } while (0)
; #define PG8_LDA(dst, b, h) do { _Pragma("unroll") for (int m = 0; m < 4; ++m) _Pragma("unroll") for (int k = 0; k < 2; ++k) dst[m][k] = *(const LAS bf16x8*)(lds + PG8_SA(b, h) + aoff + m * 2048 + k * 1024); } while (0)
; #define PG8_MMA(ai, bj, At, Bt) do { __builtin_amdgcn_s_setprio(1); _Pragma("unroll") for (int m = 0; m < 4; ++m) _Pragma("unroll") for (int n = 0; n < 2; ++n) _Pragma("unroll") for (int k = 0; k < 2; ++k) \
;         acc[ai][bj][m][n] = __builtin_amdgcn_mfma_f32_16x16x32_bf16(Bt[n][k], At[m][k], acc[ai][bj][m][n], 0, 0, 0); __builtin_amdgcn_s_setprio(0); } while (0)
; #define PG8_WAIT_V(n) asm volatile("s_waitcnt vmcnt(" #n ")" ::: "memory")
; #define PG8_WAIT_L(n) asm volatile("s_waitcnt lgkmcnt(" #n ")" ::: "memory")
; #define PG8_BAR __builtin_amdgcn_s_barrier()
; #define PG8_SCHED __builtin_amdgcn_sched_barrier(0)
; template <class Epi>
; __device__ __forceinline__ void gemm_phase(LAS unsigned char* lds, const Gemm g, const Epi& E) {
;     ...
;             PG8_BAR; PG8_WAIT_L(0); PG8_MMA(0, 1, At, B1); PG8_BAR;
;             PG8_LDA(At, 1, 1); PG8_STAGE(PG8_SA(1, 0), a3, voffA);
;             PG8_BAR; PG8_WAIT_L(0); PG8_MMA(1, 0, At, B0); PG8_BAR; PG8_SCHED;
;             PG8_STAGE(PG8_SB(1, 1), b3 + hstepB, voffB);
;             PG8_WAIT_V(6); PG8_BAR; PG8_MMA(1, 1, At, B1); PG8_BAR;
	s_waitcnt lgkmcnt(0)
	v_mfma_f32_16x16x32_bf16 v[114:117], v[196:199], v[160:163], v[114:117]
	v_mfma_f32_16x16x32_bf16 v[106:109], v[204:207], v[160:163], v[106:109]
	v_mfma_f32_16x16x32_bf16 v[98:101], v[196:199], v[168:171], v[98:101]
	v_mfma_f32_16x16x32_bf16 v[90:93], v[204:207], v[168:171], v[90:93]
	v_mfma_f32_16x16x32_bf16 v[82:85], v[196:199], v[180:183], v[82:85]
	v_mfma_f32_16x16x32_bf16 v[74:77], v[204:207], v[180:183], v[74:77]
	v_mfma_f32_16x16x32_bf16 v[70:73], v[196:199], v[188:191], v[70:73]
	v_mfma_f32_16x16x32_bf16 v[66:69], v[204:207], v[188:191], v[66:69]
	v_mfma_f32_16x16x32_bf16 v[114:117], v[200:203], v[164:167], v[114:117]
	v_mfma_f32_16x16x32_bf16 v[106:109], v[226:229], v[164:167], v[106:109]
	v_mfma_f32_16x16x32_bf16 v[98:101], v[200:203], v[172:175], v[98:101]
	v_mfma_f32_16x16x32_bf16 v[90:93], v[226:229], v[172:175], v[90:93]
	v_mfma_f32_16x16x32_bf16 v[82:85], v[200:203], v[184:187], v[82:85]
	v_mfma_f32_16x16x32_bf16 v[74:77], v[226:229], v[184:187], v[74:77]
	v_mfma_f32_16x16x32_bf16 v[70:73], v[200:203], v[192:195], v[70:73]
	v_mfma_f32_16x16x32_bf16 v[66:69], v[226:229], v[192:195], v[66:69]
	s_barrier
	ds_read_b128 v[160:163], v158 offset:49152
	ds_read_b128 v[164:167], v158 offset:50176
	ds_read_b128 v[168:171], v158 offset:51200
	ds_read_b128 v[172:175], v158 offset:52224
	ds_read_b128 v[180:183], v158 offset:53248
	ds_read_b128 v[184:187], v158 offset:54272
	ds_read_b128 v[188:191], v158 offset:55296
	ds_read_b128 v[192:195], v158 offset:56320
	global_load_lds_dwordx4 v[154:155], off
	v_lshl_add_u64 v[154:155], v[230:231], 0, s[86:87]
	s_mov_b32 m0, s53
	s_nop 0
	global_load_lds_dwordx4 v[154:155], off
	s_barrier
	s_waitcnt lgkmcnt(0)
	v_mfma_f32_16x16x32_bf16 v[62:65], v[130:133], v[160:163], v[62:65]
	v_mfma_f32_16x16x32_bf16 v[58:61], v[138:141], v[160:163], v[58:61]
	v_mfma_f32_16x16x32_bf16 v[54:57], v[130:133], v[168:171], v[54:57]
	v_mfma_f32_16x16x32_bf16 v[46:49], v[138:141], v[168:171], v[46:49]
	v_mfma_f32_16x16x32_bf16 v[38:41], v[130:133], v[180:183], v[38:41]
	v_mfma_f32_16x16x32_bf16 v[30:33], v[138:141], v[180:183], v[30:33]
	v_mfma_f32_16x16x32_bf16 v[22:25], v[130:133], v[188:191], v[22:25]
	v_mfma_f32_16x16x32_bf16 v[14:17], v[138:141], v[188:191], v[14:17]
	v_mfma_f32_16x16x32_bf16 v[62:65], v[134:137], v[164:167], v[62:65]
	v_mfma_f32_16x16x32_bf16 v[58:61], v[142:145], v[164:167], v[58:61]
	v_mfma_f32_16x16x32_bf16 v[54:57], v[134:137], v[172:175], v[54:57]
	v_mfma_f32_16x16x32_bf16 v[46:49], v[142:145], v[172:175], v[46:49]
	v_mfma_f32_16x16x32_bf16 v[38:41], v[134:137], v[184:187], v[38:41]
	v_mfma_f32_16x16x32_bf16 v[30:33], v[142:145], v[184:187], v[30:33]
	v_mfma_f32_16x16x32_bf16 v[22:25], v[134:137], v[192:195], v[22:25]
	v_mfma_f32_16x16x32_bf16 v[14:17], v[142:145], v[192:195], v[14:17]
	s_barrier
	s_add_u32 s8, s12, 0xb0080
	s_addc_u32 s9, s13, 0
	s_add_i32 s12, s14, s18
	v_lshl_add_u64 v[130:131], s[8:9], 0, v[148:149]
	s_mov_b32 m0, s12
	s_nop 0
	global_load_lds_dwordx4 v[130:131], off
	v_lshl_add_u64 v[130:131], s[8:9], 0, v[146:147]
	s_add_i32 m0, s12, 0x2000
	s_nop 0
	global_load_lds_dwordx4 v[130:131], off
	s_add_i32 s67, s67, 2
	s_add_u32 s65, s65, 0x100
	s_addc_u32 s66, s66, 0
	s_add_i32 s26, 0, 0x10000
	v_add_u32_e32 v142, s26, v157
	s_cmp_gt_u32 s67, 41
	s_mov_b64 s[8:9], s[10:11]
	s_waitcnt vmcnt(6)
	s_barrier
	v_mfma_f32_16x16x32_bf16 v[50:53], v[196:199], v[160:163], v[50:53]
	v_mfma_f32_16x16x32_bf16 v[42:45], v[204:207], v[160:163], v[42:45]
	v_mfma_f32_16x16x32_bf16 v[34:37], v[196:199], v[168:171], v[34:37]
	v_mfma_f32_16x16x32_bf16 v[26:29], v[204:207], v[168:171], v[26:29]
	v_mfma_f32_16x16x32_bf16 v[18:21], v[196:199], v[180:183], v[18:21]
	v_mfma_f32_16x16x32_bf16 v[10:13], v[204:207], v[180:183], v[10:13]
	v_mfma_f32_16x16x32_bf16 v[6:9], v[196:199], v[188:191], v[6:9]
	v_mfma_f32_16x16x32_bf16 v[2:5], v[204:207], v[188:191], v[2:5]
	v_mfma_f32_16x16x32_bf16 v[50:53], v[200:203], v[164:167], v[50:53]
	v_mfma_f32_16x16x32_bf16 v[42:45], v[226:229], v[164:167], v[42:45]
	v_mfma_f32_16x16x32_bf16 v[34:37], v[200:203], v[172:175], v[34:37]
	v_mfma_f32_16x16x32_bf16 v[26:29], v[226:229], v[172:175], v[26:29]
	v_mfma_f32_16x16x32_bf16 v[18:21], v[200:203], v[184:187], v[18:21]
	v_mfma_f32_16x16x32_bf16 v[10:13], v[226:229], v[184:187], v[10:13]
	v_mfma_f32_16x16x32_bf16 v[6:9], v[200:203], v[192:195], v[6:9]
	v_mfma_f32_16x16x32_bf16 v[2:5], v[226:229], v[192:195], v[2:5]
	s_barrier
	s_cbranch_scc0 .LBB0_547
;     __device__ __forceinline__ void operator()(const AccT& acc, const Unit& u, int wr, int wc, int fr, int fq) const {
;         asm volatile("" : "+v"(fr), "+v"(fq));
;         const int gpm = mapA.src(u.pm);
;         const int mb = gpm < 32 ? 32 : (gpm - 32) >> 3;
;         const int row0 = gpm * 256 + wr * 64 + fr, col0 = u.pn * 256 + wc * 32 + 4 * fq;
;         const float* gp = modl + ((size_t)mb * 6 + gi) * 1024;
;         f32x4 gv[2][2];
; #pragma unroll
;         for (int bj = 0; bj < 2; ++bj)
; #pragma unroll
;             for (int n = 0; n < 2; ++n) { gv[bj][n] = *(const f32x4*)(gp + col0 + bj * 128 + n * 16); if (scale) gv[bj][n] = gv[bj][n] * *(const f32x4*)(scale + col0 + bj * 128 + n * 16); }
;         const float* sbase = (gpm < 32 ? Xc : Xl) + (size_t)row0 * 1024 + col0;
; #pragma unroll
;         for (int ai = 0; ai < 2; ++ai) {
;             f32x4 xo[4][2][2];
; #pragma unroll
;             for (int m = 0; m < 4; ++m)
; #pragma unroll
;                 for (int bj = 0; bj < 2; ++bj)
; #pragma unroll
;                     for (int n = 0; n < 2; ++n) xo[m][bj][n] = *(const f32x4*)(sbase + (size_t)(ai * 128 + m * 16) * 1024 + bj * 128 + n * 16);
;             __builtin_amdgcn_sched_barrier(0);
; #pragma unroll
;             for (int m = 0; m < 4; ++m) { float* rowp = X + (size_t)(row0 + ai * 128 + m * 16) * 1024 + col0;
; #pragma unroll
;                 for (int bj = 0; bj < 2; ++bj)
; #pragma unroll
;                     for (int n = 0; n < 2; ++n) *(f32x4*)(rowp + bj * 128 + n * 16) = xo[m][bj][n] + gv[bj][n] * acc[ai][bj][m][n]; }
	v_readlane_b32 s8, v255, 27
	s_cmp_ge_i32 s64, s8
	s_cselect_b32 s8, s25, 0
	s_add_i32 s10, s64, s8
	s_sub_i32 s8, s10, 32
	s_lshl_b32 s9, s61, 8
	s_ashr_i32 s8, s8, 3
	s_or_b32 s9, s9, s50
	v_mov_b32_e32 v130, v1
	v_mov_b32_e32 v159, v156
	s_mul_i32 s8, s8, 6
	s_cmp_gt_i32 s10, 31
	s_cselect_b32 s8, s8, 0xc0
	v_lshl_add_u32 v130, v130, 2, s9
	s_ashr_i32 s9, s8, 31
	s_lshl_b64 s[8:9], s[8:9], 12
	v_readlane_b32 s12, v255, 14
	v_readlane_b32 s13, v255, 15
	s_add_u32 s8, s12, s8
	v_ashrrev_i32_e32 v131, 31, v130
	s_addc_u32 s9, s13, s9
	v_lshlrev_b64 v[154:155], 2, v[130:131]
	v_lshl_add_u64 v[130:131], s[8:9], 0, v[154:155]
	s_mov_b64 s[8:9], 0x5000
	v_lshl_add_u64 v[132:133], v[130:131], 0, s[8:9]
	s_movk_i32 s8, 0x5000
	v_add_co_u32_e32 v130, vcc, s8, v130
	s_lshl_b32 s8, s10, 8
	s_add_i32 s8, s8, s44
	v_add_u32_e32 v160, s8, v159
	v_ashrrev_i32_e32 v161, 31, v160
	v_readlane_b32 s8, v254, 0
	v_lshlrev_b64 v[160:161], 12, v[160:161]
	v_readlane_b32 s9, v254, 1
	v_addc_co_u32_e32 v131, vcc, 0, v131, vcc
	s_nop 0
	v_lshl_add_u64 v[160:161], s[8:9], 0, v[160:161]
	v_lshl_add_u64 v[154:155], v[160:161], 0, v[154:155]
	v_add_co_u32_e32 v176, vcc, s45, v154
	global_load_dwordx4 v[138:141], v[132:133], off offset:64
	global_load_dwordx4 v[134:137], v[132:133], off offset:512
	global_load_dwordx4 v[142:145], v[130:131], off
	s_nop 0
	global_load_dwordx4 v[130:133], v[132:133], off offset:576
	v_addc_co_u32_e32 v177, vcc, 0, v155, vcc
	v_add_co_u32_e32 v208, vcc, s19, v154
	global_load_dwordx4 v[160:163], v[154:155], off
	global_load_dwordx4 v[164:167], v[154:155], off offset:64
	global_load_dwordx4 v[168:171], v[154:155], off offset:512
	global_load_dwordx4 v[172:175], v[154:155], off offset:576
	v_addc_co_u32_e32 v209, vcc, 0, v155, vcc
	v_add_co_u32_e32 v246, vcc, s88, v154
	global_load_dwordx4 v[180:183], v[176:177], off
	global_load_dwordx4 v[184:187], v[176:177], off offset:64
	global_load_dwordx4 v[188:191], v[176:177], off offset:512
	global_load_dwordx4 v[192:195], v[176:177], off offset:576
	v_addc_co_u32_e32 v247, vcc, 0, v155, vcc
	global_load_dwordx4 v[196:199], v[208:209], off
	global_load_dwordx4 v[200:203], v[208:209], off offset:64
	global_load_dwordx4 v[204:207], v[208:209], off offset:512
	global_load_dwordx4 v[226:229], v[208:209], off offset:576
	global_load_dwordx4 v[230:233], v[246:247], off
	global_load_dwordx4 v[234:237], v[246:247], off offset:64
	global_load_dwordx4 v[238:241], v[246:247], off offset:512
	global_load_dwordx4 v[242:245], v[246:247], off offset:576
	s_mov_b64 s[8:9], 0x30000
	v_lshl_add_u64 v[248:249], v[154:155], 0, s[84:85]
	v_lshl_add_u64 v[250:251], v[154:155], 0, s[82:83]
	v_lshl_add_u64 v[252:253], v[154:155], 0, s[8:9]
	s_waitcnt vmcnt(0)
	v_pk_fma_f32 v[108:109], v[108:109], v[132:133], v[174:175]
	v_pk_fma_f32 v[106:107], v[106:107], v[130:131], v[172:173]
	v_pk_fma_f32 v[92:93], v[92:93], v[132:133], v[194:195]
	v_pk_fma_f32 v[90:91], v[90:91], v[130:131], v[192:193]
	v_pk_fma_f32 v[76:77], v[76:77], v[132:133], v[228:229]
	v_pk_fma_f32 v[74:75], v[74:75], v[130:131], v[226:227]
	global_store_dwordx4 v[154:155], v[106:109], off offset:576
	global_store_dwordx4 v[248:249], v[90:93], off offset:576
	global_store_dwordx4 v[250:251], v[74:77], off offset:576
	v_pk_fma_f32 v[108:109], v[120:121], v[144:145], v[182:183]
	v_pk_fma_f32 v[106:107], v[118:119], v[142:143], v[180:181]
	v_pk_fma_f32 v[92:93], v[104:105], v[144:145], v[198:199]
	v_pk_fma_f32 v[90:91], v[102:103], v[142:143], v[196:197]
	v_pk_fma_f32 v[76:77], v[88:89], v[144:145], v[232:233]
	v_pk_fma_f32 v[74:75], v[86:87], v[142:143], v[230:231]
	v_pk_fma_f32 v[128:129], v[128:129], v[144:145], v[162:163]
	v_pk_fma_f32 v[126:127], v[126:127], v[142:143], v[160:161]
	v_pk_fma_f32 v[124:125], v[124:125], v[140:141], v[166:167]
	v_pk_fma_f32 v[122:123], v[122:123], v[138:139], v[164:165]
	v_pk_fma_f32 v[116:117], v[116:117], v[136:137], v[170:171]
	v_pk_fma_f32 v[114:115], v[114:115], v[134:135], v[168:169]
	global_store_dwordx4 v[176:177], v[106:109], off
	v_pk_fma_f32 v[100:101], v[100:101], v[136:137], v[190:191]
	v_pk_fma_f32 v[98:99], v[98:99], v[134:135], v[188:189]
	v_pk_fma_f32 v[108:109], v[112:113], v[140:141], v[186:187]
	v_pk_fma_f32 v[106:107], v[110:111], v[138:139], v[184:185]
	global_store_dwordx4 v[208:209], v[90:93], off
	v_pk_fma_f32 v[84:85], v[84:85], v[136:137], v[206:207]
	v_pk_fma_f32 v[82:83], v[82:83], v[134:135], v[204:205]
	v_pk_fma_f32 v[92:93], v[96:97], v[140:141], v[202:203]
	v_pk_fma_f32 v[90:91], v[94:95], v[138:139], v[200:201]
	global_store_dwordx4 v[246:247], v[74:77], off
	v_pk_fma_f32 v[72:73], v[72:73], v[136:137], v[240:241]
	v_pk_fma_f32 v[70:71], v[70:71], v[134:135], v[238:239]
	v_pk_fma_f32 v[76:77], v[80:81], v[140:141], v[236:237]
	v_pk_fma_f32 v[74:75], v[78:79], v[138:139], v[234:235]
	v_pk_fma_f32 v[68:69], v[68:69], v[132:133], v[244:245]
	v_pk_fma_f32 v[66:67], v[66:67], v[130:131], v[242:243]
	global_store_dwordx4 v[154:155], v[126:129], off
	global_store_dwordx4 v[154:155], v[122:125], off offset:64
;     __device__ __forceinline__ void operator()(const AccT& acc, const Unit& u, int wr, int wc, int fr, int fq) const {
;     ...
;         for (int ai = 0; ai < 2; ++ai) {
;             f32x4 xo[4][2][2];
; #pragma unroll
;             for (int m = 0; m < 4; ++m)
; #pragma unroll
;                 for (int bj = 0; bj < 2; ++bj)
; #pragma unroll
;                     for (int n = 0; n < 2; ++n) xo[m][bj][n] = *(const f32x4*)(sbase + (size_t)(ai * 128 + m * 16) * 1024 + bj * 128 + n * 16);
;             __builtin_amdgcn_sched_barrier(0);
; #pragma unroll
;             for (int m = 0; m < 4; ++m) { float* rowp = X + (size_t)(row0 + ai * 128 + m * 16) * 1024 + col0;
; #pragma unroll
;                 for (int bj = 0; bj < 2; ++bj)
; #pragma unroll
;                     for (int n = 0; n < 2; ++n) *(f32x4*)(rowp + bj * 128 + n * 16) = xo[m][bj][n] + gv[bj][n] * acc[ai][bj][m][n]; }
	global_store_dwordx4 v[154:155], v[114:117], off offset:512
	global_store_dwordx4 v[248:249], v[106:109], off offset:64
	global_store_dwordx4 v[248:249], v[98:101], off offset:512
	global_store_dwordx4 v[250:251], v[90:93], off offset:64
	global_store_dwordx4 v[250:251], v[82:85], off offset:512
	global_store_dwordx4 v[252:253], v[74:77], off offset:64
	global_store_dwordx4 v[252:253], v[70:73], off offset:512
	global_store_dwordx4 v[252:253], v[66:69], off offset:576
	s_mov_b64 s[8:9], 0x80000
	v_lshl_add_u64 v[160:161], v[154:155], 0, s[8:9]
	s_mov_b32 s8, 0x80000
	v_add_co_u32_e32 v162, vcc, s8, v154
	s_mov_b64 s[8:9], 0x90000
	s_nop 0
	v_addc_co_u32_e32 v163, vcc, 0, v155, vcc
	v_lshl_add_u64 v[164:165], v[154:155], 0, s[8:9]
	s_mov_b32 s8, 0x90000
	v_add_co_u32_e32 v166, vcc, s8, v154
	s_mov_b64 s[8:9], 0xa0000
	s_nop 0
	v_addc_co_u32_e32 v167, vcc, 0, v155, vcc
	v_lshl_add_u64 v[168:169], v[154:155], 0, s[8:9]
	s_mov_b32 s8, 0xa0000
	v_add_co_u32_e32 v170, vcc, s8, v154
	s_mov_b64 s[8:9], 0xb0000
	s_nop 0
	v_addc_co_u32_e32 v171, vcc, 0, v155, vcc
	v_lshl_add_u64 v[172:173], v[154:155], 0, s[8:9]
	s_mov_b32 s8, 0xb0000
	v_add_co_u32_e32 v154, vcc, s8, v154
	global_load_dwordx4 v[66:69], v[162:163], off
	global_load_dwordx4 v[70:73], v[162:163], off offset:64
	global_load_dwordx4 v[74:77], v[162:163], off offset:512
	global_load_dwordx4 v[78:81], v[162:163], off offset:576
	v_addc_co_u32_e32 v155, vcc, 0, v155, vcc
	global_load_dwordx4 v[82:85], v[166:167], off
	global_load_dwordx4 v[86:89], v[166:167], off offset:64
	global_load_dwordx4 v[90:93], v[166:167], off offset:512
	global_load_dwordx4 v[94:97], v[166:167], off offset:576
	global_load_dwordx4 v[98:101], v[170:171], off
	global_load_dwordx4 v[102:105], v[170:171], off offset:64
	global_load_dwordx4 v[106:109], v[170:171], off offset:512
	global_load_dwordx4 v[110:113], v[170:171], off offset:576
	global_load_dwordx4 v[114:117], v[154:155], off
	global_load_dwordx4 v[118:121], v[154:155], off offset:64
	global_load_dwordx4 v[122:125], v[154:155], off offset:512
	global_load_dwordx4 v[126:129], v[154:155], off offset:576
	s_waitcnt vmcnt(0)
	v_pk_fma_f32 v[44:45], v[44:45], v[132:133], v[80:81]
	v_pk_fma_f32 v[42:43], v[42:43], v[130:131], v[78:79]
	v_pk_fma_f32 v[28:29], v[28:29], v[132:133], v[96:97]
	v_pk_fma_f32 v[26:27], v[26:27], v[130:131], v[94:95]
	v_pk_fma_f32 v[12:13], v[12:13], v[132:133], v[112:113]
	v_pk_fma_f32 v[10:11], v[10:11], v[130:131], v[110:111]
	global_store_dwordx4 v[160:161], v[42:45], off offset:576
	global_store_dwordx4 v[164:165], v[26:29], off offset:576
	global_store_dwordx4 v[168:169], v[10:13], off offset:576
	v_pk_fma_f32 v[44:45], v[56:57], v[144:145], v[84:85]
	v_pk_fma_f32 v[42:43], v[54:55], v[142:143], v[82:83]
	v_pk_fma_f32 v[28:29], v[40:41], v[144:145], v[100:101]
	v_pk_fma_f32 v[26:27], v[38:39], v[142:143], v[98:99]
	v_pk_fma_f32 v[12:13], v[24:25], v[144:145], v[116:117]
	v_pk_fma_f32 v[10:11], v[22:23], v[142:143], v[114:115]
	v_pk_fma_f32 v[64:65], v[64:65], v[144:145], v[68:69]
	v_pk_fma_f32 v[62:63], v[62:63], v[142:143], v[66:67]
	v_pk_fma_f32 v[60:61], v[60:61], v[140:141], v[72:73]
	v_pk_fma_f32 v[58:59], v[58:59], v[138:139], v[70:71]
	v_pk_fma_f32 v[52:53], v[52:53], v[136:137], v[76:77]
	v_pk_fma_f32 v[50:51], v[50:51], v[134:135], v[74:75]
	global_store_dwordx4 v[166:167], v[42:45], off
	v_pk_fma_f32 v[36:37], v[36:37], v[136:137], v[92:93]
	v_pk_fma_f32 v[34:35], v[34:35], v[134:135], v[90:91]
	v_pk_fma_f32 v[44:45], v[48:49], v[140:141], v[88:89]
	v_pk_fma_f32 v[42:43], v[46:47], v[138:139], v[86:87]
	global_store_dwordx4 v[170:171], v[26:29], off
	v_pk_fma_f32 v[20:21], v[20:21], v[136:137], v[108:109]
	v_pk_fma_f32 v[18:19], v[18:19], v[134:135], v[106:107]
	v_pk_fma_f32 v[28:29], v[32:33], v[140:141], v[104:105]
	v_pk_fma_f32 v[26:27], v[30:31], v[138:139], v[102:103]
	global_store_dwordx4 v[154:155], v[10:13], off
	v_pk_fma_f32 v[8:9], v[8:9], v[136:137], v[124:125]
	v_pk_fma_f32 v[6:7], v[6:7], v[134:135], v[122:123]
	v_pk_fma_f32 v[12:13], v[16:17], v[140:141], v[120:121]
	v_pk_fma_f32 v[10:11], v[14:15], v[138:139], v[118:119]
	v_pk_fma_f32 v[4:5], v[4:5], v[132:133], v[128:129]
	v_pk_fma_f32 v[2:3], v[2:3], v[130:131], v[126:127]
	global_store_dwordx4 v[162:163], v[62:65], off
	global_store_dwordx4 v[160:161], v[58:61], off offset:64
	global_store_dwordx4 v[160:161], v[50:53], off offset:512
	global_store_dwordx4 v[164:165], v[42:45], off offset:64
	global_store_dwordx4 v[164:165], v[34:37], off offset:512
	global_store_dwordx4 v[168:169], v[26:29], off offset:64
	global_store_dwordx4 v[168:169], v[18:21], off offset:512
	global_store_dwordx4 v[172:173], v[10:13], off offset:64
	global_store_dwordx4 v[172:173], v[6:9], off offset:512
	global_store_dwordx4 v[172:173], v[2:5], off offset:576
	s_and_b64 vcc, exec, s[2:3]
	s_mov_b32 s61, s59
	s_mov_b32 s64, s60
	s_mov_b64 s[10:11], s[6:7]
	s_mov_b64 s[8:9], s[4:5]
	s_cbranch_vccz .LBB0_540
	s_waitcnt vmcnt(0)
	s_cmpk_gt_u32 s1, 0xff
	s_movk_i32 s36, 0xf000
	s_cbranch_scc1 .LBB0_551
	s_barrier
